# v19: v14 + non-temporal (nt) output stores in the row phases (1,7,10,16,19) and the combine phase
# speedup vs baseline: 1.0063x; 1.0063x over previous
.LBB0_126:
	v_pk_mul_f32 v[22:23], v[16:17], v[16:17]
	v_pk_mul_f32 v[24:25], v[14:15], v[14:15]
	s_nop 0
	v_pk_mov_b32 v[30:31], v[24:25], v[22:23] op_sel:[1,0]
	v_mov_b32_e32 v25, v23
	v_pk_add_f32 v[22:23], v[30:31], v[24:25]
	v_pk_mul_f32 v[24:25], v[12:13], v[12:13]
	v_pk_mul_f32 v[30:31], v[10:11], v[10:11]
	v_pk_add_f32 v[22:23], v[22:23], v[22:23] op_sel:[0,1] op_sel_hi:[1,0]
	v_pk_mov_b32 v[32:33], v[30:31], v[24:25] op_sel:[1,0]
	v_mov_b32_e32 v31, v25
	v_pk_add_f32 v[24:25], v[32:33], v[30:31]
	v_mul_f32_e32 v30, v2, v2
	v_mul_f32_e32 v31, v3, v3
	v_pk_add_f32 v[24:25], v[24:25], v[24:25] op_sel:[0,1] op_sel_hi:[1,0]
	v_mov_b32_e32 v23, v30
	v_mov_b32_e32 v25, v31
	v_pk_add_f32 v[22:23], v[22:23], v[24:25]
	v_mul_f32_e32 v24, v7, v7
	v_mul_f32_e32 v30, v9, v9
	v_mul_f32_e32 v32, v4, v4
	v_mul_f32_e32 v33, v5, v5
	v_pk_fma_f32 v[24:25], v[6:7], v[6:7], v[24:25] op_sel_hi:[1,1,0]
	v_pk_fma_f32 v[30:31], v[8:9], v[8:9], v[30:31] op_sel_hi:[1,1,0]
	v_mov_b32_e32 v25, v32
	v_mov_b32_e32 v31, v33
	v_pk_add_f32 v[24:25], v[24:25], v[30:31]
	s_nop 0
	v_pk_add_f32 v[22:23], v[22:23], v[24:25]
	s_nop 0
	v_add_f32_e32 v22, v22, v23
	s_nop 1
	v_add_f32_dpp v22, v22, v22 quad_perm:[1,0,3,2] row_mask:0xf bank_mask:0xf bound_ctrl:1
	s_nop 1
	v_add_f32_dpp v22, v22, v22 quad_perm:[2,3,0,1] row_mask:0xf bank_mask:0xf bound_ctrl:1
	s_nop 1
	v_add_f32_dpp v22, v22, v22 row_half_mirror row_mask:0xf bank_mask:0xf bound_ctrl:1
	s_nop 1
	v_add_f32_dpp v22, v22, v22 row_mirror row_mask:0xf bank_mask:0xf bound_ctrl:1
	s_nop 0
	v_readlane_b32 s19, v22, 16
	v_readlane_b32 s20, v22, 48
	v_readlane_b32 s0, v22, 0
	v_readlane_b32 s1, v22, 32
	v_mov_b32_e32 v22, s19
	v_mov_b32_e32 v23, s20
	v_pk_add_f32 v[22:23], s[0:1], v[22:23]
	s_nop 0
	v_add_f32_e32 v22, v22, v23
	v_fmamk_f32 v22, v22, 0x3a800000, v115
	v_mul_f32_e32 v23, 0x4f800000, v22
	v_cmp_gt_f32_e32 vcc, s26, v22
	s_nop 1
	v_cndmask_b32_e32 v22, v22, v23, vcc
	v_sqrt_f32_e32 v23, v22
	s_nop 0
	v_add_u32_e32 v24, -1, v23
	v_fma_f32 v25, -v24, v23, v22
	v_cmp_ge_f32_e64 s[0:1], 0, v25
	v_add_u32_e32 v25, 1, v23
	s_nop 0
	v_cndmask_b32_e64 v24, v23, v24, s[0:1]
	v_fma_f32 v23, -v25, v23, v22
	v_cmp_lt_f32_e64 s[0:1], 0, v23
	s_nop 1
	v_cndmask_b32_e64 v23, v24, v25, s[0:1]
	v_mul_f32_e32 v24, 0x37800000, v23
	v_cndmask_b32_e32 v23, v23, v24, vcc
	v_cmp_class_f32_e32 vcc, v22, v116
	s_nop 1
	v_cndmask_b32_e32 v22, v23, v22, vcc
	v_div_scale_f32 v23, s[0:1], v22, v22, 1.0
	v_rcp_f32_e32 v24, v23
	s_lshl_b64 s[0:1], s[16:17], 11
	s_add_u32 s4, s4, s6
	s_addc_u32 s5, s5, s7
	v_fma_f32 v25, -v23, v24, 1.0
	v_fmac_f32_e32 v24, v25, v24
	v_div_scale_f32 v25, vcc, 1.0, v22, 1.0
	v_mul_f32_e32 v30, v25, v24
	v_fma_f32 v31, -v23, v30, v25
	v_fmac_f32_e32 v30, v31, v24
	s_add_u32 s8, s8, s10
	v_fma_f32 v23, -v23, v30, v25
	s_addc_u32 s9, s9, s11
	v_div_fmas_f32 v23, v23, v24, v30
	s_add_u32 s12, s12, s10
	v_div_fixup_f32 v22, v23, v22, 1.0
	s_addc_u32 s13, s13, s11
	v_pk_mul_f32 v[14:15], v[14:15], v[22:23] op_sel_hi:[1,0]
	v_pk_mul_f32 v[16:17], v[16:17], v[22:23] op_sel_hi:[1,0]
	v_pk_mul_f32 v[10:11], v[10:11], v[22:23] op_sel_hi:[1,0]
	v_pk_mul_f32 v[12:13], v[12:13], v[22:23] op_sel_hi:[1,0]
	v_pk_mul_f32 v[6:7], v[6:7], v[22:23] op_sel_hi:[1,0]
	v_pk_mul_f32 v[8:9], v[8:9], v[22:23] op_sel_hi:[1,0]
	v_pk_mul_f32 v[2:3], v[2:3], v[22:23] op_sel_hi:[1,0]
	v_pk_mul_f32 v[4:5], v[4:5], v[22:23] op_sel_hi:[1,0]
	s_add_u32 s14, s14, s6
	s_waitcnt vmcnt(3)
	v_pk_fma_f32 v[16:17], v[90:91], v[16:17], v[36:37]
	v_pk_fma_f32 v[14:15], v[92:93], v[14:15], v[34:35]
	s_waitcnt vmcnt(2)
	v_pk_fma_f32 v[12:13], v[94:95], v[12:13], v[28:29]
	v_pk_fma_f32 v[10:11], v[96:97], v[10:11], v[26:27]
	s_waitcnt vmcnt(1)
	v_pk_fma_f32 v[8:9], v[84:85], v[8:9], v[20:21]
	v_pk_fma_f32 v[6:7], v[98:99], v[6:7], v[18:19]
	s_waitcnt vmcnt(0)
	v_pk_fma_f32 v[4:5], v[82:83], v[4:5], v[44:45]
	v_pk_fma_f32 v[2:3], v[86:87], v[2:3], v[42:43]
	s_addc_u32 s15, s15, s7
	s_add_i32 s29, s3, s18
	v_cvt_pk_bf16_f32 v14, v14, v15
	v_cvt_pk_bf16_f32 v15, v16, v17
	v_lshl_add_u64 v[16:17], v[110:111], 0, s[0:1]
	v_cvt_pk_bf16_f32 v10, v10, v11
	v_cvt_pk_bf16_f32 v11, v12, v13
	v_cvt_pk_bf16_f32 v6, v6, v7
	v_cvt_pk_bf16_f32 v7, v8, v9
	v_cvt_pk_bf16_f32 v2, v2, v3
	v_cvt_pk_bf16_f32 v3, v4, v5
	s_cmp_lt_i32 s29, 0x8000
	global_store_dwordx2 v[16:17], v[14:15], off nt
	global_store_dwordx2 v[16:17], v[10:11], off offset:512 nt
	global_store_dwordx2 v[16:17], v[6:7], off offset:1024 nt
	global_store_dwordx2 v[16:17], v[2:3], off offset:1536 nt
	s_cbranch_scc0 .LBB0_133
.LBB0_127:
	v_lshl_add_u64 v[2:3], s[8:9], 0, v[102:103]
	global_load_dwordx4 v[78:81], v[2:3], off
	global_load_dwordx4 v[70:73], v[2:3], off offset:1024
	global_load_dwordx4 v[66:69], v[2:3], off offset:3072
	global_load_dwordx4 v[74:77], v[2:3], off offset:2048
	s_ashr_i32 s0, s29, 31
	s_lshr_b32 s0, s0, 18
	s_add_i32 s0, s29, s0
	s_ashr_i32 s28, s0, 14
	s_add_i32 s18, s24, s29
	s_add_i32 s16, s25, s29
	s_mul_i32 s0, s28, 0xc00
	s_ashr_i32 s19, s18, 31
	s_ashr_i32 s17, s16, 31
	s_ashr_i32 s1, s0, 31
	s_lshl_b64 s[22:23], s[18:19], 12
	s_lshl_b64 s[20:21], s[16:17], 12
	s_lshl_b64 s[0:1], s[0:1], 2
	s_add_u32 s0, s94, s0
	s_addc_u32 s1, s95, s1
	s_add_u32 s30, s0, 0x1000
	s_addc_u32 s31, s1, 0
	global_load_dwordx4 v[90:93], v1, s[30:31]
	global_load_dwordx4 v[94:97], v112, s[30:31]
	global_load_dwordx4 v[118:121], v113, s[30:31]
	global_load_dwordx4 v[122:125], v114, s[30:31]
	global_load_dwordx4 v[126:129], v[104:105], off
	global_load_dwordx4 v[98:101], v[104:105], off offset:1024
	global_load_dwordx4 v[82:85], v[104:105], off offset:2048
	v_lshl_add_u64 v[2:3], s[12:13], 0, v[102:103]
	global_load_dwordx4 v[86:89], v[104:105], off offset:3072
	global_load_dwordx4 v[62:65], v[2:3], off
	global_load_dwordx4 v[58:61], v[2:3], off offset:1024
	global_load_dwordx4 v[54:57], v[2:3], off offset:2048
	global_load_dwordx4 v[50:53], v[2:3], off offset:3072
	v_lshl_add_u64 v[18:19], v[106:107], 0, s[22:23]
	v_lshl_add_u64 v[20:21], v[106:107], 0, s[20:21]
	global_load_dwordx4 v[46:49], v[18:19], off
	global_load_dwordx4 v[38:41], v[18:19], off offset:1024
	global_load_dwordx4 v[30:33], v[18:19], off offset:2048
	global_load_dwordx4 v[22:25], v[18:19], off offset:3072
	global_load_dwordx4 v[14:17], v[20:21], off
	global_load_dwordx4 v[10:13], v[20:21], off offset:1024
	global_load_dwordx4 v[6:9], v[20:21], off offset:2048
	global_load_dwordx4 v[2:5], v[20:21], off offset:3072
	global_load_dwordx4 v[34:37], v1, s[0:1]
	global_load_dwordx4 v[26:29], v1, s[0:1] offset:1024
	s_nop 0
	global_load_dwordx4 v[18:21], v1, s[0:1] offset:2048
	global_load_dwordx4 v[42:45], v1, s[0:1] offset:3072
	s_waitcnt vmcnt(27)
	v_pk_mul_f32 v[130:131], v[80:81], v[80:81]
	v_pk_mul_f32 v[132:133], v[78:79], v[78:79]
	s_waitcnt vmcnt(26)
	v_pk_mul_f32 v[134:135], v[72:73], v[72:73]
	v_pk_mul_f32 v[136:137], v[70:71], v[70:71]
	v_pk_mov_b32 v[142:143], v[132:133], v[130:131] op_sel:[1,0]
	v_mov_b32_e32 v133, v131
	v_pk_mov_b32 v[130:131], v[136:137], v[134:135] op_sel:[1,0]
	v_mov_b32_e32 v137, v135
	s_waitcnt vmcnt(25)
	v_mul_f32_e32 v141, v69, v69
	s_waitcnt vmcnt(24)
	v_mul_f32_e32 v138, v75, v75
	v_mul_f32_e32 v140, v77, v77
	v_pk_add_f32 v[132:133], v[142:143], v[132:133]
	v_pk_add_f32 v[130:131], v[130:131], v[136:137]
	v_mul_f32_e32 v117, v68, v68
	v_mul_f32_e32 v144, v66, v66
	v_mul_f32_e32 v145, v67, v67
	v_pk_fma_f32 v[134:135], v[74:75], v[74:75], v[138:139] op_sel_hi:[1,1,0]
	v_pk_fma_f32 v[138:139], v[76:77], v[76:77], v[140:141] op_sel_hi:[1,1,0]
	v_pk_add_f32 v[132:133], v[132:133], v[132:133] op_sel:[0,1] op_sel_hi:[1,0]
	v_pk_add_f32 v[130:131], v[130:131], v[130:131] op_sel:[0,1] op_sel_hi:[1,0]
	v_mov_b32_e32 v135, v117
	v_mov_b32_e32 v139, v141
	v_mov_b32_e32 v133, v144
	v_mov_b32_e32 v131, v145
	v_pk_add_f32 v[134:135], v[134:135], v[138:139]
	v_pk_add_f32 v[130:131], v[132:133], v[130:131]
	s_waitcnt vmcnt(22)
	v_pk_add_f32 v[132:133], v[94:95], 1.0 op_sel_hi:[1,0]
	v_pk_add_f32 v[130:131], v[130:131], v[134:135]
	v_pk_add_f32 v[92:93], v[92:93], 1.0 op_sel_hi:[1,0]
	v_add_f32_e32 v117, v130, v131
	v_pk_add_f32 v[130:131], v[90:91], 1.0 op_sel_hi:[1,0]
	s_waitcnt vmcnt(19)
	v_pk_mul_f32 v[90:91], v[128:129], v[92:93]
	v_add_f32_dpp v117, v117, v117 quad_perm:[1,0,3,2] row_mask:0xf bank_mask:0xf bound_ctrl:1
	v_pk_mul_f32 v[92:93], v[126:127], v[130:131]
	v_pk_add_f32 v[96:97], v[96:97], 1.0 op_sel_hi:[1,0]
	v_add_f32_dpp v117, v117, v117 quad_perm:[2,3,0,1] row_mask:0xf bank_mask:0xf bound_ctrl:1
	v_pk_add_f32 v[118:119], v[118:119], 1.0 op_sel_hi:[1,0]
	v_pk_add_f32 v[124:125], v[124:125], 1.0 op_sel_hi:[1,0]
	v_add_f32_dpp v94, v117, v117 row_half_mirror row_mask:0xf bank_mask:0xf bound_ctrl:1
	v_pk_add_f32 v[120:121], v[120:121], 1.0 op_sel_hi:[1,0]
	v_pk_add_f32 v[122:123], v[122:123], 1.0 op_sel_hi:[1,0]
	v_add_f32_dpp v94, v94, v94 row_mirror row_mask:0xf bank_mask:0xf bound_ctrl:1
	s_waitcnt vmcnt(17)
	v_pk_mul_f32 v[84:85], v[84:85], v[120:121]
	v_readlane_b32 s20, v94, 16
	v_readlane_b32 s21, v94, 48
	v_readlane_b32 s0, v94, 0
	v_readlane_b32 s1, v94, 32
	v_mov_b32_e32 v94, s20
	v_mov_b32_e32 v95, s21
	v_pk_add_f32 v[94:95], s[0:1], v[94:95]
	s_add_i32 s20, s3, s29
	v_add_f32_e32 v94, v94, v95
	v_fmamk_f32 v94, v94, 0x3a800000, v115
	v_mul_f32_e32 v95, 0x4f800000, v94
	v_cmp_gt_f32_e32 vcc, s26, v94
	s_waitcnt vmcnt(16)
	v_pk_mul_f32 v[86:87], v[86:87], v[122:123]
	v_cndmask_b32_e32 v117, v94, v95, vcc
	v_sqrt_f32_e32 v126, v117
	v_pk_mul_f32 v[94:95], v[100:101], v[96:97]
	v_pk_mul_f32 v[96:97], v[98:99], v[132:133]
	v_add_u32_e32 v98, -1, v126
	v_add_u32_e32 v99, 1, v126
	v_fma_f32 v100, -v98, v126, v117
	v_fma_f32 v101, -v99, v126, v117
	v_cmp_ge_f32_e64 s[0:1], 0, v100
	s_nop 1
	v_cndmask_b32_e64 v98, v126, v98, s[0:1]
	v_cmp_lt_f32_e64 s[0:1], 0, v101
	s_nop 1
	v_cndmask_b32_e64 v98, v98, v99, s[0:1]
	v_mul_f32_e32 v99, 0x37800000, v98
	v_cndmask_b32_e32 v98, v98, v99, vcc
	v_cmp_class_f32_e32 vcc, v117, v116
	s_nop 1
	v_cndmask_b32_e32 v100, v98, v117, vcc
	v_div_scale_f32 v101, s[0:1], v100, v100, 1.0
	v_rcp_f32_e32 v117, v101
	v_pk_mul_f32 v[98:99], v[82:83], v[118:119]
	v_pk_mul_f32 v[82:83], v[88:89], v[124:125]
	s_ashr_i32 s0, s20, 31
	v_fma_f32 v88, -v101, v117, 1.0
	v_fmac_f32_e32 v117, v88, v117
	v_div_scale_f32 v88, vcc, 1.0, v100, 1.0
	v_mul_f32_e32 v89, v88, v117
	v_fma_f32 v118, -v101, v89, v88
	v_fmac_f32_e32 v89, v118, v117
	v_fma_f32 v88, -v101, v89, v88
	v_div_fmas_f32 v88, v88, v117, v89
	v_div_fixup_f32 v88, v88, v100, 1.0
	v_pk_mul_f32 v[78:79], v[78:79], v[88:89] op_sel_hi:[1,0]
	v_pk_mul_f32 v[80:81], v[80:81], v[88:89] op_sel_hi:[1,0]
	v_pk_mul_f32 v[70:71], v[70:71], v[88:89] op_sel_hi:[1,0]
	v_pk_mul_f32 v[72:73], v[72:73], v[88:89] op_sel_hi:[1,0]
	s_waitcnt vmcnt(3)
	v_pk_fma_f32 v[80:81], v[90:91], v[80:81], v[36:37]
	v_pk_fma_f32 v[78:79], v[92:93], v[78:79], v[34:35]
	s_waitcnt vmcnt(2)
	v_pk_fma_f32 v[72:73], v[94:95], v[72:73], v[28:29]
	v_pk_fma_f32 v[70:71], v[96:97], v[70:71], v[26:27]
	s_lshr_b32 s0, s0, 18
	v_cvt_pk_bf16_f32 v78, v78, v79
	v_cvt_pk_bf16_f32 v79, v80, v81
	v_pk_mul_f32 v[74:75], v[74:75], v[88:89] op_sel_hi:[1,0]
	v_pk_mul_f32 v[76:77], v[76:77], v[88:89] op_sel_hi:[1,0]
	v_pk_mul_f32 v[66:67], v[66:67], v[88:89] op_sel_hi:[1,0]
	v_pk_mul_f32 v[68:69], v[68:69], v[88:89] op_sel_hi:[1,0]
	v_lshl_add_u64 v[80:81], s[14:15], 0, v[108:109]
	v_cvt_pk_bf16_f32 v70, v70, v71
	v_cvt_pk_bf16_f32 v71, v72, v73
	s_add_i32 s0, s20, s0
	global_store_dwordx2 v[80:81], v[70:71], off offset:-512 nt
	s_waitcnt vmcnt(2)
	v_pk_fma_f32 v[70:71], v[84:85], v[76:77], v[20:21]
	v_pk_fma_f32 v[72:73], v[98:99], v[74:75], v[18:19]
	s_waitcnt vmcnt(1)
	v_pk_fma_f32 v[68:69], v[82:83], v[68:69], v[44:45]
	v_pk_fma_f32 v[66:67], v[86:87], v[66:67], v[42:43]
	s_ashr_i32 s0, s0, 14
	v_cvt_pk_bf16_f32 v72, v72, v73
	v_cvt_pk_bf16_f32 v73, v70, v71
	v_cvt_pk_bf16_f32 v66, v66, v67
	v_cvt_pk_bf16_f32 v67, v68, v69
	s_cmp_eq_u32 s0, s28
	global_store_dwordx2 v[80:81], v[78:79], off offset:-1024 nt
	global_store_dwordx2 v[80:81], v[72:73], off nt
	global_store_dwordx2 v[80:81], v[66:67], off offset:512 nt
	s_cbranch_scc1 .LBB0_129
	s_mul_i32 s22, s0, 0xc00
	s_ashr_i32 s23, s22, 31
	s_lshl_b64 s[22:23], s[22:23], 2
	s_add_u32 s22, s94, s22
	s_addc_u32 s23, s95, s23
	s_add_u32 s28, s22, 0x1000
	s_addc_u32 s29, s23, 0
	global_load_dwordx4 v[66:69], v1, s[28:29]
	global_load_dwordx4 v[70:73], v112, s[28:29]
	global_load_dwordx4 v[74:77], v113, s[28:29]
	global_load_dwordx4 v[78:81], v114, s[28:29]
	global_load_dwordx4 v[82:85], v[104:105], off
	global_load_dwordx4 v[86:89], v[104:105], off offset:1024
	global_load_dwordx4 v[98:101], v[104:105], off offset:2048
	global_load_dwordx4 v[118:121], v[104:105], off offset:3072
	global_load_dwordx4 v[34:37], v1, s[22:23]
	global_load_dwordx4 v[26:29], v1, s[22:23] offset:1024
	global_load_dwordx4 v[18:21], v1, s[22:23] offset:2048
	global_load_dwordx4 v[42:45], v1, s[22:23] offset:3072
	s_mov_b32 s28, s0
	s_waitcnt vmcnt(11)
	v_pk_add_f32 v[68:69], v[68:69], 1.0 op_sel_hi:[1,0]
	v_pk_add_f32 v[66:67], v[66:67], 1.0 op_sel_hi:[1,0]
	s_waitcnt vmcnt(10)
	v_pk_add_f32 v[72:73], v[72:73], 1.0 op_sel_hi:[1,0]
	v_pk_add_f32 v[70:71], v[70:71], 1.0 op_sel_hi:[1,0]
	s_waitcnt vmcnt(9)
	v_pk_add_f32 v[76:77], v[76:77], 1.0 op_sel_hi:[1,0]
	v_pk_add_f32 v[74:75], v[74:75], 1.0 op_sel_hi:[1,0]
	s_waitcnt vmcnt(8)
	v_pk_add_f32 v[80:81], v[80:81], 1.0 op_sel_hi:[1,0]
	v_pk_add_f32 v[78:79], v[78:79], 1.0 op_sel_hi:[1,0]
	s_waitcnt vmcnt(7)
	v_pk_mul_f32 v[90:91], v[84:85], v[68:69]
	v_pk_mul_f32 v[92:93], v[82:83], v[66:67]
	s_waitcnt vmcnt(6)
	v_pk_mul_f32 v[94:95], v[88:89], v[72:73]
	v_pk_mul_f32 v[96:97], v[86:87], v[70:71]
	s_waitcnt vmcnt(5)
	v_pk_mul_f32 v[84:85], v[100:101], v[76:77]
	v_pk_mul_f32 v[98:99], v[98:99], v[74:75]
	s_waitcnt vmcnt(4)
	v_pk_mul_f32 v[82:83], v[120:121], v[80:81]
	v_pk_mul_f32 v[86:87], v[118:119], v[78:79]
.LBB0_129:
	v_pk_mul_f32 v[66:67], v[64:65], v[64:65]
	v_pk_mul_f32 v[68:69], v[62:63], v[62:63]
	s_add_i32 s20, s3, s20
	v_pk_mov_b32 v[70:71], v[68:69], v[66:67] op_sel:[1,0]
	v_mov_b32_e32 v69, v67
	v_pk_add_f32 v[66:67], v[70:71], v[68:69]
	v_pk_mul_f32 v[68:69], v[60:61], v[60:61]
	v_pk_mul_f32 v[70:71], v[58:59], v[58:59]
	v_pk_add_f32 v[66:67], v[66:67], v[66:67] op_sel:[0,1] op_sel_hi:[1,0]
	v_pk_mov_b32 v[72:73], v[70:71], v[68:69] op_sel:[1,0]
	v_mov_b32_e32 v71, v69
	v_pk_add_f32 v[68:69], v[72:73], v[70:71]
	v_mul_f32_e32 v70, v50, v50
	v_mul_f32_e32 v71, v51, v51
	v_pk_add_f32 v[68:69], v[68:69], v[68:69] op_sel:[0,1] op_sel_hi:[1,0]
	v_mov_b32_e32 v67, v70
	v_mov_b32_e32 v69, v71
	v_pk_add_f32 v[66:67], v[66:67], v[68:69]
	v_mul_f32_e32 v68, v55, v55
	v_mul_f32_e32 v70, v57, v57
	v_mul_f32_e32 v72, v52, v52
	v_mul_f32_e32 v73, v53, v53
	v_pk_fma_f32 v[68:69], v[54:55], v[54:55], v[68:69] op_sel_hi:[1,1,0]
	v_pk_fma_f32 v[70:71], v[56:57], v[56:57], v[70:71] op_sel_hi:[1,1,0]
	v_mov_b32_e32 v69, v72
	v_mov_b32_e32 v71, v73
	v_pk_add_f32 v[68:69], v[68:69], v[70:71]
	s_nop 0
	v_pk_add_f32 v[66:67], v[66:67], v[68:69]
	s_nop 0
	v_add_f32_e32 v66, v66, v67
	s_nop 1
	v_add_f32_dpp v66, v66, v66 quad_perm:[1,0,3,2] row_mask:0xf bank_mask:0xf bound_ctrl:1
	s_nop 1
	v_add_f32_dpp v66, v66, v66 quad_perm:[2,3,0,1] row_mask:0xf bank_mask:0xf bound_ctrl:1
	s_nop 1
	v_add_f32_dpp v66, v66, v66 row_half_mirror row_mask:0xf bank_mask:0xf bound_ctrl:1
	s_nop 1
	v_add_f32_dpp v66, v66, v66 row_mirror row_mask:0xf bank_mask:0xf bound_ctrl:1
	s_nop 0
	v_readlane_b32 s21, v66, 16
	v_readlane_b32 s22, v66, 48
	v_readlane_b32 s0, v66, 0
	v_readlane_b32 s1, v66, 32
	v_mov_b32_e32 v66, s21
	v_mov_b32_e32 v67, s22
	v_pk_add_f32 v[66:67], s[0:1], v[66:67]
	s_nop 0
	v_add_f32_e32 v66, v66, v67
	v_fmamk_f32 v66, v66, 0x3a800000, v115
	v_mul_f32_e32 v67, 0x4f800000, v66
	v_cmp_gt_f32_e32 vcc, s26, v66
	s_nop 1
	v_cndmask_b32_e32 v66, v66, v67, vcc
	v_sqrt_f32_e32 v67, v66
	s_nop 0
	v_add_u32_e32 v68, -1, v67
	v_fma_f32 v69, -v68, v67, v66
	v_cmp_ge_f32_e64 s[0:1], 0, v69
	v_add_u32_e32 v69, 1, v67
	s_nop 0
	v_cndmask_b32_e64 v68, v67, v68, s[0:1]
	v_fma_f32 v67, -v69, v67, v66
	v_cmp_lt_f32_e64 s[0:1], 0, v67
	s_nop 1
	v_cndmask_b32_e64 v67, v68, v69, s[0:1]
	v_mul_f32_e32 v68, 0x37800000, v67
	v_cndmask_b32_e32 v67, v67, v68, vcc
	v_cmp_class_f32_e32 vcc, v66, v116
	s_nop 1
	v_cndmask_b32_e32 v66, v67, v66, vcc
	v_div_scale_f32 v67, s[0:1], v66, v66, 1.0
	v_rcp_f32_e32 v68, v67
	s_ashr_i32 s0, s20, 31
	s_lshr_b32 s0, s0, 18
	s_add_i32 s0, s20, s0
	v_fma_f32 v69, -v67, v68, 1.0
	v_fmac_f32_e32 v68, v69, v68
	v_div_scale_f32 v69, vcc, 1.0, v66, 1.0
	v_mul_f32_e32 v70, v69, v68
	v_fma_f32 v71, -v67, v70, v69
	v_fmac_f32_e32 v70, v71, v68
	v_fma_f32 v67, -v67, v70, v69
	v_div_fmas_f32 v67, v67, v68, v70
	v_div_fixup_f32 v66, v67, v66, 1.0
	v_pk_mul_f32 v[62:63], v[62:63], v[66:67] op_sel_hi:[1,0]
	v_pk_mul_f32 v[64:65], v[64:65], v[66:67] op_sel_hi:[1,0]
	s_waitcnt vmcnt(3)
	v_pk_fma_f32 v[62:63], v[92:93], v[62:63], v[34:35]
	v_pk_fma_f32 v[64:65], v[90:91], v[64:65], v[36:37]
	v_cvt_pk_bf16_f32 v62, v62, v63
	v_cvt_pk_bf16_f32 v63, v64, v65
	v_lshl_add_u64 v[64:65], s[4:5], 0, v[108:109]
	v_pk_mul_f32 v[58:59], v[58:59], v[66:67] op_sel_hi:[1,0]
	v_pk_mul_f32 v[60:61], v[60:61], v[66:67] op_sel_hi:[1,0]
	v_pk_mul_f32 v[54:55], v[54:55], v[66:67] op_sel_hi:[1,0]
	v_pk_mul_f32 v[56:57], v[56:57], v[66:67] op_sel_hi:[1,0]
	v_pk_mul_f32 v[50:51], v[50:51], v[66:67] op_sel_hi:[1,0]
	v_pk_mul_f32 v[52:53], v[52:53], v[66:67] op_sel_hi:[1,0]
	v_add_co_u32_e32 v64, vcc, s27, v64
	s_waitcnt vmcnt(2)
	v_pk_fma_f32 v[60:61], v[94:95], v[60:61], v[28:29]
	v_pk_fma_f32 v[58:59], v[96:97], v[58:59], v[26:27]
	s_waitcnt vmcnt(1)
	v_pk_fma_f32 v[56:57], v[84:85], v[56:57], v[20:21]
	v_pk_fma_f32 v[54:55], v[98:99], v[54:55], v[18:19]
	s_waitcnt vmcnt(0)
	v_pk_fma_f32 v[52:53], v[82:83], v[52:53], v[44:45]
	v_pk_fma_f32 v[50:51], v[86:87], v[50:51], v[42:43]
	s_ashr_i32 s0, s0, 14
	v_addc_co_u32_e32 v65, vcc, 0, v65, vcc
	v_cvt_pk_bf16_f32 v58, v58, v59
	v_cvt_pk_bf16_f32 v59, v60, v61
	v_cvt_pk_bf16_f32 v54, v54, v55
	v_cvt_pk_bf16_f32 v55, v56, v57
	v_cvt_pk_bf16_f32 v50, v50, v51
	v_cvt_pk_bf16_f32 v51, v52, v53
	s_cmp_eq_u32 s0, s28
	global_store_dwordx2 v[64:65], v[62:63], off nt
	global_store_dwordx2 v[64:65], v[58:59], off offset:512 nt
	global_store_dwordx2 v[64:65], v[54:55], off offset:1024 nt
	global_store_dwordx2 v[64:65], v[50:51], off offset:1536 nt
	s_cbranch_scc1 .LBB0_131
	s_mul_i32 s22, s0, 0xc00
	s_ashr_i32 s23, s22, 31
	s_lshl_b64 s[22:23], s[22:23], 2
	s_add_u32 s22, s94, s22
	s_addc_u32 s23, s95, s23
	s_add_u32 s28, s22, 0x1000
	s_addc_u32 s29, s23, 0
	global_load_dwordx4 v[50:53], v1, s[28:29]
	global_load_dwordx4 v[54:57], v112, s[28:29]
	global_load_dwordx4 v[58:61], v113, s[28:29]
	global_load_dwordx4 v[62:65], v114, s[28:29]
	global_load_dwordx4 v[66:69], v[104:105], off
	global_load_dwordx4 v[70:73], v[104:105], off offset:1024
	global_load_dwordx4 v[74:77], v[104:105], off offset:2048
	global_load_dwordx4 v[78:81], v[104:105], off offset:3072
	global_load_dwordx4 v[34:37], v1, s[22:23]
	global_load_dwordx4 v[26:29], v1, s[22:23] offset:1024
	global_load_dwordx4 v[18:21], v1, s[22:23] offset:2048
	global_load_dwordx4 v[42:45], v1, s[22:23] offset:3072
	s_mov_b32 s28, s0
	s_waitcnt vmcnt(11)
	v_pk_add_f32 v[52:53], v[52:53], 1.0 op_sel_hi:[1,0]
	v_pk_add_f32 v[50:51], v[50:51], 1.0 op_sel_hi:[1,0]
	s_waitcnt vmcnt(10)
	v_pk_add_f32 v[56:57], v[56:57], 1.0 op_sel_hi:[1,0]
	v_pk_add_f32 v[54:55], v[54:55], 1.0 op_sel_hi:[1,0]
	s_waitcnt vmcnt(9)
	v_pk_add_f32 v[60:61], v[60:61], 1.0 op_sel_hi:[1,0]
	v_pk_add_f32 v[58:59], v[58:59], 1.0 op_sel_hi:[1,0]
	s_waitcnt vmcnt(8)
	v_pk_add_f32 v[64:65], v[64:65], 1.0 op_sel_hi:[1,0]
	v_pk_add_f32 v[62:63], v[62:63], 1.0 op_sel_hi:[1,0]
	s_waitcnt vmcnt(7)
	v_pk_mul_f32 v[90:91], v[68:69], v[52:53]
	v_pk_mul_f32 v[92:93], v[66:67], v[50:51]
	s_waitcnt vmcnt(6)
	v_pk_mul_f32 v[94:95], v[72:73], v[56:57]
	v_pk_mul_f32 v[96:97], v[70:71], v[54:55]
	s_waitcnt vmcnt(5)
	v_pk_mul_f32 v[84:85], v[76:77], v[60:61]
	v_pk_mul_f32 v[98:99], v[74:75], v[58:59]
	s_waitcnt vmcnt(4)
	v_pk_mul_f32 v[82:83], v[80:81], v[64:65]
	v_pk_mul_f32 v[86:87], v[78:79], v[62:63]
.LBB0_131:
	v_pk_mul_f32 v[50:51], v[48:49], v[48:49]
	v_pk_mul_f32 v[52:53], v[46:47], v[46:47]
	s_nop 0
	v_pk_mov_b32 v[54:55], v[52:53], v[50:51] op_sel:[1,0]
	v_mov_b32_e32 v53, v51
	v_pk_add_f32 v[50:51], v[54:55], v[52:53]
	v_pk_mul_f32 v[52:53], v[40:41], v[40:41]
	v_pk_mul_f32 v[54:55], v[38:39], v[38:39]
	v_pk_add_f32 v[50:51], v[50:51], v[50:51] op_sel:[0,1] op_sel_hi:[1,0]
	v_pk_mov_b32 v[56:57], v[54:55], v[52:53] op_sel:[1,0]
	v_mov_b32_e32 v55, v53
	v_pk_add_f32 v[52:53], v[56:57], v[54:55]
	v_mul_f32_e32 v54, v22, v22
	v_mul_f32_e32 v55, v23, v23
	v_pk_add_f32 v[52:53], v[52:53], v[52:53] op_sel:[0,1] op_sel_hi:[1,0]
	v_mov_b32_e32 v51, v54
	v_mov_b32_e32 v53, v55
	v_pk_add_f32 v[50:51], v[50:51], v[52:53]
	v_mul_f32_e32 v52, v31, v31
	v_mul_f32_e32 v54, v33, v33
	v_mul_f32_e32 v56, v24, v24
	v_mul_f32_e32 v57, v25, v25
	v_pk_fma_f32 v[52:53], v[30:31], v[30:31], v[52:53] op_sel_hi:[1,1,0]
	v_pk_fma_f32 v[54:55], v[32:33], v[32:33], v[54:55] op_sel_hi:[1,1,0]
	v_mov_b32_e32 v53, v56
	v_mov_b32_e32 v55, v57
	v_pk_add_f32 v[52:53], v[52:53], v[54:55]
	s_nop 0
	v_pk_add_f32 v[50:51], v[50:51], v[52:53]
	s_nop 0
	v_add_f32_e32 v50, v50, v51
	s_nop 1
	v_add_f32_dpp v50, v50, v50 quad_perm:[1,0,3,2] row_mask:0xf bank_mask:0xf bound_ctrl:1
	s_nop 1
	v_add_f32_dpp v50, v50, v50 quad_perm:[2,3,0,1] row_mask:0xf bank_mask:0xf bound_ctrl:1
	s_nop 1
	v_add_f32_dpp v50, v50, v50 row_half_mirror row_mask:0xf bank_mask:0xf bound_ctrl:1
	s_nop 1
	v_add_f32_dpp v50, v50, v50 row_mirror row_mask:0xf bank_mask:0xf bound_ctrl:1
	s_nop 0
	v_readlane_b32 s21, v50, 16
	v_readlane_b32 s22, v50, 48
	v_readlane_b32 s0, v50, 0
	v_readlane_b32 s1, v50, 32
	v_mov_b32_e32 v50, s21
	v_mov_b32_e32 v51, s22
	v_pk_add_f32 v[50:51], s[0:1], v[50:51]
	s_nop 0
	v_add_f32_e32 v50, v50, v51
	v_fmamk_f32 v50, v50, 0x3a800000, v115
	v_mul_f32_e32 v51, 0x4f800000, v50
	v_cmp_gt_f32_e32 vcc, s26, v50
	s_nop 1
	v_cndmask_b32_e32 v50, v50, v51, vcc
	v_sqrt_f32_e32 v51, v50
	s_nop 0
	v_add_u32_e32 v52, -1, v51
	v_fma_f32 v53, -v52, v51, v50
	v_cmp_ge_f32_e64 s[0:1], 0, v53
	v_add_u32_e32 v53, 1, v51
	s_nop 0
	v_cndmask_b32_e64 v52, v51, v52, s[0:1]
	v_fma_f32 v51, -v53, v51, v50
	v_cmp_lt_f32_e64 s[0:1], 0, v51
	s_nop 1
	v_cndmask_b32_e64 v51, v52, v53, s[0:1]
	v_mul_f32_e32 v52, 0x37800000, v51
	v_cndmask_b32_e32 v51, v51, v52, vcc
	v_cmp_class_f32_e32 vcc, v50, v116
	s_nop 1
	v_cndmask_b32_e32 v50, v51, v50, vcc
	v_div_scale_f32 v51, s[0:1], v50, v50, 1.0
	v_rcp_f32_e32 v52, v51
	s_lshl_b64 s[0:1], s[18:19], 11
	s_add_i32 s18, s3, s20
	v_fma_f32 v53, -v51, v52, 1.0
	v_fmac_f32_e32 v52, v53, v52
	v_div_scale_f32 v53, vcc, 1.0, v50, 1.0
	v_mul_f32_e32 v54, v53, v52
	v_fma_f32 v55, -v51, v54, v53
	v_fmac_f32_e32 v54, v55, v52
	v_fma_f32 v51, -v51, v54, v53
	v_div_fmas_f32 v51, v51, v52, v54
	v_div_fixup_f32 v50, v51, v50, 1.0
	v_pk_mul_f32 v[46:47], v[46:47], v[50:51] op_sel_hi:[1,0]
	v_pk_mul_f32 v[48:49], v[48:49], v[50:51] op_sel_hi:[1,0]
	s_waitcnt vmcnt(3)
	v_pk_fma_f32 v[46:47], v[92:93], v[46:47], v[34:35]
	v_pk_fma_f32 v[48:49], v[90:91], v[48:49], v[36:37]
	v_cvt_pk_bf16_f32 v46, v46, v47
	v_cvt_pk_bf16_f32 v47, v48, v49
	v_lshl_add_u64 v[48:49], v[110:111], 0, s[0:1]
	s_ashr_i32 s0, s18, 31
	s_lshr_b32 s0, s0, 18
	v_pk_mul_f32 v[38:39], v[38:39], v[50:51] op_sel_hi:[1,0]
	v_pk_mul_f32 v[40:41], v[40:41], v[50:51] op_sel_hi:[1,0]
	v_pk_mul_f32 v[30:31], v[30:31], v[50:51] op_sel_hi:[1,0]
	v_pk_mul_f32 v[32:33], v[32:33], v[50:51] op_sel_hi:[1,0]
	v_pk_mul_f32 v[22:23], v[22:23], v[50:51] op_sel_hi:[1,0]
	v_pk_mul_f32 v[24:25], v[24:25], v[50:51] op_sel_hi:[1,0]
	s_add_i32 s0, s18, s0
	s_waitcnt vmcnt(2)
	v_pk_fma_f32 v[40:41], v[94:95], v[40:41], v[28:29]
	v_pk_fma_f32 v[38:39], v[96:97], v[38:39], v[26:27]
	s_waitcnt vmcnt(1)
	v_pk_fma_f32 v[32:33], v[84:85], v[32:33], v[20:21]
	v_pk_fma_f32 v[30:31], v[98:99], v[30:31], v[18:19]
	s_waitcnt vmcnt(0)
	v_pk_fma_f32 v[24:25], v[82:83], v[24:25], v[44:45]
	v_pk_fma_f32 v[22:23], v[86:87], v[22:23], v[42:43]
	s_ashr_i32 s0, s0, 14
	v_cvt_pk_bf16_f32 v38, v38, v39
	v_cvt_pk_bf16_f32 v39, v40, v41
	v_cvt_pk_bf16_f32 v30, v30, v31
	v_cvt_pk_bf16_f32 v31, v32, v33
	v_cvt_pk_bf16_f32 v22, v22, v23
	v_cvt_pk_bf16_f32 v23, v24, v25
	s_cmp_eq_u32 s0, s28
	global_store_dwordx2 v[48:49], v[46:47], off nt
	global_store_dwordx2 v[48:49], v[38:39], off offset:512 nt
	global_store_dwordx2 v[48:49], v[30:31], off offset:1024 nt
	global_store_dwordx2 v[48:49], v[22:23], off offset:1536 nt
	s_cbranch_scc1 .LBB0_126
	s_mulk_i32 s0, 0xc00
	s_ashr_i32 s1, s0, 31
	s_lshl_b64 s[0:1], s[0:1], 2
	s_add_u32 s0, s94, s0
	s_addc_u32 s1, s95, s1
	s_add_u32 s20, s0, 0x1000
	s_addc_u32 s21, s1, 0
	global_load_dwordx4 v[22:25], v1, s[20:21]
	global_load_dwordx4 v[30:33], v112, s[20:21]
	global_load_dwordx4 v[38:41], v113, s[20:21]
	global_load_dwordx4 v[46:49], v114, s[20:21]
	global_load_dwordx4 v[50:53], v[104:105], off
	global_load_dwordx4 v[54:57], v[104:105], off offset:1024
	global_load_dwordx4 v[58:61], v[104:105], off offset:2048
	global_load_dwordx4 v[62:65], v[104:105], off offset:3072
	global_load_dwordx4 v[34:37], v1, s[0:1]
	global_load_dwordx4 v[26:29], v1, s[0:1] offset:1024
	global_load_dwordx4 v[18:21], v1, s[0:1] offset:2048
	global_load_dwordx4 v[42:45], v1, s[0:1] offset:3072
	s_waitcnt vmcnt(11)
	v_pk_add_f32 v[24:25], v[24:25], 1.0 op_sel_hi:[1,0]
	v_pk_add_f32 v[22:23], v[22:23], 1.0 op_sel_hi:[1,0]
	s_waitcnt vmcnt(10)
	v_pk_add_f32 v[32:33], v[32:33], 1.0 op_sel_hi:[1,0]
	v_pk_add_f32 v[30:31], v[30:31], 1.0 op_sel_hi:[1,0]
	s_waitcnt vmcnt(9)
	v_pk_add_f32 v[40:41], v[40:41], 1.0 op_sel_hi:[1,0]
	v_pk_add_f32 v[38:39], v[38:39], 1.0 op_sel_hi:[1,0]
	s_waitcnt vmcnt(8)
	v_pk_add_f32 v[48:49], v[48:49], 1.0 op_sel_hi:[1,0]
	v_pk_add_f32 v[46:47], v[46:47], 1.0 op_sel_hi:[1,0]
	s_waitcnt vmcnt(7)
	v_pk_mul_f32 v[90:91], v[52:53], v[24:25]
	v_pk_mul_f32 v[92:93], v[50:51], v[22:23]
	s_waitcnt vmcnt(6)
	v_pk_mul_f32 v[94:95], v[56:57], v[32:33]
	v_pk_mul_f32 v[96:97], v[54:55], v[30:31]
	s_waitcnt vmcnt(5)
	v_pk_mul_f32 v[84:85], v[60:61], v[40:41]
	v_pk_mul_f32 v[98:99], v[58:59], v[38:39]
	s_waitcnt vmcnt(4)
	v_pk_mul_f32 v[82:83], v[64:65], v[48:49]
	v_pk_mul_f32 v[86:87], v[62:63], v[46:47]
	s_branch .LBB0_126

.LBB0_445:
	s_ashr_i32 s9, s8, 31
	v_lshl_add_u64 v[8:9], s[8:9], 4, v[4:5]
	s_lshl_b64 s[0:1], s[8:9], 9
	v_add_co_u32_e32 v12, vcc, 0x80000, v8
	v_lshl_add_u64 v[10:11], v[6:7], 0, s[0:1]
	s_nop 0
	v_addc_co_u32_e32 v13, vcc, 0, v9, vcc
	v_add_co_u32_e32 v14, vcc, 0x1000000, v10
	s_add_i32 s6, s8, s3
	s_nop 0
	v_addc_co_u32_e32 v15, vcc, 0, v11, vcc
	global_load_dword v1, v[8:9], off
	global_load_dwordx2 v[20:21], v[10:11], off
	global_load_dword v40, v[12:13], off
	global_load_dwordx2 v[22:23], v[14:15], off
	v_add_co_u32_e32 v8, vcc, 0x100000, v8
	s_ashr_i32 s7, s6, 31
	s_nop 0
	v_addc_co_u32_e32 v9, vcc, 0, v9, vcc
	global_load_dword v41, v[8:9], off
	v_add_co_u32_e32 v8, vcc, 0x2000000, v10
	s_lshl_b64 s[0:1], s[6:7], 9
	s_nop 0
	v_addc_co_u32_e32 v9, vcc, 0, v11, vcc
	v_lshl_add_u64 v[10:11], s[6:7], 4, v[4:5]
	v_lshl_add_u64 v[12:13], v[6:7], 0, s[0:1]
	global_load_dwordx2 v[24:25], v[8:9], off
	global_load_dword v42, v[10:11], off
	global_load_dwordx2 v[26:27], v[12:13], off
	v_add_co_u32_e32 v8, vcc, s12, v10
	s_add_i32 s4, s10, s8
	s_nop 0
	v_addc_co_u32_e32 v9, vcc, 0, v11, vcc
	v_add_co_u32_e32 v14, vcc, s13, v12
	s_ashr_i32 s5, s4, 31
	s_nop 0
	v_addc_co_u32_e32 v15, vcc, 0, v13, vcc
	v_add_co_u32_e32 v10, vcc, s14, v10
	s_lshl_b64 s[0:1], s[4:5], 9
	s_nop 0
	v_addc_co_u32_e32 v11, vcc, 0, v11, vcc
	v_add_co_u32_e32 v12, vcc, s15, v12
	s_add_i32 s7, s6, s3
	s_nop 0
	v_addc_co_u32_e32 v13, vcc, 0, v13, vcc
	global_load_dword v43, v[8:9], off
	global_load_dwordx2 v[28:29], v[14:15], off
	global_load_dword v44, v[10:11], off
	global_load_dwordx2 v[30:31], v[12:13], off
	v_lshl_add_u64 v[8:9], s[4:5], 4, v[4:5]
	v_add_co_u32_e32 v12, vcc, s12, v8
	v_lshl_add_u64 v[10:11], v[6:7], 0, s[0:1]
	s_nop 0
	v_addc_co_u32_e32 v13, vcc, 0, v9, vcc
	v_add_co_u32_e32 v18, vcc, s13, v10
	s_add_i32 s0, s11, s8
	s_nop 0
	v_addc_co_u32_e32 v19, vcc, 0, v11, vcc
	global_load_dword v45, v[8:9], off
	global_load_dwordx2 v[16:17], v[10:11], off
	global_load_dword v46, v[12:13], off
	global_load_dwordx2 v[14:15], v[18:19], off
	v_add_co_u32_e32 v12, vcc, s14, v8
	s_ashr_i32 s1, s0, 31
	s_nop 0
	v_addc_co_u32_e32 v13, vcc, 0, v9, vcc
	v_add_co_u32_e32 v10, vcc, s15, v10
	s_lshl_b64 s[18:19], s[0:1], 9
	s_nop 0
	v_addc_co_u32_e32 v11, vcc, 0, v11, vcc
	v_lshl_add_u64 v[32:33], s[0:1], 4, v[4:5]
	v_lshl_add_u64 v[34:35], v[6:7], 0, s[18:19]
	global_load_dword v47, v[12:13], off
	global_load_dwordx2 v[18:19], v[10:11], off
	global_load_dword v48, v[32:33], off
	global_load_dwordx2 v[8:9], v[34:35], off
	v_add_co_u32_e32 v36, vcc, s12, v32
	s_add_i32 s5, s7, s3
	s_nop 0
	v_addc_co_u32_e32 v37, vcc, 0, v33, vcc
	v_add_co_u32_e32 v38, vcc, s13, v34
	s_mul_i32 s7, s8, 0x600
	s_nop 0
	v_addc_co_u32_e32 v39, vcc, 0, v35, vcc
	v_add_co_u32_e32 v32, vcc, s14, v32
	s_mul_hi_i32 s1, s8, 0x600
	s_nop 0
	v_addc_co_u32_e32 v33, vcc, 0, v33, vcc
	v_add_co_u32_e32 v34, vcc, s15, v34
	s_add_u32 s8, s94, s7
	s_nop 0
	v_addc_co_u32_e32 v35, vcc, 0, v35, vcc
	s_addc_u32 s9, s95, s1
	s_mul_hi_i32 s1, s6, 0x600
	s_mulk_i32 s6, 0x600
	s_add_u32 s6, s94, s6
	s_addc_u32 s7, s95, s1
	s_waitcnt vmcnt(0)
	v_max3_f32 v10, v1, v40, v41
	v_sub_f32_e32 v1, v1, v10
	v_exp_f32_e32 v1, v1
	v_sub_f32_e32 v11, v40, v10
	v_exp_f32_e32 v40, v11
	v_sub_f32_e32 v10, v41, v10
	v_exp_f32_e32 v41, v10
	v_add_f32_e32 v10, 0, v1
	v_add_f32_e32 v10, v40, v10
	s_mul_hi_i32 s1, s4, 0x600
	v_add_f32_e32 v49, v41, v10
	global_load_dword v52, v[36:37], off
	global_load_dwordx2 v[12:13], v[38:39], off
	global_load_dword v53, v[32:33], off
	global_load_dwordx2 v[10:11], v[34:35], off
	v_div_scale_f32 v50, s[18:19], v49, v49, 1.0
	v_rcp_f32_e32 v51, v50
	v_lshlrev_b32_e32 v38, 16, v20
	v_and_b32_e32 v39, 0xffff0000, v20
	v_lshlrev_b32_e32 v20, 16, v21
	v_fma_f32 v32, -v50, v51, 1.0
	v_fmac_f32_e32 v51, v32, v51
	v_div_scale_f32 v32, vcc, 1.0, v49, 1.0
	v_mul_f32_e32 v33, v32, v51
	v_fma_f32 v34, -v50, v33, v32
	v_fmac_f32_e32 v33, v34, v51
	v_fma_f32 v32, -v50, v33, v32
	v_div_fmas_f32 v32, v32, v51, v33
	v_div_fixup_f32 v33, v32, v49, 1.0
	v_mul_f32_e32 v32, v1, v33
	v_and_b32_e32 v21, 0xffff0000, v21
	v_mul_f32_e32 v34, v40, v33
	v_mul_f32_e32 v36, v41, v33
	v_lshlrev_b32_e32 v40, 16, v22
	v_and_b32_e32 v41, 0xffff0000, v22
	v_pk_fma_f32 v[20:21], v[32:33], v[20:21], 0 op_sel_hi:[0,1,0]
	v_lshlrev_b32_e32 v22, 16, v23
	v_and_b32_e32 v23, 0xffff0000, v23
	v_pk_fma_f32 v[20:21], v[34:35], v[22:23], v[20:21] op_sel_hi:[0,1,1]
	v_lshlrev_b32_e32 v22, 16, v25
	v_and_b32_e32 v23, 0xffff0000, v25
	v_pk_fma_f32 v[20:21], v[36:37], v[22:23], v[20:21] op_sel_hi:[0,1,1]
	v_max3_f32 v1, v42, v43, v44
	v_pk_fma_f32 v[38:39], v[32:33], v[38:39], 0 op_sel_hi:[0,1,0]
	v_cvt_pk_bf16_f32 v23, v20, v21
	v_sub_f32_e32 v20, v42, v1
	v_pk_fma_f32 v[38:39], v[34:35], v[40:41], v[38:39] op_sel_hi:[0,1,1]
	v_lshlrev_b32_e32 v40, 16, v24
	v_and_b32_e32 v41, 0xffff0000, v24
	v_exp_f32_e32 v24, v20
	v_sub_f32_e32 v20, v43, v1
	v_exp_f32_e32 v25, v20
	v_sub_f32_e32 v1, v44, v1
	v_exp_f32_e32 v1, v1
	v_add_f32_e32 v32, 0, v24
	v_add_f32_e32 v32, v25, v32
	v_lshl_add_u64 v[20:21], s[8:9], 0, v[2:3]
	v_add_f32_e32 v32, v1, v32
	v_div_scale_f32 v33, s[8:9], v32, v32, 1.0
	v_rcp_f32_e32 v34, v33
	v_pk_fma_f32 v[38:39], v[36:37], v[40:41], v[38:39] op_sel_hi:[0,1,1]
	v_add_co_u32_e32 v20, vcc, s16, v20
	v_cvt_pk_bf16_f32 v22, v38, v39
	s_nop 0
	v_addc_co_u32_e32 v21, vcc, 0, v21, vcc
	global_store_dwordx2 v[20:21], v[22:23], off offset:1024 nt
	v_fma_f32 v20, -v33, v34, 1.0
	v_fmac_f32_e32 v34, v20, v34
	v_div_scale_f32 v20, vcc, 1.0, v32, 1.0
	v_mul_f32_e32 v21, v20, v34
	v_fma_f32 v22, -v33, v21, v20
	v_fmac_f32_e32 v21, v22, v34
	v_fma_f32 v20, -v33, v21, v20
	v_div_fmas_f32 v20, v20, v34, v21
	v_div_fixup_f32 v21, v20, v32, 1.0
	v_mul_f32_e32 v20, v24, v21
	v_lshlrev_b32_e32 v32, 16, v26
	v_and_b32_e32 v33, 0xffff0000, v26
	v_lshlrev_b32_e32 v26, 16, v27
	v_and_b32_e32 v27, 0xffff0000, v27
	v_mul_f32_e32 v22, v25, v21
	v_mul_f32_e32 v24, v1, v21
	v_pk_fma_f32 v[32:33], v[20:21], v[32:33], 0 op_sel_hi:[0,1,0]
	v_lshlrev_b32_e32 v34, 16, v28
	v_and_b32_e32 v35, 0xffff0000, v28
	v_pk_fma_f32 v[20:21], v[20:21], v[26:27], 0 op_sel_hi:[0,1,0]
	v_lshlrev_b32_e32 v26, 16, v29
	v_and_b32_e32 v27, 0xffff0000, v29
	v_pk_fma_f32 v[32:33], v[22:23], v[34:35], v[32:33] op_sel_hi:[0,1,1]
	v_pk_fma_f32 v[20:21], v[22:23], v[26:27], v[20:21] op_sel_hi:[0,1,1]
	v_lshlrev_b32_e32 v22, 16, v31
	v_and_b32_e32 v23, 0xffff0000, v31
	v_pk_fma_f32 v[20:21], v[24:25], v[22:23], v[20:21] op_sel_hi:[0,1,1]
	v_max3_f32 v1, v45, v46, v47
	v_lshlrev_b32_e32 v34, 16, v30
	v_and_b32_e32 v35, 0xffff0000, v30
	v_cvt_pk_bf16_f32 v23, v20, v21
	v_sub_f32_e32 v20, v45, v1
	v_pk_fma_f32 v[32:33], v[24:25], v[34:35], v[32:33] op_sel_hi:[0,1,1]
	v_exp_f32_e32 v24, v20
	v_sub_f32_e32 v20, v46, v1
	v_exp_f32_e32 v25, v20
	v_sub_f32_e32 v1, v47, v1
	v_exp_f32_e32 v1, v1
	v_add_f32_e32 v26, 0, v24
	v_add_f32_e32 v26, v25, v26
	v_lshl_add_u64 v[20:21], s[6:7], 0, v[2:3]
	v_add_f32_e32 v26, v1, v26
	v_div_scale_f32 v27, s[6:7], v26, v26, 1.0
	v_rcp_f32_e32 v28, v27
	v_add_co_u32_e32 v20, vcc, s16, v20
	v_cvt_pk_bf16_f32 v22, v32, v33
	s_nop 0
	v_addc_co_u32_e32 v21, vcc, 0, v21, vcc
	global_store_dwordx2 v[20:21], v[22:23], off offset:1024 nt
	v_fma_f32 v20, -v27, v28, 1.0
	v_fmac_f32_e32 v28, v20, v28
	v_div_scale_f32 v20, vcc, 1.0, v26, 1.0
	v_mul_f32_e32 v21, v20, v28
	v_fma_f32 v22, -v27, v21, v20
	v_fmac_f32_e32 v21, v22, v28
	v_fma_f32 v20, -v27, v21, v20
	v_div_fmas_f32 v20, v20, v28, v21
	v_div_fixup_f32 v21, v20, v26, 1.0
	v_mul_f32_e32 v20, v24, v21
	v_lshlrev_b32_e32 v26, 16, v16
	v_and_b32_e32 v27, 0xffff0000, v16
	v_lshlrev_b32_e32 v16, 16, v17
	v_and_b32_e32 v17, 0xffff0000, v17
	v_mul_f32_e32 v22, v25, v21
	v_lshlrev_b32_e32 v28, 16, v14
	v_and_b32_e32 v29, 0xffff0000, v14
	v_pk_fma_f32 v[16:17], v[20:21], v[16:17], 0 op_sel_hi:[0,1,0]
	v_lshlrev_b32_e32 v14, 16, v15
	v_and_b32_e32 v15, 0xffff0000, v15
	v_mul_f32_e32 v24, v1, v21
	v_pk_fma_f32 v[14:15], v[22:23], v[14:15], v[16:17] op_sel_hi:[0,1,1]
	v_lshlrev_b32_e32 v16, 16, v19
	v_and_b32_e32 v17, 0xffff0000, v19
	v_pk_fma_f32 v[14:15], v[24:25], v[16:17], v[14:15] op_sel_hi:[0,1,1]
	s_waitcnt vmcnt(3)
	v_max3_f32 v1, v48, v52, v53
	v_pk_fma_f32 v[26:27], v[20:21], v[26:27], 0 op_sel_hi:[0,1,0]
	v_cvt_pk_bf16_f32 v17, v14, v15
	v_sub_f32_e32 v14, v48, v1
	v_pk_fma_f32 v[26:27], v[22:23], v[28:29], v[26:27] op_sel_hi:[0,1,1]
	v_lshlrev_b32_e32 v28, 16, v18
	v_and_b32_e32 v29, 0xffff0000, v18
	v_exp_f32_e32 v18, v14
	v_sub_f32_e32 v14, v52, v1
	v_exp_f32_e32 v19, v14
	v_sub_f32_e32 v1, v53, v1
	v_exp_f32_e32 v1, v1
	s_mulk_i32 s4, 0x600
	v_add_f32_e32 v20, 0, v18
	s_add_u32 s6, s94, s4
	v_add_f32_e32 v20, v19, v20
	s_addc_u32 s7, s95, s1
	v_add_f32_e32 v20, v1, v20
	v_lshl_add_u64 v[14:15], s[6:7], 0, v[2:3]
	v_div_scale_f32 v21, s[6:7], v20, v20, 1.0
	v_rcp_f32_e32 v22, v21
	v_pk_fma_f32 v[26:27], v[24:25], v[28:29], v[26:27] op_sel_hi:[0,1,1]
	v_add_co_u32_e32 v14, vcc, s16, v14
	v_cvt_pk_bf16_f32 v16, v26, v27
	s_nop 0
	v_addc_co_u32_e32 v15, vcc, 0, v15, vcc
	global_store_dwordx2 v[14:15], v[16:17], off offset:1024 nt
	v_fma_f32 v14, -v21, v22, 1.0
	v_fmac_f32_e32 v22, v14, v22
	v_div_scale_f32 v14, vcc, 1.0, v20, 1.0
	v_mul_f32_e32 v15, v14, v22
	v_fma_f32 v16, -v21, v15, v14
	v_fmac_f32_e32 v15, v16, v22
	v_fma_f32 v14, -v21, v15, v14
	v_div_fmas_f32 v14, v14, v22, v15
	v_div_fixup_f32 v15, v14, v20, 1.0
	v_mul_f32_e32 v14, v18, v15
	v_lshlrev_b32_e32 v20, 16, v8
	v_and_b32_e32 v21, 0xffff0000, v8
	v_lshlrev_b32_e32 v8, 16, v9
	v_and_b32_e32 v9, 0xffff0000, v9
	v_mul_f32_e32 v16, v19, v15
	v_pk_fma_f32 v[20:21], v[14:15], v[20:21], 0 op_sel_hi:[0,1,0]
	v_lshlrev_b32_e32 v22, 16, v12
	v_and_b32_e32 v23, 0xffff0000, v12
	v_pk_fma_f32 v[8:9], v[14:15], v[8:9], 0 op_sel_hi:[0,1,0]
	v_lshlrev_b32_e32 v12, 16, v13
	v_and_b32_e32 v13, 0xffff0000, v13
	s_mul_hi_i32 s1, s0, 0x600
	s_mulk_i32 s0, 0x600
	v_mul_f32_e32 v18, v1, v15
	v_pk_fma_f32 v[20:21], v[16:17], v[22:23], v[20:21] op_sel_hi:[0,1,1]
	s_waitcnt vmcnt(3)
	v_lshlrev_b32_e32 v22, 16, v10
	v_and_b32_e32 v23, 0xffff0000, v10
	v_pk_fma_f32 v[8:9], v[16:17], v[12:13], v[8:9] op_sel_hi:[0,1,1]
	v_lshlrev_b32_e32 v10, 16, v11
	v_and_b32_e32 v11, 0xffff0000, v11
	s_add_u32 s0, s94, s0
	v_pk_fma_f32 v[8:9], v[18:19], v[10:11], v[8:9] op_sel_hi:[0,1,1]
	s_addc_u32 s1, s95, s1
	v_cvt_pk_bf16_f32 v11, v8, v9
	v_lshl_add_u64 v[8:9], s[0:1], 0, v[2:3]
	v_pk_fma_f32 v[20:21], v[18:19], v[22:23], v[20:21] op_sel_hi:[0,1,1]
	v_add_co_u32_e32 v8, vcc, 0x17800000, v8
	s_add_i32 s8, s5, s3
	v_cvt_pk_bf16_f32 v10, v20, v21
	v_addc_co_u32_e32 v9, vcc, 0, v9, vcc
	s_cmp_lt_i32 s8, 0x8000
	global_store_dwordx2 v[8:9], v[10:11], off offset:1024 nt
	s_cbranch_scc1 .LBB0_445

.LBB0_578:
	v_and_b32_e32 v35, 0xffff0000, v100
	v_and_b32_e32 v37, 0xffff0000, v101
	v_lshlrev_b32_e32 v34, 16, v100
	v_lshlrev_b32_e32 v36, 16, v101
	v_mul_f32_e32 v38, v37, v37
	v_and_b32_e32 v43, 0xffff0000, v99
	v_and_b32_e32 v42, 0xffff0000, v98
	v_lshlrev_b32_e32 v51, 16, v94
	v_mul_f32_e32 v50, v35, v35
	v_pk_fma_f32 v[38:39], v[36:37], v[36:37], v[38:39] op_sel_hi:[1,1,0]
	v_lshlrev_b32_e32 v41, 16, v99
	v_lshlrev_b32_e32 v40, 16, v98
	v_pk_mul_f32 v[44:45], v[42:43], v[42:43]
	v_pk_fma_f32 v[56:57], v[34:35], v[34:35], v[50:51] op_sel_hi:[1,1,0]
	v_pk_fma_f32 v[44:45], v[40:41], v[40:41], v[44:45]
	v_and_b32_e32 v53, 0xffff0000, v94
	v_mov_b32_e32 v50, v56
	v_mov_b32_e32 v58, v38
	v_mov_b32_e32 v59, v51
	v_mul_f32_e32 v52, v53, v53
	v_pk_add_f32 v[38:39], v[56:57], v[38:39]
	v_pk_mul_f32 v[56:57], v[50:51], v[58:59]
	v_pk_add_f32 v[44:45], v[44:45], v[44:45] op_sel:[0,1] op_sel_hi:[1,0]
	v_and_b32_e32 v47, 0xffff0000, v96
	v_and_b32_e32 v49, 0xffff0000, v97
	v_mov_b32_e32 v39, v57
	v_mov_b32_e32 v45, v52
	v_lshlrev_b32_e32 v46, 16, v96
	v_lshlrev_b32_e32 v48, 16, v97
	v_lshlrev_b32_e32 v54, 16, v95
	v_and_b32_e32 v55, 0xffff0000, v95
	v_pk_add_f32 v[38:39], v[38:39], v[44:45]
	v_mul_f32_e32 v44, v47, v47
	v_mul_f32_e32 v50, v49, v49
	v_mul_f32_e32 v60, v54, v54
	v_mul_f32_e32 v61, v55, v55
	v_pk_fma_f32 v[44:45], v[46:47], v[46:47], v[44:45] op_sel_hi:[1,1,0]
	v_pk_fma_f32 v[56:57], v[48:49], v[48:49], v[50:51] op_sel_hi:[1,1,0]
	v_mov_b32_e32 v45, v60
	v_mov_b32_e32 v57, v61
	v_pk_add_f32 v[44:45], v[44:45], v[56:57]
	s_add_u32 s4, s4, s6
	v_pk_add_f32 v[38:39], v[38:39], v[44:45]
	s_addc_u32 s5, s5, s7
	v_add_f32_e32 v38, v38, v39
	s_add_u32 s8, s8, s10
	s_addc_u32 s9, s9, s11
	v_add_f32_dpp v38, v38, v38 quad_perm:[1,0,3,2] row_mask:0xf bank_mask:0xf bound_ctrl:1
	s_add_u32 s12, s12, s10
	s_addc_u32 s13, s13, s11
	v_add_f32_dpp v38, v38, v38 quad_perm:[2,3,0,1] row_mask:0xf bank_mask:0xf bound_ctrl:1
	s_add_u32 s14, s14, s6
	s_addc_u32 s15, s15, s7
	v_add_f32_dpp v38, v38, v38 row_half_mirror row_mask:0xf bank_mask:0xf bound_ctrl:1
	s_add_i32 s38, s3, s22
	s_cmp_lt_i32 s38, 0x8000
	v_add_f32_dpp v38, v38, v38 row_mirror row_mask:0xf bank_mask:0xf bound_ctrl:1
	s_nop 0
	v_readlane_b32 s18, v38, 16
	v_readlane_b32 s19, v38, 48
	v_readlane_b32 s0, v38, 0
	v_readlane_b32 s1, v38, 32
	v_mov_b32_e32 v38, s18
	v_mov_b32_e32 v39, s19
	v_pk_add_f32 v[38:39], s[0:1], v[38:39]
	s_nop 0
	v_add_f32_e32 v38, v38, v39
	v_fmamk_f32 v38, v38, 0x3a800000, v157
	v_mul_f32_e32 v39, 0x4f800000, v38
	v_cmp_gt_f32_e32 vcc, s34, v38
	s_nop 1
	v_cndmask_b32_e32 v38, v38, v39, vcc
	v_sqrt_f32_e32 v39, v38
	s_nop 0
	v_add_u32_e32 v44, -1, v39
	v_fma_f32 v45, -v44, v39, v38
	v_cmp_ge_f32_e64 s[0:1], 0, v45
	v_add_u32_e32 v45, 1, v39
	s_nop 0
	v_cndmask_b32_e64 v44, v39, v44, s[0:1]
	v_fma_f32 v39, -v45, v39, v38
	v_cmp_lt_f32_e64 s[0:1], 0, v39
	s_nop 1
	v_cndmask_b32_e64 v39, v44, v45, s[0:1]
	v_mul_f32_e32 v44, 0x37800000, v39
	v_cndmask_b32_e32 v39, v39, v44, vcc
	v_cmp_class_f32_e32 vcc, v38, v158
	s_nop 1
	v_cndmask_b32_e32 v38, v39, v38, vcc
	v_div_scale_f32 v39, s[0:1], v38, v38, 1.0
	v_rcp_f32_e32 v44, v39
	s_nop 0
	v_fma_f32 v45, -v39, v44, 1.0
	v_fmac_f32_e32 v44, v45, v44
	v_div_scale_f32 v45, vcc, 1.0, v38, 1.0
	v_mul_f32_e32 v50, v45, v44
	v_fma_f32 v52, -v39, v50, v45
	v_fmac_f32_e32 v50, v52, v44
	v_fma_f32 v39, -v39, v50, v45
	v_div_fmas_f32 v39, v39, v44, v50
	v_div_fixup_f32 v38, v39, v38, 1.0
	v_pk_mul_f32 v[34:35], v[38:39], v[34:35] op_sel_hi:[0,1]
	v_pk_mul_f32 v[36:37], v[38:39], v[36:37] op_sel_hi:[0,1]
	v_pk_fma_f32 v[16:17], v[124:125], v[36:37], v[16:17]
	v_pk_fma_f32 v[14:15], v[128:129], v[34:35], v[14:15]
	v_cvt_pk_bf16_f32 v35, v16, v17
	v_cvt_pk_bf16_f32 v34, v14, v15
	v_lshl_add_u64 v[36:37], v[90:91], 0, s[16:17]
	global_store_dwordx2 v[36:37], v[34:35], off nt
	v_mov_b32_e32 v34, v40
	v_mov_b32_e32 v35, v42
	v_mov_b32_e32 v42, v41
	v_pk_mul_f32 v[34:35], v[38:39], v[34:35] op_sel_hi:[0,1]
	v_pk_mul_f32 v[40:41], v[38:39], v[42:43] op_sel_hi:[0,1]
	v_pk_fma_f32 v[12:13], v[114:115], v[40:41], v[12:13]
	v_pk_fma_f32 v[10:11], v[120:121], v[34:35], v[10:11]
	v_cvt_pk_bf16_f32 v35, v12, v13
	v_cvt_pk_bf16_f32 v34, v10, v11
	global_store_dwordx2 v[36:37], v[34:35], off offset:512 nt
	v_pk_mul_f32 v[34:35], v[38:39], v[46:47] op_sel_hi:[0,1]
	v_mov_b32_e32 v52, v51
	v_pk_mul_f32 v[40:41], v[38:39], v[48:49] op_sel_hi:[0,1]
	v_pk_fma_f32 v[6:7], v[118:119], v[34:35], v[6:7]
	v_pk_mul_f32 v[34:35], v[52:53], v[38:39] op_sel_hi:[1,0]
	v_pk_mul_f32 v[38:39], v[54:55], v[38:39] op_sel_hi:[1,0]
	v_pk_fma_f32 v[2:3], v[132:133], v[34:35], v[2:3]
	v_pk_fma_f32 v[4:5], v[130:131], v[38:39], v[4:5]
	v_pk_mul_f32 v[34:35], v[16:17], v[16:17]
	v_pk_mul_f32 v[38:39], v[14:15], v[14:15]
	v_pk_fma_f32 v[8:9], v[116:117], v[40:41], v[8:9]
	v_pk_mov_b32 v[40:41], v[38:39], v[34:35] op_sel:[1,0]
	v_mov_b32_e32 v39, v35
	v_pk_add_f32 v[34:35], v[40:41], v[38:39]
	v_pk_mul_f32 v[38:39], v[12:13], v[12:13]
	v_pk_add_f32 v[34:35], v[34:35], v[34:35] op_sel_hi:[0,1]
	v_pk_mul_f32 v[40:41], v[10:11], v[10:11]
	v_mul_f32_e32 v34, v6, v6
	v_pk_mov_b32 v[42:43], v[40:41], v[38:39] op_sel:[1,0]
	v_mov_b32_e32 v41, v39
	v_pk_add_f32 v[38:39], v[42:43], v[40:41]
	v_pk_fma_f32 v[40:41], v[6:7], v[6:7], v[34:35] op_sel_hi:[1,1,0]
	v_mul_f32_e32 v34, v8, v8
	v_pk_add_f32 v[38:39], v[38:39], v[38:39] op_sel_hi:[0,1]
	v_pk_fma_f32 v[42:43], v[8:9], v[8:9], v[34:35] op_sel_hi:[1,1,0]
	v_mul_f32_e32 v40, v2, v2
	v_mul_f32_e32 v42, v3, v3
	v_mul_f32_e32 v34, v4, v4
	v_mul_f32_e32 v38, v5, v5
	v_pk_add_f32 v[40:41], v[40:41], v[42:43]
	v_pk_add_f32 v[34:35], v[34:35], v[38:39]
	s_nop 0
	v_pk_add_f32 v[34:35], v[40:41], v[34:35]
	s_nop 0
	v_add_f32_e32 v34, v34, v35
	s_nop 1
	v_add_f32_dpp v34, v34, v34 quad_perm:[1,0,3,2] row_mask:0xf bank_mask:0xf bound_ctrl:1
	s_nop 1
	v_add_f32_dpp v34, v34, v34 quad_perm:[2,3,0,1] row_mask:0xf bank_mask:0xf bound_ctrl:1
	s_nop 1
	v_add_f32_dpp v34, v34, v34 row_half_mirror row_mask:0xf bank_mask:0xf bound_ctrl:1
	s_nop 1
	v_add_f32_dpp v34, v34, v34 row_mirror row_mask:0xf bank_mask:0xf bound_ctrl:1
	s_nop 0
	v_readlane_b32 s18, v34, 16
	v_readlane_b32 s19, v34, 48
	v_readlane_b32 s0, v34, 0
	v_readlane_b32 s1, v34, 32
	v_mov_b32_e32 v34, s18
	v_mov_b32_e32 v35, s19
	v_pk_add_f32 v[34:35], s[0:1], v[34:35]
	s_nop 0
	v_add_f32_e32 v34, v34, v35
	v_fmamk_f32 v34, v34, 0x3a800000, v157
	v_mul_f32_e32 v35, 0x4f800000, v34
	v_cmp_gt_f32_e32 vcc, s34, v34
	s_nop 1
	v_cndmask_b32_e32 v38, v34, v35, vcc
	v_sqrt_f32_e32 v39, v38
	v_cvt_pk_bf16_f32 v34, v6, v7
	v_cvt_pk_bf16_f32 v35, v8, v9
	global_store_dwordx2 v[36:37], v[34:35], off offset:1024 nt
	v_add_u32_e32 v34, -1, v39
	v_fma_f32 v35, -v34, v39, v38
	v_cmp_ge_f32_e64 s[0:1], 0, v35
	v_add_u32_e32 v35, 1, v39
	s_nop 0
	v_cndmask_b32_e64 v34, v39, v34, s[0:1]
	v_fma_f32 v39, -v35, v39, v38
	v_cmp_lt_f32_e64 s[0:1], 0, v39
	s_nop 1
	v_cndmask_b32_e64 v34, v34, v35, s[0:1]
	v_mul_f32_e32 v35, 0x37800000, v34
	v_cndmask_b32_e32 v34, v34, v35, vcc
	v_cmp_class_f32_e32 vcc, v38, v158
	v_cvt_pk_bf16_f32 v35, v4, v5
	s_nop 0
	v_cndmask_b32_e32 v38, v34, v38, vcc
	v_div_scale_f32 v39, s[0:1], v38, v38, 1.0
	v_rcp_f32_e32 v40, v39
	v_cvt_pk_bf16_f32 v34, v2, v3
	global_store_dwordx2 v[36:37], v[34:35], off offset:1536 nt
	v_fma_f32 v34, -v39, v40, 1.0
	v_fmac_f32_e32 v40, v34, v40
	v_div_scale_f32 v34, vcc, 1.0, v38, 1.0
	v_mul_f32_e32 v35, v34, v40
	v_fma_f32 v36, -v39, v35, v34
	v_fmac_f32_e32 v35, v36, v40
	v_fma_f32 v34, -v39, v35, v34
	v_div_fmas_f32 v34, v34, v40, v35
	v_div_fixup_f32 v34, v34, v38, 1.0
	v_pk_mul_f32 v[14:15], v[14:15], v[34:35] op_sel_hi:[1,0]
	v_pk_mul_f32 v[16:17], v[16:17], v[34:35] op_sel_hi:[1,0]
	v_pk_mul_f32 v[10:11], v[10:11], v[34:35] op_sel_hi:[1,0]
	v_pk_mul_f32 v[12:13], v[12:13], v[34:35] op_sel_hi:[1,0]
	v_pk_mul_f32 v[6:7], v[6:7], v[34:35] op_sel_hi:[1,0]
	v_pk_mul_f32 v[8:9], v[8:9], v[34:35] op_sel_hi:[1,0]
	v_pk_mul_f32 v[2:3], v[2:3], v[34:35] op_sel_hi:[1,0]
	v_pk_mul_f32 v[4:5], v[4:5], v[34:35] op_sel_hi:[1,0]
	s_waitcnt vmcnt(7)
	v_pk_fma_f32 v[16:17], v[110:111], v[16:17], v[20:21]
	v_pk_fma_f32 v[14:15], v[112:113], v[14:15], v[18:19]
	s_waitcnt vmcnt(6)
	v_pk_fma_f32 v[12:13], v[104:105], v[12:13], v[32:33]
	v_pk_fma_f32 v[10:11], v[108:109], v[10:11], v[30:31]
	s_waitcnt vmcnt(5)
	v_pk_fma_f32 v[8:9], v[102:103], v[8:9], v[24:25]
	v_pk_fma_f32 v[6:7], v[106:107], v[6:7], v[22:23]
	s_waitcnt vmcnt(4)
	v_pk_fma_f32 v[4:5], v[122:123], v[4:5], v[28:29]
	v_pk_fma_f32 v[2:3], v[126:127], v[2:3], v[26:27]
	v_cvt_pk_bf16_f32 v14, v14, v15
	v_cvt_pk_bf16_f32 v15, v16, v17
	v_lshl_add_u64 v[16:17], v[92:93], 0, s[16:17]
	v_cvt_pk_bf16_f32 v10, v10, v11
	v_cvt_pk_bf16_f32 v11, v12, v13
	v_cvt_pk_bf16_f32 v6, v6, v7
	v_cvt_pk_bf16_f32 v7, v8, v9
	v_cvt_pk_bf16_f32 v2, v2, v3
	v_cvt_pk_bf16_f32 v3, v4, v5
	global_store_dwordx2 v[16:17], v[14:15], off nt
	global_store_dwordx2 v[16:17], v[10:11], off offset:512 nt
	global_store_dwordx2 v[16:17], v[6:7], off offset:1024 nt
	global_store_dwordx2 v[16:17], v[2:3], off offset:1536 nt
	s_cbranch_scc0 .LBB0_585
.LBB0_579:
	s_add_i32 s0, s30, s38
	s_ashr_i32 s1, s0, 31
	s_lshl_b64 s[20:21], s[0:1], 12
	s_lshl_b64 s[18:19], s[0:1], 11
	s_add_i32 s0, s31, s38
	s_ashr_i32 s1, s0, 31
	s_lshl_b64 s[22:23], s[0:1], 12
	s_lshl_b64 s[16:17], s[0:1], 11
	s_ashr_i32 s0, s38, 31
	s_lshr_b32 s0, s0, 18
	s_add_i32 s0, s38, s0
	s_ashr_i32 s37, s0, 14
	s_mul_i32 s0, s37, 0xc00
	s_ashr_i32 s1, s0, 31
	s_lshl_b64 s[0:1], s[0:1], 2
	s_add_u32 s24, s94, s0
	s_addc_u32 s25, s95, s1
	s_add_u32 s24, s24, 0x2000
	s_addc_u32 s25, s25, 0
	s_add_u32 s0, s28, s0
	s_addc_u32 s1, s29, s1
	s_add_u32 s26, s0, 0x1000
	s_addc_u32 s27, s1, 0
	global_load_dwordx4 v[22:25], v1, s[24:25]
	global_load_dwordx4 v[30:33], v[68:69], off
	global_load_dwordx4 v[102:105], v154, s[24:25]
	global_load_dwordx4 v[106:109], v[72:73], off
	global_load_dwordx4 v[110:113], v1, s[26:27]
	global_load_dwordx4 v[116:119], v[70:71], off
	global_load_dwordx4 v[130:133], v154, s[26:27]
	global_load_dwordx4 v[160:163], v[74:75], off
	global_load_dwordx4 v[164:167], v155, s[24:25]
	global_load_dwordx4 v[168:171], v[76:77], off
	global_load_dwordx4 v[172:175], v155, s[26:27]
	global_load_dwordx4 v[176:179], v[78:79], off
	v_lshl_add_u64 v[152:153], s[14:15], 0, v[86:87]
	v_add_co_u32_e32 v2, vcc, 0x7800000, v152
	v_lshl_add_u64 v[4:5], s[8:9], 0, v[66:67]
	s_nop 0
	v_addc_co_u32_e32 v3, vcc, 0, v153, vcc
	global_load_dwordx2 v[122:123], v[2:3], off
	global_load_dwordx2 v[126:127], v[2:3], off offset:512
	global_load_dwordx2 v[208:209], v[2:3], off offset:1024
	v_lshl_add_u64 v[6:7], s[12:13], 0, v[66:67]
	global_load_dwordx2 v[210:211], v[2:3], off offset:1536
	global_load_dwordx4 v[180:183], v[80:81], off
	global_load_dwordx4 v[184:187], v[4:5], off
	global_load_dwordx4 v[188:191], v[4:5], off offset:1024
	global_load_dwordx4 v[192:195], v[4:5], off offset:2048
	global_load_dwordx4 v[196:199], v[4:5], off offset:3072
	global_load_dwordx4 v[62:65], v[6:7], off
	global_load_dwordx4 v[58:61], v[6:7], off offset:1024
	global_load_dwordx4 v[54:57], v[6:7], off offset:2048
	global_load_dwordx4 v[50:53], v[6:7], off offset:3072
	v_lshl_add_u64 v[142:143], s[4:5], 0, v[86:87]
	v_add_co_u32_e32 v2, vcc, s33, v142
	v_lshl_add_u64 v[4:5], v[84:85], 0, s[20:21]
	s_nop 0
	v_addc_co_u32_e32 v3, vcc, 0, v143, vcc
	v_lshl_add_u64 v[6:7], v[88:89], 0, s[18:19]
	v_lshl_add_u64 v[18:19], v[84:85], 0, s[22:23]
	v_lshl_add_u64 v[20:21], v[88:89], 0, s[16:17]
	global_load_dwordx2 v[150:151], v[2:3], off
	global_load_dwordx2 v[148:149], v[2:3], off offset:512
	global_load_dwordx2 v[146:147], v[2:3], off offset:1024
	global_load_dwordx2 v[144:145], v[2:3], off offset:1536
	global_load_dwordx4 v[46:49], v[4:5], off
	global_load_dwordx4 v[42:45], v[4:5], off offset:1024
	global_load_dwordx4 v[38:41], v[4:5], off offset:2048
	global_load_dwordx4 v[34:37], v[4:5], off offset:3072
	global_load_dwordx2 v[140:141], v[6:7], off
	global_load_dwordx2 v[138:139], v[6:7], off offset:512
	global_load_dwordx2 v[136:137], v[6:7], off offset:1024
	global_load_dwordx2 v[134:135], v[6:7], off offset:1536
	global_load_dwordx4 v[14:17], v[18:19], off
	global_load_dwordx4 v[10:13], v[18:19], off offset:1024
	s_nop 0
	global_load_dwordx4 v[6:9], v[18:19], off offset:2048
	global_load_dwordx4 v[2:5], v[18:19], off offset:3072
	global_load_dwordx2 v[100:101], v[20:21], off
	global_load_dwordx2 v[98:99], v[20:21], off offset:512
	global_load_dwordx2 v[96:97], v[20:21], off offset:1024
	global_load_dwordx2 v[94:95], v[20:21], off offset:1536
	s_nop 0
	global_load_dwordx4 v[18:21], v1, s[0:1]
	global_load_dwordx4 v[200:203], v156, s[24:25]
	global_load_dwordx4 v[204:207], v156, s[26:27]
	global_load_dwordx4 v[26:29], v1, s[0:1] offset:3072
	s_add_i32 s24, s3, s38
	s_waitcnt vmcnt(0)
	v_pk_mul_f32 v[124:125], v[24:25], v[32:33]
	v_pk_mul_f32 v[128:129], v[22:23], v[30:31]
	v_pk_mul_f32 v[114:115], v[104:105], v[108:109]
	v_pk_add_f32 v[22:23], v[112:113], 1.0 op_sel_hi:[1,0]
	v_pk_add_f32 v[24:25], v[110:111], 1.0 op_sel_hi:[1,0]
	v_pk_mul_f32 v[110:111], v[118:119], v[22:23]
	v_pk_mul_f32 v[112:113], v[116:117], v[24:25]
	v_pk_add_f32 v[22:23], v[132:133], 1.0 op_sel_hi:[1,0]
	v_pk_add_f32 v[24:25], v[130:131], 1.0 op_sel_hi:[1,0]
	v_pk_mul_f32 v[104:105], v[162:163], v[22:23]
	v_pk_mul_f32 v[108:109], v[160:161], v[24:25]
	v_pk_add_f32 v[22:23], v[174:175], 1.0 op_sel_hi:[1,0]
	v_pk_add_f32 v[24:25], v[172:173], 1.0 op_sel_hi:[1,0]
	v_pk_mul_f32 v[120:121], v[102:103], v[106:107]
	v_pk_mul_f32 v[102:103], v[178:179], v[22:23]
	v_pk_mul_f32 v[106:107], v[176:177], v[24:25]
	global_load_dwordx4 v[30:33], v1, s[0:1] offset:1024
	global_load_dwordx4 v[22:25], v1, s[0:1] offset:2048
	global_load_dwordx4 v[160:163], v[82:83], off
	v_pk_mul_f32 v[116:117], v[166:167], v[170:171]
	v_pk_mul_f32 v[118:119], v[164:165], v[168:169]
	v_and_b32_e32 v165, 0xffff0000, v122
	v_and_b32_e32 v167, 0xffff0000, v123
	v_lshlrev_b32_e32 v164, 16, v122
	v_lshlrev_b32_e32 v166, 16, v123
	v_mul_f32_e32 v122, v167, v167
	v_and_b32_e32 v171, 0xffff0000, v127
	v_and_b32_e32 v170, 0xffff0000, v126
	v_mul_f32_e32 v130, v165, v165
	v_pk_fma_f32 v[122:123], v[166:167], v[166:167], v[122:123] op_sel_hi:[1,1,0]
	v_lshlrev_b32_e32 v169, 16, v127
	v_lshlrev_b32_e32 v168, 16, v126
	v_pk_mul_f32 v[126:127], v[170:171], v[170:171]
	v_lshlrev_b32_e32 v177, 16, v210
	v_pk_fma_f32 v[130:131], v[164:165], v[164:165], v[130:131] op_sel_hi:[1,1,0]
	v_pk_fma_f32 v[126:127], v[168:169], v[168:169], v[126:127]
	v_and_b32_e32 v179, 0xffff0000, v210
	v_mov_b32_e32 v176, v130
	v_mov_b32_e32 v132, v122
	v_mov_b32_e32 v133, v177
	v_mul_f32_e32 v159, v179, v179
	v_pk_add_f32 v[122:123], v[130:131], v[122:123]
	v_pk_mul_f32 v[130:131], v[176:177], v[132:133]
	v_pk_add_f32 v[126:127], v[126:127], v[126:127] op_sel:[0,1] op_sel_hi:[1,0]
	v_and_b32_e32 v173, 0xffff0000, v208
	v_and_b32_e32 v175, 0xffff0000, v209
	v_mov_b32_e32 v123, v131
	v_mov_b32_e32 v127, v159
	v_lshlrev_b32_e32 v172, 16, v208
	v_lshlrev_b32_e32 v174, 16, v209
	v_lshlrev_b32_e32 v208, 16, v211
	v_and_b32_e32 v209, 0xffff0000, v211
	v_pk_add_f32 v[122:123], v[122:123], v[126:127]
	v_mul_f32_e32 v126, v173, v173
	v_mul_f32_e32 v130, v175, v175
	v_mul_f32_e32 v178, v208, v208
	v_mul_f32_e32 v210, v209, v209
	v_pk_fma_f32 v[126:127], v[172:173], v[172:173], v[126:127] op_sel_hi:[1,1,0]
	v_pk_fma_f32 v[130:131], v[174:175], v[174:175], v[130:131] op_sel_hi:[1,1,0]
	v_mov_b32_e32 v127, v178
	v_mov_b32_e32 v131, v210
	v_pk_add_f32 v[126:127], v[126:127], v[130:131]
	v_pk_mul_f32 v[132:133], v[200:201], v[180:181]
	v_pk_add_f32 v[122:123], v[122:123], v[126:127]
	v_pk_mul_f32 v[130:131], v[202:203], v[182:183]
	v_add_f32_e32 v122, v122, v123
	s_nop 1
	v_add_f32_dpp v122, v122, v122 quad_perm:[1,0,3,2] row_mask:0xf bank_mask:0xf bound_ctrl:1
	s_nop 1
	v_add_f32_dpp v122, v122, v122 quad_perm:[2,3,0,1] row_mask:0xf bank_mask:0xf bound_ctrl:1
	s_nop 1
	v_add_f32_dpp v122, v122, v122 row_half_mirror row_mask:0xf bank_mask:0xf bound_ctrl:1
	s_nop 1
	v_add_f32_dpp v122, v122, v122 row_mirror row_mask:0xf bank_mask:0xf bound_ctrl:1
	s_nop 0
	v_readlane_b32 s20, v122, 16
	v_readlane_b32 s21, v122, 48
	v_readlane_b32 s0, v122, 0
	v_readlane_b32 s1, v122, 32
	v_mov_b32_e32 v122, s20
	v_mov_b32_e32 v123, s21
	v_pk_add_f32 v[122:123], s[0:1], v[122:123]
	s_nop 0
	v_add_f32_e32 v122, v122, v123
	v_fmamk_f32 v122, v122, 0x3a800000, v157
	v_mul_f32_e32 v123, 0x4f800000, v122
	v_cmp_gt_f32_e32 vcc, s34, v122
	s_nop 1
	v_cndmask_b32_e32 v126, v122, v123, vcc
	v_sqrt_f32_e32 v127, v126
	v_pk_add_f32 v[122:123], v[206:207], 1.0 op_sel_hi:[1,0]
	v_add_u32_e32 v159, -1, v127
	v_fma_f32 v176, -v159, v127, v126
	v_cmp_ge_f32_e64 s[0:1], 0, v176
	v_add_u32_e32 v176, 1, v127
	s_waitcnt vmcnt(0)
	v_pk_mul_f32 v[122:123], v[162:163], v[122:123]
	v_cndmask_b32_e64 v159, v127, v159, s[0:1]
	v_fma_f32 v127, -v176, v127, v126
	v_cmp_lt_f32_e64 s[0:1], 0, v127
	s_nop 1
	v_cndmask_b32_e64 v127, v159, v176, s[0:1]
	v_mul_f32_e32 v159, 0x37800000, v127
	v_cndmask_b32_e32 v127, v127, v159, vcc
	v_cmp_class_f32_e32 vcc, v126, v158
	s_nop 1
	v_cndmask_b32_e32 v159, v127, v126, vcc
	v_div_scale_f32 v176, s[0:1], v159, v159, 1.0
	v_rcp_f32_e32 v178, v176
	v_pk_add_f32 v[126:127], v[204:205], 1.0 op_sel_hi:[1,0]
	s_nop 0
	v_pk_mul_f32 v[126:127], v[160:161], v[126:127]
	v_fma_f32 v160, -v176, v178, 1.0
	v_fmac_f32_e32 v178, v160, v178
	v_div_scale_f32 v160, vcc, 1.0, v159, 1.0
	v_mul_f32_e32 v161, v160, v178
	v_fma_f32 v162, -v176, v161, v160
	v_fmac_f32_e32 v161, v162, v178
	v_fma_f32 v160, -v176, v161, v160
	v_div_fmas_f32 v160, v160, v178, v161
	v_div_fixup_f32 v160, v160, v159, 1.0
	v_pk_mul_f32 v[162:163], v[160:161], v[164:165] op_sel_hi:[0,1]
	v_pk_mul_f32 v[164:165], v[160:161], v[166:167] op_sel_hi:[0,1]
	v_pk_fma_f32 v[164:165], v[124:125], v[164:165], v[186:187]
	v_pk_fma_f32 v[162:163], v[128:129], v[162:163], v[184:185]
	v_add_co_u32_e32 v180, vcc, s35, v152
	v_cvt_pk_bf16_f32 v166, v162, v163
	v_cvt_pk_bf16_f32 v167, v164, v165
	v_addc_co_u32_e32 v181, vcc, 0, v153, vcc
	global_store_dwordx2 v[180:181], v[166:167], off nt
	v_mov_b32_e32 v166, v168
	v_mov_b32_e32 v167, v170
	v_mov_b32_e32 v170, v169
	v_pk_mul_f32 v[166:167], v[160:161], v[166:167] op_sel_hi:[0,1]
	v_pk_mul_f32 v[168:169], v[160:161], v[170:171] op_sel_hi:[0,1]
	v_pk_fma_f32 v[168:169], v[114:115], v[168:169], v[190:191]
	v_pk_fma_f32 v[166:167], v[120:121], v[166:167], v[188:189]
	v_cvt_pk_bf16_f32 v171, v168, v169
	v_cvt_pk_bf16_f32 v170, v166, v167
	v_mov_b32_e32 v178, v177
	global_store_dwordx2 v[180:181], v[170:171], off offset:512 nt
	v_pk_mul_f32 v[170:171], v[160:161], v[172:173] op_sel_hi:[0,1]
	v_pk_mul_f32 v[172:173], v[160:161], v[174:175] op_sel_hi:[0,1]
	v_pk_mul_f32 v[174:175], v[178:179], v[160:161] op_sel_hi:[1,0]
	v_pk_mul_f32 v[176:177], v[164:165], v[164:165]
	v_pk_mul_f32 v[178:179], v[162:163], v[162:163]
	v_pk_fma_f32 v[170:171], v[118:119], v[170:171], v[192:193]
	v_pk_mov_b32 v[182:183], v[178:179], v[176:177] op_sel:[1,0]
	v_mov_b32_e32 v179, v177
	v_pk_add_f32 v[176:177], v[182:183], v[178:179]
	v_pk_mul_f32 v[178:179], v[168:169], v[168:169]
	v_pk_add_f32 v[176:177], v[176:177], v[176:177] op_sel_hi:[0,1]
	v_pk_mul_f32 v[182:183], v[166:167], v[166:167]
	v_pk_fma_f32 v[172:173], v[116:117], v[172:173], v[194:195]
	v_pk_mov_b32 v[184:185], v[182:183], v[178:179] op_sel:[1,0]
	v_mov_b32_e32 v183, v179
	v_mul_f32_e32 v176, v170, v170
	v_pk_mul_f32 v[160:161], v[208:209], v[160:161] op_sel_hi:[1,0]
	v_pk_add_f32 v[178:179], v[184:185], v[182:183]
	v_pk_fma_f32 v[182:183], v[170:171], v[170:171], v[176:177] op_sel_hi:[1,1,0]
	v_mul_f32_e32 v176, v172, v172
	v_pk_fma_f32 v[160:161], v[130:131], v[160:161], v[198:199]
	v_pk_fma_f32 v[174:175], v[132:133], v[174:175], v[196:197]
	v_pk_add_f32 v[178:179], v[178:179], v[178:179] op_sel_hi:[0,1]
	v_pk_fma_f32 v[184:185], v[172:173], v[172:173], v[176:177] op_sel_hi:[1,1,0]
	v_mul_f32_e32 v182, v174, v174
	v_mul_f32_e32 v184, v175, v175
	v_mul_f32_e32 v176, v160, v160
	v_mul_f32_e32 v178, v161, v161
	v_pk_add_f32 v[182:183], v[182:183], v[184:185]
	v_pk_add_f32 v[176:177], v[176:177], v[178:179]
	s_nop 0
	v_pk_add_f32 v[176:177], v[182:183], v[176:177]
	s_nop 0
	v_add_f32_e32 v159, v176, v177
	s_nop 1
	v_add_f32_dpp v159, v159, v159 quad_perm:[1,0,3,2] row_mask:0xf bank_mask:0xf bound_ctrl:1
	s_nop 1
	v_add_f32_dpp v159, v159, v159 quad_perm:[2,3,0,1] row_mask:0xf bank_mask:0xf bound_ctrl:1
	s_nop 1
	v_add_f32_dpp v159, v159, v159 row_half_mirror row_mask:0xf bank_mask:0xf bound_ctrl:1
	s_nop 1
	v_add_f32_dpp v159, v159, v159 row_mirror row_mask:0xf bank_mask:0xf bound_ctrl:1
	s_nop 0
	v_readlane_b32 s20, v159, 16
	v_readlane_b32 s21, v159, 48
	v_readlane_b32 s0, v159, 0
	v_readlane_b32 s1, v159, 32
	v_mov_b32_e32 v176, s20
	v_mov_b32_e32 v177, s21
	v_pk_add_f32 v[176:177], s[0:1], v[176:177]
	s_nop 0
	v_add_f32_e32 v159, v176, v177
	v_fmamk_f32 v159, v159, 0x3a800000, v157
	v_mul_f32_e32 v176, 0x4f800000, v159
	v_cmp_gt_f32_e32 vcc, s34, v159
	v_cvt_pk_bf16_f32 v177, v172, v173
	s_nop 0
	v_cndmask_b32_e32 v159, v159, v176, vcc
	v_sqrt_f32_e32 v178, v159
	v_cvt_pk_bf16_f32 v176, v170, v171
	global_store_dwordx2 v[180:181], v[176:177], off offset:1024 nt
	v_add_u32_e32 v176, -1, v178
	v_fma_f32 v177, -v176, v178, v159
	v_cmp_ge_f32_e64 s[0:1], 0, v177
	v_add_u32_e32 v177, 1, v178
	s_nop 0
	v_cndmask_b32_e64 v176, v178, v176, s[0:1]
	v_fma_f32 v178, -v177, v178, v159
	v_cmp_lt_f32_e64 s[0:1], 0, v178
	s_nop 1
	v_cndmask_b32_e64 v176, v176, v177, s[0:1]
	v_mul_f32_e32 v177, 0x37800000, v176
	v_cndmask_b32_e32 v176, v176, v177, vcc
	v_cmp_class_f32_e32 vcc, v159, v158
	v_cvt_pk_bf16_f32 v177, v160, v161
	s_nop 0
	v_cndmask_b32_e32 v159, v176, v159, vcc
	v_div_scale_f32 v178, s[0:1], v159, v159, 1.0
	v_rcp_f32_e32 v179, v178
	v_cvt_pk_bf16_f32 v176, v174, v175
	global_store_dwordx2 v[180:181], v[176:177], off offset:1536 nt
	s_ashr_i32 s0, s24, 31
	v_fma_f32 v176, -v178, v179, 1.0
	v_fmac_f32_e32 v179, v176, v179
	v_div_scale_f32 v176, vcc, 1.0, v159, 1.0
	v_mul_f32_e32 v177, v176, v179
	v_fma_f32 v180, -v178, v177, v176
	v_fmac_f32_e32 v177, v180, v179
	v_fma_f32 v176, -v178, v177, v176
	v_div_fmas_f32 v176, v176, v179, v177
	v_div_fixup_f32 v176, v176, v159, 1.0
	v_pk_mul_f32 v[162:163], v[162:163], v[176:177] op_sel_hi:[1,0]
	v_pk_mul_f32 v[164:165], v[164:165], v[176:177] op_sel_hi:[1,0]
	v_pk_fma_f32 v[162:163], v[112:113], v[162:163], v[18:19]
	v_pk_fma_f32 v[164:165], v[110:111], v[164:165], v[20:21]
	v_add_co_u32_e32 v152, vcc, s36, v152
	v_cvt_pk_bf16_f32 v162, v162, v163
	v_cvt_pk_bf16_f32 v163, v164, v165
	v_addc_co_u32_e32 v153, vcc, 0, v153, vcc
	global_store_dwordx2 v[152:153], v[162:163], off nt
	v_pk_mul_f32 v[162:163], v[166:167], v[176:177] op_sel_hi:[1,0]
	v_pk_mul_f32 v[164:165], v[168:169], v[176:177] op_sel_hi:[1,0]
	v_pk_fma_f32 v[162:163], v[108:109], v[162:163], v[30:31]
	v_pk_fma_f32 v[164:165], v[104:105], v[164:165], v[32:33]
	v_cvt_pk_bf16_f32 v162, v162, v163
	v_cvt_pk_bf16_f32 v163, v164, v165
	global_store_dwordx2 v[152:153], v[162:163], off offset:512 nt
	v_pk_mul_f32 v[162:163], v[170:171], v[176:177] op_sel_hi:[1,0]
	v_pk_mul_f32 v[164:165], v[172:173], v[176:177] op_sel_hi:[1,0]
	v_pk_fma_f32 v[162:163], v[106:107], v[162:163], v[22:23]
	v_pk_fma_f32 v[164:165], v[102:103], v[164:165], v[24:25]
	v_cvt_pk_bf16_f32 v162, v162, v163
	v_cvt_pk_bf16_f32 v163, v164, v165
	s_lshr_b32 s0, s0, 18
	global_store_dwordx2 v[152:153], v[162:163], off offset:1024 nt
	v_pk_mul_f32 v[162:163], v[174:175], v[176:177] op_sel_hi:[1,0]
	v_pk_mul_f32 v[160:161], v[160:161], v[176:177] op_sel_hi:[1,0]
	s_add_i32 s0, s24, s0
	v_pk_fma_f32 v[160:161], v[122:123], v[160:161], v[28:29]
	v_pk_fma_f32 v[162:163], v[126:127], v[162:163], v[26:27]
	s_ashr_i32 s25, s0, 14
	v_cvt_pk_bf16_f32 v162, v162, v163
	v_cvt_pk_bf16_f32 v163, v160, v161
	s_cmp_eq_u32 s25, s37
	global_store_dwordx2 v[152:153], v[162:163], off offset:1536 nt
	s_cbranch_scc1 .LBB0_581
	s_mul_i32 s0, s25, 0xc00
	s_ashr_i32 s1, s0, 31
	s_lshl_b64 s[0:1], s[0:1], 2
	s_add_u32 s20, s94, s0
	s_addc_u32 s21, s95, s1
	s_add_u32 s22, s20, 0x2000
	s_addc_u32 s23, s21, 0
	s_add_u32 s0, s28, s0
	global_load_dwordx4 v[102:105], v1, s[22:23]
	global_load_dwordx4 v[106:109], v[68:69], off
	global_load_dwordx4 v[110:113], v154, s[22:23]
	global_load_dwordx4 v[116:119], v[72:73], off
	global_load_dwordx4 v[130:133], v155, s[22:23]
	global_load_dwordx4 v[160:163], v[76:77], off
	global_load_dwordx4 v[164:167], v156, s[22:23]
	global_load_dwordx4 v[168:171], v[80:81], off
	s_addc_u32 s1, s29, s1
	s_add_u32 s20, s0, 0x1000
	s_addc_u32 s21, s1, 0
	global_load_dwordx4 v[172:175], v1, s[20:21]
	global_load_dwordx4 v[176:179], v154, s[20:21]
	global_load_dwordx4 v[180:183], v155, s[20:21]
	global_load_dwordx4 v[184:187], v156, s[20:21]
	global_load_dwordx4 v[188:191], v[70:71], off
	global_load_dwordx4 v[192:195], v[74:75], off
	global_load_dwordx4 v[196:199], v[78:79], off
	global_load_dwordx4 v[200:203], v[82:83], off
	global_load_dwordx4 v[18:21], v1, s[0:1]
	global_load_dwordx4 v[30:33], v1, s[0:1] offset:1024
	global_load_dwordx4 v[22:25], v1, s[0:1] offset:2048
	global_load_dwordx4 v[26:29], v1, s[0:1] offset:3072
	s_mov_b32 s37, s25
	s_waitcnt vmcnt(18)
	v_pk_mul_f32 v[124:125], v[104:105], v[108:109]
	v_pk_mul_f32 v[128:129], v[102:103], v[106:107]
	s_waitcnt vmcnt(16)
	v_pk_mul_f32 v[114:115], v[112:113], v[118:119]
	s_waitcnt vmcnt(11)
	v_pk_add_f32 v[102:103], v[174:175], 1.0 op_sel_hi:[1,0]
	v_pk_mul_f32 v[118:119], v[130:131], v[160:161]
	v_pk_add_f32 v[104:105], v[172:173], 1.0 op_sel_hi:[1,0]
	s_waitcnt vmcnt(10)
	v_pk_add_f32 v[106:107], v[178:179], 1.0 op_sel_hi:[1,0]
	v_pk_add_f32 v[108:109], v[176:177], 1.0 op_sel_hi:[1,0]
	s_waitcnt vmcnt(9)
	v_pk_add_f32 v[122:123], v[182:183], 1.0 op_sel_hi:[1,0]
	v_pk_add_f32 v[126:127], v[180:181], 1.0 op_sel_hi:[1,0]
	s_waitcnt vmcnt(8)
	v_pk_add_f32 v[152:153], v[186:187], 1.0 op_sel_hi:[1,0]
	v_pk_add_f32 v[160:161], v[184:185], 1.0 op_sel_hi:[1,0]
	v_pk_mul_f32 v[120:121], v[110:111], v[116:117]
	v_pk_mul_f32 v[116:117], v[132:133], v[162:163]
	v_pk_mul_f32 v[130:131], v[166:167], v[170:171]
	v_pk_mul_f32 v[132:133], v[164:165], v[168:169]
	s_waitcnt vmcnt(7)
	v_pk_mul_f32 v[110:111], v[190:191], v[102:103]
	v_pk_mul_f32 v[112:113], v[188:189], v[104:105]
	s_waitcnt vmcnt(6)
	v_pk_mul_f32 v[104:105], v[194:195], v[106:107]
	v_pk_mul_f32 v[108:109], v[192:193], v[108:109]
	s_waitcnt vmcnt(5)
	v_pk_mul_f32 v[102:103], v[198:199], v[122:123]
	v_pk_mul_f32 v[106:107], v[196:197], v[126:127]
	s_waitcnt vmcnt(4)
	v_pk_mul_f32 v[122:123], v[202:203], v[152:153]
	v_pk_mul_f32 v[126:127], v[200:201], v[160:161]
.LBB0_581:
	v_lshlrev_b32_e32 v152, 16, v150
	v_and_b32_e32 v153, 0xffff0000, v150
	v_lshlrev_b32_e32 v150, 16, v151
	v_and_b32_e32 v151, 0xffff0000, v151
	v_mul_f32_e32 v160, v151, v151
	v_lshlrev_b32_e32 v163, 16, v149
	v_lshlrev_b32_e32 v162, 16, v148
	v_and_b32_e32 v149, 0xffff0000, v149
	v_and_b32_e32 v148, 0xffff0000, v148
	v_lshlrev_b32_e32 v169, 16, v144
	v_mul_f32_e32 v168, v153, v153
	v_pk_fma_f32 v[160:161], v[150:151], v[150:151], v[160:161] op_sel_hi:[1,1,0]
	v_pk_mul_f32 v[164:165], v[148:149], v[148:149]
	v_pk_fma_f32 v[172:173], v[152:153], v[152:153], v[168:169] op_sel_hi:[1,1,0]
	v_pk_fma_f32 v[164:165], v[162:163], v[162:163], v[164:165]
	v_and_b32_e32 v171, 0xffff0000, v144
	v_mov_b32_e32 v168, v172
	v_mov_b32_e32 v174, v160
	v_mov_b32_e32 v175, v169
	v_mul_f32_e32 v159, v171, v171
	v_pk_add_f32 v[160:161], v[172:173], v[160:161]
	v_pk_mul_f32 v[172:173], v[168:169], v[174:175]
	v_pk_add_f32 v[164:165], v[164:165], v[164:165] op_sel:[0,1] op_sel_hi:[1,0]
	v_lshlrev_b32_e32 v166, 16, v146
	v_and_b32_e32 v167, 0xffff0000, v146
	v_lshlrev_b32_e32 v146, 16, v147
	v_and_b32_e32 v147, 0xffff0000, v147
	v_mov_b32_e32 v161, v173
	v_mov_b32_e32 v165, v159
	v_lshlrev_b32_e32 v144, 16, v145
	v_and_b32_e32 v145, 0xffff0000, v145
	v_pk_add_f32 v[160:161], v[160:161], v[164:165]
	v_mul_f32_e32 v164, v167, v167
	v_mul_f32_e32 v168, v147, v147
	v_mul_f32_e32 v170, v144, v144
	v_mul_f32_e32 v176, v145, v145
	v_pk_fma_f32 v[164:165], v[166:167], v[166:167], v[164:165] op_sel_hi:[1,1,0]
	v_pk_fma_f32 v[172:173], v[146:147], v[146:147], v[168:169] op_sel_hi:[1,1,0]
	v_mov_b32_e32 v165, v170
	v_mov_b32_e32 v173, v176
	v_pk_add_f32 v[164:165], v[164:165], v[172:173]
	v_mov_b32_e32 v170, v169
	v_pk_add_f32 v[160:161], v[160:161], v[164:165]
	s_add_i32 s24, s3, s24
	v_add_f32_e32 v159, v160, v161
	s_nop 1
	v_add_f32_dpp v159, v159, v159 quad_perm:[1,0,3,2] row_mask:0xf bank_mask:0xf bound_ctrl:1
	s_nop 1
	v_add_f32_dpp v159, v159, v159 quad_perm:[2,3,0,1] row_mask:0xf bank_mask:0xf bound_ctrl:1
	s_nop 1
	v_add_f32_dpp v159, v159, v159 row_half_mirror row_mask:0xf bank_mask:0xf bound_ctrl:1
	s_nop 1
	v_add_f32_dpp v159, v159, v159 row_mirror row_mask:0xf bank_mask:0xf bound_ctrl:1
	s_nop 0
	v_readlane_b32 s20, v159, 16
	v_readlane_b32 s21, v159, 48
	v_readlane_b32 s0, v159, 0
	v_readlane_b32 s1, v159, 32
	v_mov_b32_e32 v160, s20
	v_mov_b32_e32 v161, s21
	v_pk_add_f32 v[160:161], s[0:1], v[160:161]
	s_nop 0
	v_add_f32_e32 v159, v160, v161
	v_fmamk_f32 v159, v159, 0x3a800000, v157
	v_mul_f32_e32 v160, 0x4f800000, v159
	v_cmp_gt_f32_e32 vcc, s34, v159
	s_nop 1
	v_cndmask_b32_e32 v159, v159, v160, vcc
	v_sqrt_f32_e32 v160, v159
	s_nop 0
	v_add_u32_e32 v161, -1, v160
	v_fma_f32 v164, -v161, v160, v159
	v_cmp_ge_f32_e64 s[0:1], 0, v164
	v_add_u32_e32 v164, 1, v160
	s_nop 0
	v_cndmask_b32_e64 v161, v160, v161, s[0:1]
	v_fma_f32 v160, -v164, v160, v159
	v_cmp_lt_f32_e64 s[0:1], 0, v160
	s_nop 1
	v_cndmask_b32_e64 v160, v161, v164, s[0:1]
	v_mul_f32_e32 v161, 0x37800000, v160
	v_cndmask_b32_e32 v160, v160, v161, vcc
	v_cmp_class_f32_e32 vcc, v159, v158
	s_nop 1
	v_cndmask_b32_e32 v159, v160, v159, vcc
	v_div_scale_f32 v160, s[0:1], v159, v159, 1.0
	v_rcp_f32_e32 v161, v160
	s_nop 0
	v_fma_f32 v164, -v160, v161, 1.0
	v_fmac_f32_e32 v161, v164, v161
	v_div_scale_f32 v164, vcc, 1.0, v159, 1.0
	v_mul_f32_e32 v165, v164, v161
	v_fma_f32 v168, -v160, v165, v164
	v_fmac_f32_e32 v165, v168, v161
	v_fma_f32 v160, -v160, v165, v164
	v_div_fmas_f32 v160, v160, v161, v165
	v_div_fixup_f32 v160, v160, v159, 1.0
	v_pk_mul_f32 v[152:153], v[160:161], v[152:153] op_sel_hi:[0,1]
	v_pk_mul_f32 v[150:151], v[160:161], v[150:151] op_sel_hi:[0,1]
	v_pk_fma_f32 v[64:65], v[124:125], v[150:151], v[64:65]
	v_pk_fma_f32 v[62:63], v[128:129], v[152:153], v[62:63]
	v_add_co_u32_e32 v152, vcc, s35, v142
	v_cvt_pk_bf16_f32 v150, v62, v63
	v_cvt_pk_bf16_f32 v151, v64, v65
	v_addc_co_u32_e32 v153, vcc, 0, v143, vcc
	global_store_dwordx2 v[152:153], v[150:151], off nt
	v_mov_b32_e32 v150, v162
	v_mov_b32_e32 v151, v148
	v_mov_b32_e32 v148, v163
	v_pk_mul_f32 v[150:151], v[160:161], v[150:151] op_sel_hi:[0,1]
	v_pk_mul_f32 v[148:149], v[160:161], v[148:149] op_sel_hi:[0,1]
	v_pk_fma_f32 v[60:61], v[114:115], v[148:149], v[60:61]
	v_pk_fma_f32 v[58:59], v[120:121], v[150:151], v[58:59]
	v_pk_mul_f32 v[146:147], v[160:161], v[146:147] op_sel_hi:[0,1]
	v_cvt_pk_bf16_f32 v148, v58, v59
	v_cvt_pk_bf16_f32 v149, v60, v61
	v_pk_fma_f32 v[56:57], v[116:117], v[146:147], v[56:57]
	v_pk_mul_f32 v[146:147], v[170:171], v[160:161] op_sel_hi:[1,0]
	v_pk_mul_f32 v[144:145], v[144:145], v[160:161] op_sel_hi:[1,0]
	global_store_dwordx2 v[152:153], v[148:149], off offset:512 nt
	v_pk_mul_f32 v[148:149], v[160:161], v[166:167] op_sel_hi:[0,1]
	v_pk_fma_f32 v[52:53], v[130:131], v[144:145], v[52:53]
	v_pk_fma_f32 v[50:51], v[132:133], v[146:147], v[50:51]
	v_pk_mul_f32 v[144:145], v[64:65], v[64:65]
	v_pk_mul_f32 v[146:147], v[62:63], v[62:63]
	v_pk_fma_f32 v[54:55], v[118:119], v[148:149], v[54:55]
	v_pk_mov_b32 v[148:149], v[146:147], v[144:145] op_sel:[1,0]
	v_mov_b32_e32 v147, v145
	v_pk_add_f32 v[144:145], v[148:149], v[146:147]
	v_pk_mul_f32 v[146:147], v[60:61], v[60:61]
	v_pk_add_f32 v[144:145], v[144:145], v[144:145] op_sel_hi:[0,1]
	v_pk_mul_f32 v[148:149], v[58:59], v[58:59]
	v_mul_f32_e32 v144, v54, v54
	v_pk_mov_b32 v[150:151], v[148:149], v[146:147] op_sel:[1,0]
	v_mov_b32_e32 v149, v147
	v_pk_add_f32 v[146:147], v[150:151], v[148:149]
	v_pk_fma_f32 v[148:149], v[54:55], v[54:55], v[144:145] op_sel_hi:[1,1,0]
	v_mul_f32_e32 v144, v56, v56
	v_pk_add_f32 v[146:147], v[146:147], v[146:147] op_sel_hi:[0,1]
	v_pk_fma_f32 v[150:151], v[56:57], v[56:57], v[144:145] op_sel_hi:[1,1,0]
	v_mul_f32_e32 v148, v50, v50
	v_mul_f32_e32 v150, v51, v51
	v_mul_f32_e32 v144, v52, v52
	v_mul_f32_e32 v146, v53, v53
	v_pk_add_f32 v[148:149], v[148:149], v[150:151]
	v_pk_add_f32 v[144:145], v[144:145], v[146:147]
	s_nop 0
	v_pk_add_f32 v[144:145], v[148:149], v[144:145]
	s_nop 0
	v_add_f32_e32 v144, v144, v145
	s_nop 1
	v_add_f32_dpp v144, v144, v144 quad_perm:[1,0,3,2] row_mask:0xf bank_mask:0xf bound_ctrl:1
	s_nop 1
	v_add_f32_dpp v144, v144, v144 quad_perm:[2,3,0,1] row_mask:0xf bank_mask:0xf bound_ctrl:1
	s_nop 1
	v_add_f32_dpp v144, v144, v144 row_half_mirror row_mask:0xf bank_mask:0xf bound_ctrl:1
	s_nop 1
	v_add_f32_dpp v144, v144, v144 row_mirror row_mask:0xf bank_mask:0xf bound_ctrl:1
	s_nop 0
	v_readlane_b32 s20, v144, 16
	v_readlane_b32 s21, v144, 48
	v_readlane_b32 s0, v144, 0
	v_readlane_b32 s1, v144, 32
	v_mov_b32_e32 v144, s20
	v_mov_b32_e32 v145, s21
	v_pk_add_f32 v[144:145], s[0:1], v[144:145]
	s_nop 0
	v_add_f32_e32 v144, v144, v145
	v_fmamk_f32 v144, v144, 0x3a800000, v157
	v_mul_f32_e32 v145, 0x4f800000, v144
	v_cmp_gt_f32_e32 vcc, s34, v144
	s_nop 1
	v_cndmask_b32_e32 v146, v144, v145, vcc
	v_sqrt_f32_e32 v147, v146
	v_cvt_pk_bf16_f32 v144, v54, v55
	v_cvt_pk_bf16_f32 v145, v56, v57
	global_store_dwordx2 v[152:153], v[144:145], off offset:1024 nt
	v_add_u32_e32 v144, -1, v147
	v_fma_f32 v145, -v144, v147, v146
	v_cmp_ge_f32_e64 s[0:1], 0, v145
	v_add_u32_e32 v145, 1, v147
	s_nop 0
	v_cndmask_b32_e64 v144, v147, v144, s[0:1]
	v_fma_f32 v147, -v145, v147, v146
	v_cmp_lt_f32_e64 s[0:1], 0, v147
	s_nop 1
	v_cndmask_b32_e64 v144, v144, v145, s[0:1]
	v_mul_f32_e32 v145, 0x37800000, v144
	v_cndmask_b32_e32 v144, v144, v145, vcc
	v_cmp_class_f32_e32 vcc, v146, v158
	v_cvt_pk_bf16_f32 v145, v52, v53
	s_nop 0
	v_cndmask_b32_e32 v146, v144, v146, vcc
	v_div_scale_f32 v147, s[0:1], v146, v146, 1.0
	v_rcp_f32_e32 v148, v147
	v_cvt_pk_bf16_f32 v144, v50, v51
	global_store_dwordx2 v[152:153], v[144:145], off offset:1536 nt
	s_ashr_i32 s0, s24, 31
	v_fma_f32 v144, -v147, v148, 1.0
	v_fmac_f32_e32 v148, v144, v148
	v_div_scale_f32 v144, vcc, 1.0, v146, 1.0
	v_mul_f32_e32 v145, v144, v148
	v_fma_f32 v149, -v147, v145, v144
	v_fmac_f32_e32 v145, v149, v148
	v_fma_f32 v144, -v147, v145, v144
	v_div_fmas_f32 v144, v144, v148, v145
	v_div_fixup_f32 v144, v144, v146, 1.0
	v_pk_mul_f32 v[62:63], v[62:63], v[144:145] op_sel_hi:[1,0]
	v_pk_mul_f32 v[64:65], v[64:65], v[144:145] op_sel_hi:[1,0]
	s_lshr_b32 s0, s0, 18
	s_waitcnt vmcnt(7)
	v_pk_fma_f32 v[64:65], v[110:111], v[64:65], v[20:21]
	v_pk_fma_f32 v[62:63], v[112:113], v[62:63], v[18:19]
	v_pk_mul_f32 v[58:59], v[58:59], v[144:145] op_sel_hi:[1,0]
	v_pk_mul_f32 v[60:61], v[60:61], v[144:145] op_sel_hi:[1,0]
	v_pk_mul_f32 v[54:55], v[54:55], v[144:145] op_sel_hi:[1,0]
	v_pk_mul_f32 v[56:57], v[56:57], v[144:145] op_sel_hi:[1,0]
	v_pk_mul_f32 v[50:51], v[50:51], v[144:145] op_sel_hi:[1,0]
	v_pk_mul_f32 v[52:53], v[52:53], v[144:145] op_sel_hi:[1,0]
	s_add_i32 s0, s24, s0
	v_cvt_pk_bf16_f32 v62, v62, v63
	v_cvt_pk_bf16_f32 v63, v64, v65
	v_add_co_u32_e32 v64, vcc, s36, v142
	s_waitcnt vmcnt(6)
	v_pk_fma_f32 v[60:61], v[104:105], v[60:61], v[32:33]
	v_pk_fma_f32 v[58:59], v[108:109], v[58:59], v[30:31]
	s_waitcnt vmcnt(5)
	v_pk_fma_f32 v[56:57], v[102:103], v[56:57], v[24:25]
	v_pk_fma_f32 v[54:55], v[106:107], v[54:55], v[22:23]
	s_waitcnt vmcnt(4)
	v_pk_fma_f32 v[52:53], v[122:123], v[52:53], v[28:29]
	v_pk_fma_f32 v[50:51], v[126:127], v[50:51], v[26:27]
	s_ashr_i32 s25, s0, 14
	v_addc_co_u32_e32 v65, vcc, 0, v143, vcc
	v_cvt_pk_bf16_f32 v58, v58, v59
	v_cvt_pk_bf16_f32 v59, v60, v61
	v_cvt_pk_bf16_f32 v54, v54, v55
	v_cvt_pk_bf16_f32 v55, v56, v57
	v_cvt_pk_bf16_f32 v50, v50, v51
	v_cvt_pk_bf16_f32 v51, v52, v53
	s_cmp_eq_u32 s25, s37
	global_store_dwordx2 v[64:65], v[62:63], off nt
	global_store_dwordx2 v[64:65], v[58:59], off offset:512 nt
	global_store_dwordx2 v[64:65], v[54:55], off offset:1024 nt
	global_store_dwordx2 v[64:65], v[50:51], off offset:1536 nt
	s_cbranch_scc1 .LBB0_583
	s_mul_i32 s0, s25, 0xc00
	s_ashr_i32 s1, s0, 31
	s_lshl_b64 s[0:1], s[0:1], 2
	s_add_u32 s20, s94, s0
	s_addc_u32 s21, s95, s1
	s_add_u32 s22, s20, 0x2000
	s_addc_u32 s23, s21, 0
	s_add_u32 s0, s28, s0
	global_load_dwordx4 v[50:53], v1, s[22:23]
	global_load_dwordx4 v[54:57], v[68:69], off
	global_load_dwordx4 v[58:61], v154, s[22:23]
	global_load_dwordx4 v[62:65], v[72:73], off
	global_load_dwordx4 v[102:105], v155, s[22:23]
	global_load_dwordx4 v[106:109], v[76:77], off
	global_load_dwordx4 v[110:113], v156, s[22:23]
	global_load_dwordx4 v[142:145], v[80:81], off
	s_addc_u32 s1, s29, s1
	s_add_u32 s20, s0, 0x1000
	s_addc_u32 s21, s1, 0
	global_load_dwordx4 v[146:149], v1, s[20:21]
	global_load_dwordx4 v[150:153], v154, s[20:21]
	global_load_dwordx4 v[160:163], v155, s[20:21]
	global_load_dwordx4 v[164:167], v156, s[20:21]
	global_load_dwordx4 v[168:171], v[70:71], off
	global_load_dwordx4 v[172:175], v[74:75], off
	global_load_dwordx4 v[176:179], v[78:79], off
	global_load_dwordx4 v[180:183], v[82:83], off
	global_load_dwordx4 v[18:21], v1, s[0:1]
	global_load_dwordx4 v[30:33], v1, s[0:1] offset:1024
	global_load_dwordx4 v[22:25], v1, s[0:1] offset:2048
	global_load_dwordx4 v[26:29], v1, s[0:1] offset:3072
	s_mov_b32 s37, s25
	s_waitcnt vmcnt(18)
	v_pk_mul_f32 v[124:125], v[52:53], v[56:57]
	v_pk_mul_f32 v[128:129], v[50:51], v[54:55]
	s_waitcnt vmcnt(16)
	v_pk_mul_f32 v[114:115], v[60:61], v[64:65]
	v_pk_mul_f32 v[120:121], v[58:59], v[62:63]
	s_waitcnt vmcnt(11)
	v_pk_add_f32 v[50:51], v[148:149], 1.0 op_sel_hi:[1,0]
	v_pk_add_f32 v[52:53], v[146:147], 1.0 op_sel_hi:[1,0]
	s_waitcnt vmcnt(10)
	v_pk_add_f32 v[54:55], v[152:153], 1.0 op_sel_hi:[1,0]
	v_pk_add_f32 v[56:57], v[150:151], 1.0 op_sel_hi:[1,0]
	s_waitcnt vmcnt(9)
	v_pk_add_f32 v[58:59], v[162:163], 1.0 op_sel_hi:[1,0]
	v_pk_add_f32 v[60:61], v[160:161], 1.0 op_sel_hi:[1,0]
	s_waitcnt vmcnt(8)
	v_pk_add_f32 v[62:63], v[166:167], 1.0 op_sel_hi:[1,0]
	v_pk_add_f32 v[64:65], v[164:165], 1.0 op_sel_hi:[1,0]
	v_pk_mul_f32 v[116:117], v[104:105], v[108:109]
	v_pk_mul_f32 v[118:119], v[102:103], v[106:107]
	v_pk_mul_f32 v[130:131], v[112:113], v[144:145]
	v_pk_mul_f32 v[132:133], v[110:111], v[142:143]
	s_waitcnt vmcnt(7)
	v_pk_mul_f32 v[110:111], v[170:171], v[50:51]
	v_pk_mul_f32 v[112:113], v[168:169], v[52:53]
	s_waitcnt vmcnt(6)
	v_pk_mul_f32 v[104:105], v[174:175], v[54:55]
	v_pk_mul_f32 v[108:109], v[172:173], v[56:57]
	s_waitcnt vmcnt(5)
	v_pk_mul_f32 v[102:103], v[178:179], v[58:59]
	v_pk_mul_f32 v[106:107], v[176:177], v[60:61]
	s_waitcnt vmcnt(4)
	v_pk_mul_f32 v[122:123], v[182:183], v[62:63]
	v_pk_mul_f32 v[126:127], v[180:181], v[64:65]
.LBB0_583:
	v_and_b32_e32 v51, 0xffff0000, v140
	v_and_b32_e32 v53, 0xffff0000, v141
	v_lshlrev_b32_e32 v50, 16, v140
	v_lshlrev_b32_e32 v52, 16, v141
	v_mul_f32_e32 v54, v53, v53
	v_and_b32_e32 v59, 0xffff0000, v139
	v_and_b32_e32 v58, 0xffff0000, v138
	v_lshlrev_b32_e32 v62, 16, v136
	v_and_b32_e32 v63, 0xffff0000, v136
	v_lshlrev_b32_e32 v64, 16, v137
	v_and_b32_e32 v65, 0xffff0000, v137
	v_lshlrev_b32_e32 v137, 16, v134
	v_mul_f32_e32 v136, v51, v51
	v_pk_fma_f32 v[54:55], v[52:53], v[52:53], v[54:55] op_sel_hi:[1,1,0]
	v_lshlrev_b32_e32 v57, 16, v139
	v_lshlrev_b32_e32 v56, 16, v138
	v_pk_mul_f32 v[60:61], v[58:59], v[58:59]
	v_pk_fma_f32 v[140:141], v[50:51], v[50:51], v[136:137] op_sel_hi:[1,1,0]
	v_pk_fma_f32 v[60:61], v[56:57], v[56:57], v[60:61]
	v_and_b32_e32 v139, 0xffff0000, v134
	v_mov_b32_e32 v136, v140
	v_mov_b32_e32 v142, v54
	v_mov_b32_e32 v143, v137
	v_mul_f32_e32 v138, v139, v139
	v_pk_add_f32 v[54:55], v[140:141], v[54:55]
	v_pk_mul_f32 v[140:141], v[136:137], v[142:143]
	v_pk_add_f32 v[60:61], v[60:61], v[60:61] op_sel:[0,1] op_sel_hi:[1,0]
	v_mov_b32_e32 v55, v141
	v_mov_b32_e32 v61, v138
	v_lshlrev_b32_e32 v134, 16, v135
	v_and_b32_e32 v135, 0xffff0000, v135
	v_pk_add_f32 v[54:55], v[54:55], v[60:61]
	v_mul_f32_e32 v60, v63, v63
	v_mul_f32_e32 v136, v65, v65
	v_mul_f32_e32 v144, v134, v134
	v_mul_f32_e32 v145, v135, v135
	v_pk_fma_f32 v[60:61], v[62:63], v[62:63], v[60:61] op_sel_hi:[1,1,0]
	v_pk_fma_f32 v[140:141], v[64:65], v[64:65], v[136:137] op_sel_hi:[1,1,0]
	v_mov_b32_e32 v61, v144
	v_mov_b32_e32 v141, v145
	v_pk_add_f32 v[60:61], v[60:61], v[140:141]
	s_add_i32 s22, s3, s24
	v_pk_add_f32 v[54:55], v[54:55], v[60:61]
	s_nop 0
	v_add_f32_e32 v54, v54, v55
	s_nop 1
	v_add_f32_dpp v54, v54, v54 quad_perm:[1,0,3,2] row_mask:0xf bank_mask:0xf bound_ctrl:1
	s_nop 1
	v_add_f32_dpp v54, v54, v54 quad_perm:[2,3,0,1] row_mask:0xf bank_mask:0xf bound_ctrl:1
	s_nop 1
	v_add_f32_dpp v54, v54, v54 row_half_mirror row_mask:0xf bank_mask:0xf bound_ctrl:1
	s_nop 1
	v_add_f32_dpp v54, v54, v54 row_mirror row_mask:0xf bank_mask:0xf bound_ctrl:1
	s_nop 0
	v_readlane_b32 s20, v54, 16
	v_readlane_b32 s21, v54, 48
	v_readlane_b32 s0, v54, 0
	v_readlane_b32 s1, v54, 32
	v_mov_b32_e32 v54, s20
	v_mov_b32_e32 v55, s21
	v_pk_add_f32 v[54:55], s[0:1], v[54:55]
	s_nop 0
	v_add_f32_e32 v54, v54, v55
	v_fmamk_f32 v54, v54, 0x3a800000, v157
	v_mul_f32_e32 v55, 0x4f800000, v54
	v_cmp_gt_f32_e32 vcc, s34, v54
	s_nop 1
	v_cndmask_b32_e32 v54, v54, v55, vcc
	v_sqrt_f32_e32 v55, v54
	s_nop 0
	v_add_u32_e32 v60, -1, v55
	v_fma_f32 v61, -v60, v55, v54
	v_cmp_ge_f32_e64 s[0:1], 0, v61
	v_add_u32_e32 v61, 1, v55
	s_nop 0
	v_cndmask_b32_e64 v60, v55, v60, s[0:1]
	v_fma_f32 v55, -v61, v55, v54
	v_cmp_lt_f32_e64 s[0:1], 0, v55
	s_nop 1
	v_cndmask_b32_e64 v55, v60, v61, s[0:1]
	v_mul_f32_e32 v60, 0x37800000, v55
	v_cndmask_b32_e32 v55, v55, v60, vcc
	v_cmp_class_f32_e32 vcc, v54, v158
	s_nop 1
	v_cndmask_b32_e32 v54, v55, v54, vcc
	v_div_scale_f32 v55, s[0:1], v54, v54, 1.0
	v_rcp_f32_e32 v60, v55
	s_nop 0
	v_fma_f32 v61, -v55, v60, 1.0
	v_fmac_f32_e32 v60, v61, v60
	v_div_scale_f32 v61, vcc, 1.0, v54, 1.0
	v_mul_f32_e32 v136, v61, v60
	v_fma_f32 v138, -v55, v136, v61
	v_fmac_f32_e32 v136, v138, v60
	v_fma_f32 v55, -v55, v136, v61
	v_div_fmas_f32 v55, v55, v60, v136
	v_div_fixup_f32 v54, v55, v54, 1.0
	v_pk_mul_f32 v[50:51], v[54:55], v[50:51] op_sel_hi:[0,1]
	v_pk_mul_f32 v[52:53], v[54:55], v[52:53] op_sel_hi:[0,1]
	v_pk_fma_f32 v[48:49], v[124:125], v[52:53], v[48:49]
	v_pk_fma_f32 v[46:47], v[128:129], v[50:51], v[46:47]
	v_cvt_pk_bf16_f32 v51, v48, v49
	v_cvt_pk_bf16_f32 v50, v46, v47
	v_lshl_add_u64 v[52:53], v[90:91], 0, s[18:19]
	global_store_dwordx2 v[52:53], v[50:51], off nt
	v_mov_b32_e32 v50, v56
	v_mov_b32_e32 v51, v58
	v_mov_b32_e32 v58, v57
	v_pk_mul_f32 v[50:51], v[54:55], v[50:51] op_sel_hi:[0,1]
	v_pk_mul_f32 v[56:57], v[54:55], v[58:59] op_sel_hi:[0,1]
	v_pk_fma_f32 v[44:45], v[114:115], v[56:57], v[44:45]
	v_pk_fma_f32 v[42:43], v[120:121], v[50:51], v[42:43]
	v_cvt_pk_bf16_f32 v51, v44, v45
	v_cvt_pk_bf16_f32 v50, v42, v43
	global_store_dwordx2 v[52:53], v[50:51], off offset:512 nt
	v_pk_mul_f32 v[50:51], v[54:55], v[62:63] op_sel_hi:[0,1]
	v_mov_b32_e32 v138, v137
	v_pk_mul_f32 v[56:57], v[54:55], v[64:65] op_sel_hi:[0,1]
	v_pk_fma_f32 v[38:39], v[118:119], v[50:51], v[38:39]
	v_pk_mul_f32 v[50:51], v[138:139], v[54:55] op_sel_hi:[1,0]
	v_pk_mul_f32 v[54:55], v[134:135], v[54:55] op_sel_hi:[1,0]
	v_pk_fma_f32 v[34:35], v[132:133], v[50:51], v[34:35]
	v_pk_fma_f32 v[36:37], v[130:131], v[54:55], v[36:37]
	v_pk_mul_f32 v[50:51], v[48:49], v[48:49]
	v_pk_mul_f32 v[54:55], v[46:47], v[46:47]
	v_pk_fma_f32 v[40:41], v[116:117], v[56:57], v[40:41]
	v_pk_mov_b32 v[56:57], v[54:55], v[50:51] op_sel:[1,0]
	v_mov_b32_e32 v55, v51
	v_pk_add_f32 v[50:51], v[56:57], v[54:55]
	v_pk_mul_f32 v[54:55], v[44:45], v[44:45]
	v_pk_add_f32 v[50:51], v[50:51], v[50:51] op_sel_hi:[0,1]
	v_pk_mul_f32 v[56:57], v[42:43], v[42:43]
	v_mul_f32_e32 v50, v38, v38
	v_pk_mov_b32 v[58:59], v[56:57], v[54:55] op_sel:[1,0]
	v_mov_b32_e32 v57, v55
	v_pk_add_f32 v[54:55], v[58:59], v[56:57]
	v_pk_fma_f32 v[56:57], v[38:39], v[38:39], v[50:51] op_sel_hi:[1,1,0]
	v_mul_f32_e32 v50, v40, v40
	v_pk_add_f32 v[54:55], v[54:55], v[54:55] op_sel_hi:[0,1]
	v_pk_fma_f32 v[58:59], v[40:41], v[40:41], v[50:51] op_sel_hi:[1,1,0]
	v_mul_f32_e32 v56, v34, v34
	v_mul_f32_e32 v58, v35, v35
	v_mul_f32_e32 v50, v36, v36
	v_mul_f32_e32 v54, v37, v37
	v_pk_add_f32 v[56:57], v[56:57], v[58:59]
	v_pk_add_f32 v[50:51], v[50:51], v[54:55]
	s_nop 0
	v_pk_add_f32 v[50:51], v[56:57], v[50:51]
	s_nop 0
	v_add_f32_e32 v50, v50, v51
	s_nop 1
	v_add_f32_dpp v50, v50, v50 quad_perm:[1,0,3,2] row_mask:0xf bank_mask:0xf bound_ctrl:1
	s_nop 1
	v_add_f32_dpp v50, v50, v50 quad_perm:[2,3,0,1] row_mask:0xf bank_mask:0xf bound_ctrl:1
	s_nop 1
	v_add_f32_dpp v50, v50, v50 row_half_mirror row_mask:0xf bank_mask:0xf bound_ctrl:1
	s_nop 1
	v_add_f32_dpp v50, v50, v50 row_mirror row_mask:0xf bank_mask:0xf bound_ctrl:1
	s_nop 0
	v_readlane_b32 s20, v50, 16
	v_readlane_b32 s21, v50, 48
	v_readlane_b32 s0, v50, 0
	v_readlane_b32 s1, v50, 32
	v_mov_b32_e32 v50, s20
	v_mov_b32_e32 v51, s21
	v_pk_add_f32 v[50:51], s[0:1], v[50:51]
	s_nop 0
	v_add_f32_e32 v50, v50, v51
	v_fmamk_f32 v50, v50, 0x3a800000, v157
	v_mul_f32_e32 v51, 0x4f800000, v50
	v_cmp_gt_f32_e32 vcc, s34, v50
	s_nop 1
	v_cndmask_b32_e32 v54, v50, v51, vcc
	v_sqrt_f32_e32 v55, v54
	v_cvt_pk_bf16_f32 v50, v38, v39
	v_cvt_pk_bf16_f32 v51, v40, v41
	global_store_dwordx2 v[52:53], v[50:51], off offset:1024 nt
	v_add_u32_e32 v50, -1, v55
	v_fma_f32 v51, -v50, v55, v54
	v_cmp_ge_f32_e64 s[0:1], 0, v51
	v_add_u32_e32 v51, 1, v55
	s_nop 0
	v_cndmask_b32_e64 v50, v55, v50, s[0:1]
	v_fma_f32 v55, -v51, v55, v54
	v_cmp_lt_f32_e64 s[0:1], 0, v55
	s_nop 1
	v_cndmask_b32_e64 v50, v50, v51, s[0:1]
	v_mul_f32_e32 v51, 0x37800000, v50
	v_cndmask_b32_e32 v50, v50, v51, vcc
	v_cmp_class_f32_e32 vcc, v54, v158
	v_cvt_pk_bf16_f32 v51, v36, v37
	s_nop 0
	v_cndmask_b32_e32 v54, v50, v54, vcc
	v_div_scale_f32 v55, s[0:1], v54, v54, 1.0
	v_rcp_f32_e32 v56, v55
	v_cvt_pk_bf16_f32 v50, v34, v35
	global_store_dwordx2 v[52:53], v[50:51], off offset:1536 nt
	s_ashr_i32 s0, s22, 31
	v_fma_f32 v50, -v55, v56, 1.0
	v_fmac_f32_e32 v56, v50, v56
	v_div_scale_f32 v50, vcc, 1.0, v54, 1.0
	v_mul_f32_e32 v51, v50, v56
	v_fma_f32 v52, -v55, v51, v50
	v_fmac_f32_e32 v51, v52, v56
	v_fma_f32 v50, -v55, v51, v50
	v_div_fmas_f32 v50, v50, v56, v51
	v_div_fixup_f32 v50, v50, v54, 1.0
	s_lshr_b32 s0, s0, 18
	v_pk_mul_f32 v[46:47], v[46:47], v[50:51] op_sel_hi:[1,0]
	v_pk_mul_f32 v[48:49], v[48:49], v[50:51] op_sel_hi:[1,0]
	v_pk_mul_f32 v[42:43], v[42:43], v[50:51] op_sel_hi:[1,0]
	v_pk_mul_f32 v[44:45], v[44:45], v[50:51] op_sel_hi:[1,0]
	v_pk_mul_f32 v[38:39], v[38:39], v[50:51] op_sel_hi:[1,0]
	v_pk_mul_f32 v[40:41], v[40:41], v[50:51] op_sel_hi:[1,0]
	v_pk_mul_f32 v[34:35], v[34:35], v[50:51] op_sel_hi:[1,0]
	v_pk_mul_f32 v[36:37], v[36:37], v[50:51] op_sel_hi:[1,0]
	s_add_i32 s0, s22, s0
	s_waitcnt vmcnt(7)
	v_pk_fma_f32 v[48:49], v[110:111], v[48:49], v[20:21]
	v_pk_fma_f32 v[46:47], v[112:113], v[46:47], v[18:19]
	s_waitcnt vmcnt(6)
	v_pk_fma_f32 v[44:45], v[104:105], v[44:45], v[32:33]
	v_pk_fma_f32 v[42:43], v[108:109], v[42:43], v[30:31]
	s_waitcnt vmcnt(5)
	v_pk_fma_f32 v[40:41], v[102:103], v[40:41], v[24:25]
	v_pk_fma_f32 v[38:39], v[106:107], v[38:39], v[22:23]
	s_waitcnt vmcnt(4)
	v_pk_fma_f32 v[36:37], v[122:123], v[36:37], v[28:29]
	v_pk_fma_f32 v[34:35], v[126:127], v[34:35], v[26:27]
	s_ashr_i32 s0, s0, 14
	v_cvt_pk_bf16_f32 v46, v46, v47
	v_cvt_pk_bf16_f32 v47, v48, v49
	v_lshl_add_u64 v[48:49], v[92:93], 0, s[18:19]
	v_cvt_pk_bf16_f32 v42, v42, v43
	v_cvt_pk_bf16_f32 v43, v44, v45
	v_cvt_pk_bf16_f32 v38, v38, v39
	v_cvt_pk_bf16_f32 v39, v40, v41
	v_cvt_pk_bf16_f32 v34, v34, v35
	v_cvt_pk_bf16_f32 v35, v36, v37
	s_cmp_eq_u32 s0, s37
	global_store_dwordx2 v[48:49], v[46:47], off nt
	global_store_dwordx2 v[48:49], v[42:43], off offset:512 nt
	global_store_dwordx2 v[48:49], v[38:39], off offset:1024 nt
	global_store_dwordx2 v[48:49], v[34:35], off offset:1536 nt
	s_cbranch_scc1 .LBB0_578
	s_mulk_i32 s0, 0xc00
	s_ashr_i32 s1, s0, 31
	s_lshl_b64 s[0:1], s[0:1], 2
	s_add_u32 s18, s94, s0
	s_addc_u32 s19, s95, s1
	s_add_u32 s20, s18, 0x2000
	s_addc_u32 s21, s19, 0
	global_load_dwordx4 v[34:37], v1, s[20:21]
	global_load_dwordx4 v[38:41], v[68:69], off
	global_load_dwordx4 v[42:45], v154, s[20:21]
	global_load_dwordx4 v[46:49], v[72:73], off
	global_load_dwordx4 v[50:53], v155, s[20:21]
	global_load_dwordx4 v[54:57], v[76:77], off
	global_load_dwordx4 v[58:61], v156, s[20:21]
	global_load_dwordx4 v[62:65], v[80:81], off
	s_add_u32 s0, s28, s0
	s_addc_u32 s1, s29, s1
	s_add_u32 s18, s0, 0x1000
	s_addc_u32 s19, s1, 0
	global_load_dwordx4 v[102:105], v1, s[18:19]
	global_load_dwordx4 v[106:109], v154, s[18:19]
	global_load_dwordx4 v[110:113], v155, s[18:19]
	global_load_dwordx4 v[134:137], v156, s[18:19]
	global_load_dwordx4 v[138:141], v[70:71], off
	global_load_dwordx4 v[142:145], v[74:75], off
	global_load_dwordx4 v[146:149], v[78:79], off
	global_load_dwordx4 v[150:153], v[82:83], off
	global_load_dwordx4 v[18:21], v1, s[0:1]
	global_load_dwordx4 v[30:33], v1, s[0:1] offset:1024
	global_load_dwordx4 v[22:25], v1, s[0:1] offset:2048
	global_load_dwordx4 v[26:29], v1, s[0:1] offset:3072
	s_waitcnt vmcnt(18)
	v_pk_mul_f32 v[124:125], v[36:37], v[40:41]
	v_pk_mul_f32 v[128:129], v[34:35], v[38:39]
	s_waitcnt vmcnt(16)
	v_pk_mul_f32 v[114:115], v[44:45], v[48:49]
	v_pk_mul_f32 v[120:121], v[42:43], v[46:47]
	s_waitcnt vmcnt(11)
	v_pk_add_f32 v[34:35], v[104:105], 1.0 op_sel_hi:[1,0]
	v_pk_add_f32 v[36:37], v[102:103], 1.0 op_sel_hi:[1,0]
	s_waitcnt vmcnt(10)
	v_pk_add_f32 v[38:39], v[108:109], 1.0 op_sel_hi:[1,0]
	v_pk_add_f32 v[40:41], v[106:107], 1.0 op_sel_hi:[1,0]
	s_waitcnt vmcnt(9)
	v_pk_add_f32 v[42:43], v[112:113], 1.0 op_sel_hi:[1,0]
	v_pk_add_f32 v[44:45], v[110:111], 1.0 op_sel_hi:[1,0]
	s_waitcnt vmcnt(8)
	v_pk_add_f32 v[46:47], v[136:137], 1.0 op_sel_hi:[1,0]
	v_pk_add_f32 v[48:49], v[134:135], 1.0 op_sel_hi:[1,0]
	v_pk_mul_f32 v[116:117], v[52:53], v[56:57]
	v_pk_mul_f32 v[118:119], v[50:51], v[54:55]
	v_pk_mul_f32 v[130:131], v[60:61], v[64:65]
	v_pk_mul_f32 v[132:133], v[58:59], v[62:63]
	s_waitcnt vmcnt(7)
	v_pk_mul_f32 v[110:111], v[140:141], v[34:35]
	v_pk_mul_f32 v[112:113], v[138:139], v[36:37]
	s_waitcnt vmcnt(6)
	v_pk_mul_f32 v[104:105], v[144:145], v[38:39]
	v_pk_mul_f32 v[108:109], v[142:143], v[40:41]
	s_waitcnt vmcnt(5)
	v_pk_mul_f32 v[102:103], v[148:149], v[42:43]
	v_pk_mul_f32 v[106:107], v[146:147], v[44:45]
	s_waitcnt vmcnt(4)
	v_pk_mul_f32 v[122:123], v[152:153], v[46:47]
	v_pk_mul_f32 v[126:127], v[150:151], v[48:49]
	s_branch .LBB0_578

.LBB0_788:
	v_lshlrev_b32_e32 v98, 16, v54
	v_and_b32_e32 v99, 0xffff0000, v54
	v_lshlrev_b32_e32 v54, 16, v55
	v_and_b32_e32 v55, 0xffff0000, v55
	v_lshlrev_b32_e32 v96, 16, v46
	v_and_b32_e32 v97, 0xffff0000, v46
	v_mul_f32_e32 v46, v55, v55
	v_pk_fma_f32 v[100:101], v[54:55], v[54:55], v[46:47] op_sel_hi:[1,1,0]
	v_lshlrev_b32_e32 v103, 16, v53
	v_lshlrev_b32_e32 v102, 16, v52
	v_and_b32_e32 v53, 0xffff0000, v53
	v_and_b32_e32 v52, 0xffff0000, v52
	v_mul_f32_e32 v46, v99, v99
	v_pk_mul_f32 v[104:105], v[52:53], v[52:53]
	v_lshlrev_b32_e32 v109, 16, v48
	v_pk_fma_f32 v[112:113], v[98:99], v[98:99], v[46:47] op_sel_hi:[1,1,0]
	v_pk_fma_f32 v[104:105], v[102:103], v[102:103], v[104:105]
	v_and_b32_e32 v111, 0xffff0000, v48
	v_mov_b32_e32 v108, v112
	v_mov_b32_e32 v114, v100
	v_mov_b32_e32 v115, v109
	v_and_b32_e32 v107, 0xffff0000, v50
	v_mul_f32_e32 v110, v111, v111
	v_pk_add_f32 v[100:101], v[112:113], v[100:101]
	v_pk_mul_f32 v[112:113], v[108:109], v[114:115]
	v_pk_add_f32 v[104:105], v[104:105], v[104:105] op_sel:[0,1] op_sel_hi:[1,0]
	v_lshlrev_b32_e32 v106, 16, v50
	v_lshlrev_b32_e32 v50, 16, v51
	v_and_b32_e32 v51, 0xffff0000, v51
	v_mov_b32_e32 v101, v113
	v_mov_b32_e32 v105, v110
	v_mul_f32_e32 v46, v107, v107
	v_lshlrev_b32_e32 v48, 16, v49
	v_and_b32_e32 v49, 0xffff0000, v49
	v_pk_add_f32 v[100:101], v[100:101], v[104:105]
	v_pk_fma_f32 v[104:105], v[106:107], v[106:107], v[46:47] op_sel_hi:[1,1,0]
	v_mul_f32_e32 v46, v51, v51
	v_mul_f32_e32 v116, v48, v48
	v_mul_f32_e32 v117, v49, v49
	v_pk_fma_f32 v[112:113], v[50:51], v[50:51], v[46:47] op_sel_hi:[1,1,0]
	v_mov_b32_e32 v105, v116
	v_mov_b32_e32 v113, v117
	v_pk_add_f32 v[104:105], v[104:105], v[112:113]
	v_lshlrev_b32_e32 v72, 16, v58
	v_pk_add_f32 v[100:101], v[100:101], v[104:105]
	v_and_b32_e32 v73, 0xffff0000, v58
	v_add_f32_e32 v46, v100, v101
	v_lshlrev_b32_e32 v58, 16, v59
	v_and_b32_e32 v59, 0xffff0000, v59
	v_add_f32_dpp v46, v46, v46 quad_perm:[1,0,3,2] row_mask:0xf bank_mask:0xf bound_ctrl:1
	v_lshlrev_b32_e32 v94, 16, v56
	v_and_b32_e32 v95, 0xffff0000, v56
	v_add_f32_dpp v46, v46, v46 quad_perm:[2,3,0,1] row_mask:0xf bank_mask:0xf bound_ctrl:1
	v_lshlrev_b32_e32 v56, 16, v57
	v_and_b32_e32 v57, 0xffff0000, v57
	v_add_f32_dpp v46, v46, v46 row_half_mirror row_mask:0xf bank_mask:0xf bound_ctrl:1
	v_lshl_add_u64 v[40:41], v[40:41], 0, s[4:5]
	s_nop 0
	v_add_f32_dpp v46, v46, v46 row_mirror row_mask:0xf bank_mask:0xf bound_ctrl:1
	s_nop 0
	v_readlane_b32 s8, v46, 16
	v_readlane_b32 s9, v46, 48
	v_readlane_b32 s0, v46, 0
	v_readlane_b32 s1, v46, 32
	v_mov_b32_e32 v100, s8
	v_mov_b32_e32 v101, s9
	v_pk_add_f32 v[100:101], s[0:1], v[100:101]
	s_nop 0
	v_add_f32_e32 v46, v100, v101
	v_fmamk_f32 v46, v46, 0x3a800000, v131
	v_mul_f32_e32 v100, 0x4f800000, v46
	v_cmp_gt_f32_e32 vcc, s24, v46
	s_nop 1
	v_cndmask_b32_e32 v101, v46, v100, vcc
	v_sqrt_f32_e32 v104, v101
	v_lshlrev_b32_e32 v46, 16, v47
	v_and_b32_e32 v47, 0xffff0000, v47
	v_lshlrev_b32_e32 v100, 16, v44
	v_add_u32_e32 v105, -1, v104
	v_fma_f32 v108, -v105, v104, v101
	v_cmp_ge_f32_e64 s[0:1], 0, v108
	v_add_u32_e32 v108, 1, v104
	s_nop 0
	v_cndmask_b32_e64 v105, v104, v105, s[0:1]
	v_fma_f32 v104, -v108, v104, v101
	v_cmp_lt_f32_e64 s[0:1], 0, v104
	s_nop 1
	v_cndmask_b32_e64 v104, v105, v108, s[0:1]
	v_mul_f32_e32 v105, 0x37800000, v104
	v_cndmask_b32_e32 v104, v104, v105, vcc
	v_cmp_class_f32_e32 vcc, v101, v132
	s_nop 1
	v_cndmask_b32_e32 v104, v104, v101, vcc
	v_div_scale_f32 v105, s[0:1], v104, v104, 1.0
	v_rcp_f32_e32 v108, v105
	v_and_b32_e32 v101, 0xffff0000, v44
	v_lshlrev_b32_e32 v44, 16, v45
	v_and_b32_e32 v45, 0xffff0000, v45
	v_fma_f32 v110, -v105, v108, 1.0
	v_fmac_f32_e32 v108, v110, v108
	v_div_scale_f32 v110, vcc, 1.0, v104, 1.0
	v_mul_f32_e32 v112, v110, v108
	v_fma_f32 v113, -v105, v112, v110
	v_fmac_f32_e32 v112, v113, v108
	v_fma_f32 v105, -v105, v112, v110
	v_div_fmas_f32 v105, v105, v108, v112
	v_div_fixup_f32 v104, v105, v104, 1.0
	v_pk_mul_f32 v[98:99], v[104:105], v[98:99] op_sel_hi:[0,1]
	v_pk_mul_f32 v[54:55], v[104:105], v[54:55] op_sel_hi:[0,1]
	v_pk_fma_f32 v[54:55], v[74:75], v[54:55], v[58:59]
	v_pk_fma_f32 v[58:59], v[76:77], v[98:99], v[72:73]
	v_cvt_pk_bf16_f32 v73, v54, v55
	v_cvt_pk_bf16_f32 v72, v58, v59
	global_store_dwordx2 v[42:43], v[72:73], off nt
	v_mov_b32_e32 v72, v102
	v_mov_b32_e32 v73, v52
	v_mov_b32_e32 v52, v103
	v_pk_mul_f32 v[72:73], v[104:105], v[72:73] op_sel_hi:[0,1]
	v_pk_mul_f32 v[52:53], v[104:105], v[52:53] op_sel_hi:[0,1]
	v_pk_fma_f32 v[52:53], v[84:85], v[52:53], v[56:57]
	v_pk_fma_f32 v[56:57], v[86:87], v[72:73], v[94:95]
	v_cvt_pk_bf16_f32 v73, v52, v53
	v_cvt_pk_bf16_f32 v72, v56, v57
	global_store_dwordx2 v[42:43], v[72:73], off offset:512 nt
	v_pk_mul_f32 v[72:73], v[104:105], v[106:107] op_sel_hi:[0,1]
	v_pk_mul_f32 v[50:51], v[104:105], v[50:51] op_sel_hi:[0,1]
	v_mov_b32_e32 v110, v109
	v_pk_fma_f32 v[46:47], v[78:79], v[50:51], v[46:47]
	v_pk_fma_f32 v[50:51], v[80:81], v[72:73], v[96:97]
	v_pk_mul_f32 v[72:73], v[110:111], v[104:105] op_sel_hi:[1,0]
	v_pk_mul_f32 v[48:49], v[48:49], v[104:105] op_sel_hi:[1,0]
	v_pk_mul_f32 v[74:75], v[58:59], v[58:59]
	v_pk_fma_f32 v[44:45], v[90:91], v[48:49], v[44:45]
	v_pk_fma_f32 v[48:49], v[92:93], v[72:73], v[100:101]
	v_pk_mul_f32 v[72:73], v[54:55], v[54:55]
	s_nop 0
	v_pk_mov_b32 v[76:77], v[74:75], v[72:73] op_sel:[1,0]
	v_mov_b32_e32 v75, v73
	v_pk_add_f32 v[72:73], v[76:77], v[74:75]
	v_pk_mul_f32 v[74:75], v[52:53], v[52:53]
	v_pk_add_f32 v[72:73], v[72:73], v[72:73] op_sel_hi:[0,1]
	v_pk_mul_f32 v[76:77], v[56:57], v[56:57]
	v_mul_f32_e32 v72, v50, v50
	v_pk_mov_b32 v[78:79], v[76:77], v[74:75] op_sel:[1,0]
	v_mov_b32_e32 v77, v75
	v_pk_add_f32 v[74:75], v[78:79], v[76:77]
	v_pk_fma_f32 v[76:77], v[50:51], v[50:51], v[72:73] op_sel_hi:[1,1,0]
	v_mul_f32_e32 v72, v46, v46
	v_pk_add_f32 v[74:75], v[74:75], v[74:75] op_sel_hi:[0,1]
	v_pk_fma_f32 v[78:79], v[46:47], v[46:47], v[72:73] op_sel_hi:[1,1,0]
	v_mul_f32_e32 v76, v48, v48
	v_mul_f32_e32 v78, v49, v49
	v_mul_f32_e32 v72, v44, v44
	v_mul_f32_e32 v74, v45, v45
	v_pk_add_f32 v[76:77], v[76:77], v[78:79]
	v_pk_add_f32 v[72:73], v[72:73], v[74:75]
	s_nop 0
	v_pk_add_f32 v[72:73], v[76:77], v[72:73]
	s_nop 0
	v_add_f32_e32 v72, v72, v73
	s_nop 1
	v_add_f32_dpp v72, v72, v72 quad_perm:[1,0,3,2] row_mask:0xf bank_mask:0xf bound_ctrl:1
	s_nop 1
	v_add_f32_dpp v72, v72, v72 quad_perm:[2,3,0,1] row_mask:0xf bank_mask:0xf bound_ctrl:1
	s_nop 1
	v_add_f32_dpp v72, v72, v72 row_half_mirror row_mask:0xf bank_mask:0xf bound_ctrl:1
	s_nop 1
	v_add_f32_dpp v72, v72, v72 row_mirror row_mask:0xf bank_mask:0xf bound_ctrl:1
	s_nop 0
	v_readlane_b32 s8, v72, 16
	v_readlane_b32 s9, v72, 48
	v_readlane_b32 s0, v72, 0
	v_readlane_b32 s1, v72, 32
	v_mov_b32_e32 v72, s8
	v_mov_b32_e32 v73, s9
	v_pk_add_f32 v[72:73], s[0:1], v[72:73]
	s_nop 0
	v_add_f32_e32 v72, v72, v73
	v_fmamk_f32 v72, v72, 0x3a800000, v131
	v_mul_f32_e32 v73, 0x4f800000, v72
	v_cmp_gt_f32_e32 vcc, s24, v72
	s_nop 1
	v_cndmask_b32_e32 v74, v72, v73, vcc
	v_sqrt_f32_e32 v75, v74
	v_cvt_pk_bf16_f32 v72, v50, v51
	v_cvt_pk_bf16_f32 v73, v46, v47
	global_store_dwordx2 v[42:43], v[72:73], off offset:1024 nt
	v_add_u32_e32 v72, -1, v75
	v_fma_f32 v73, -v72, v75, v74
	v_cmp_ge_f32_e64 s[0:1], 0, v73
	v_add_u32_e32 v73, 1, v75
	s_nop 0
	v_cndmask_b32_e64 v72, v75, v72, s[0:1]
	v_fma_f32 v75, -v73, v75, v74
	v_cmp_lt_f32_e64 s[0:1], 0, v75
	s_nop 1
	v_cndmask_b32_e64 v72, v72, v73, s[0:1]
	v_mul_f32_e32 v73, 0x37800000, v72
	v_cndmask_b32_e32 v72, v72, v73, vcc
	v_cmp_class_f32_e32 vcc, v74, v132
	v_cvt_pk_bf16_f32 v73, v44, v45
	s_nop 0
	v_cndmask_b32_e32 v74, v72, v74, vcc
	v_div_scale_f32 v75, s[0:1], v74, v74, 1.0
	v_rcp_f32_e32 v76, v75
	v_cvt_pk_bf16_f32 v72, v48, v49
	global_store_dwordx2 v[42:43], v[72:73], off offset:1536 nt
	s_add_i32 s0, s3, s12
	v_fma_f32 v42, -v75, v76, 1.0
	v_fmac_f32_e32 v76, v42, v76
	v_div_scale_f32 v42, vcc, 1.0, v74, 1.0
	v_mul_f32_e32 v43, v42, v76
	v_fma_f32 v72, -v75, v43, v42
	v_fmac_f32_e32 v43, v72, v76
	v_fma_f32 v42, -v75, v43, v42
	v_div_fmas_f32 v42, v42, v76, v43
	v_div_fixup_f32 v42, v42, v74, 1.0
	v_pk_mul_f32 v[58:59], v[58:59], v[42:43] op_sel_hi:[1,0]
	v_pk_mul_f32 v[54:55], v[54:55], v[42:43] op_sel_hi:[1,0]
	s_waitcnt vmcnt(7)
	v_pk_fma_f32 v[2:3], v[70:71], v[58:59], v[2:3]
	v_pk_fma_f32 v[4:5], v[66:67], v[54:55], v[4:5]
	v_cvt_pk_bf16_f32 v2, v2, v3
	v_cvt_pk_bf16_f32 v3, v4, v5
	v_lshl_add_u64 v[4:5], v[38:39], 0, s[6:7]
	global_store_dwordx2 v[4:5], v[2:3], off nt
	v_pk_mul_f32 v[2:3], v[56:57], v[42:43] op_sel_hi:[1,0]
	v_pk_mul_f32 v[52:53], v[52:53], v[42:43] op_sel_hi:[1,0]
	s_waitcnt vmcnt(7)
	v_pk_fma_f32 v[2:3], v[68:69], v[2:3], v[14:15]
	v_pk_fma_f32 v[16:17], v[62:63], v[52:53], v[16:17]
	v_cvt_pk_bf16_f32 v2, v2, v3
	v_cvt_pk_bf16_f32 v3, v16, v17
	global_store_dwordx2 v[4:5], v[2:3], off offset:512 nt
	v_pk_mul_f32 v[2:3], v[50:51], v[42:43] op_sel_hi:[1,0]
	v_pk_mul_f32 v[14:15], v[46:47], v[42:43] op_sel_hi:[1,0]
	s_waitcnt vmcnt(7)
	v_pk_fma_f32 v[2:3], v[64:65], v[2:3], v[6:7]
	v_pk_fma_f32 v[8:9], v[60:61], v[14:15], v[8:9]
	v_cvt_pk_bf16_f32 v2, v2, v3
	v_cvt_pk_bf16_f32 v3, v8, v9
	global_store_dwordx2 v[4:5], v[2:3], off offset:1024 nt
	v_pk_mul_f32 v[2:3], v[48:49], v[42:43] op_sel_hi:[1,0]
	v_pk_mul_f32 v[6:7], v[44:45], v[42:43] op_sel_hi:[1,0]
	s_waitcnt vmcnt(7)
	v_pk_fma_f32 v[2:3], v[88:89], v[2:3], v[10:11]
	v_pk_fma_f32 v[6:7], v[82:83], v[6:7], v[12:13]
	v_cvt_pk_bf16_f32 v2, v2, v3
	v_cvt_pk_bf16_f32 v3, v6, v7
	s_cmp_lt_i32 s0, 0x8000
	global_store_dwordx2 v[4:5], v[2:3], off offset:1536 nt
	s_cbranch_scc0 .LBB0_795
.LBB0_789:
	s_ashr_i32 s1, s0, 31
	s_lshr_b32 s1, s1, 18
	s_add_i32 s10, s3, s0
	s_add_i32 s6, s22, s0
	s_add_i32 s14, s23, s0
	s_add_i32 s0, s0, s1
	s_ashr_i32 s26, s0, 14
	s_mul_i32 s0, s26, 0xc00
	s_ashr_i32 s11, s10, 31
	s_ashr_i32 s7, s6, 31
	s_ashr_i32 s15, s14, 31
	s_ashr_i32 s1, s0, 31
	s_lshl_b64 s[12:13], s[10:11], 11
	s_lshl_b64 s[8:9], s[6:7], 11
	s_lshl_b64 s[6:7], s[14:15], 11
	s_lshl_b64 s[0:1], s[0:1], 2
	s_add_u32 s14, s18, s0
	s_addc_u32 s15, s19, s1
	s_add_u32 s14, s14, 0x2000
	s_addc_u32 s15, s15, 0
	s_add_u32 s0, s20, s0
	global_load_dwordx2 v[2:3], v[40:41], off offset:-1536
	global_load_dwordx2 v[4:5], v[40:41], off offset:-1024
	global_load_dwordx2 v[42:43], v[40:41], off offset:-512
	global_load_dwordx2 v[44:45], v[40:41], off
	global_load_dwordx4 v[6:9], v[18:19], off
	global_load_dwordx4 v[10:13], v1, s[14:15]
	s_addc_u32 s1, s21, s1
	s_add_u32 s16, s0, 0x1000
	s_addc_u32 s17, s1, 0
	global_load_dwordx4 v[14:17], v1, s[16:17]
	global_load_dwordx4 v[60:63], v[20:21], off
	global_load_dwordx4 v[78:81], v[22:23], off
	global_load_dwordx4 v[82:85], v128, s[14:15]
	global_load_dwordx4 v[88:91], v128, s[16:17]
	global_load_dwordx4 v[134:137], v[24:25], off
	global_load_dwordx4 v[138:141], v[26:27], off
	global_load_dwordx4 v[142:145], v129, s[14:15]
	global_load_dwordx4 v[146:149], v129, s[16:17]
	global_load_dwordx4 v[150:153], v[28:29], off
	v_add_co_u32_e32 v46, vcc, 0xfc000000, v40
	v_lshl_add_u64 v[110:111], v[34:35], 0, s[12:13]
	s_nop 0
	v_addc_co_u32_e32 v47, vcc, -1, v41, vcc
	global_load_dwordx2 v[92:93], v[46:47], off offset:-1536
	global_load_dwordx2 v[166:167], v[46:47], off offset:-1024
	global_load_dwordx2 v[168:169], v[46:47], off offset:-512
	global_load_dwordx2 v[170:171], v[46:47], off
	v_lshl_add_u64 v[46:47], v[36:37], 0, s[12:13]
	v_lshl_add_u64 v[48:49], v[36:37], 0, s[8:9]
	v_lshl_add_u64 v[72:73], v[34:35], 0, s[8:9]
	global_load_dwordx2 v[126:127], v[110:111], off
	global_load_dwordx2 v[124:125], v[110:111], off offset:512
	global_load_dwordx2 v[114:115], v[110:111], off offset:1024
	global_load_dwordx2 v[112:113], v[110:111], off offset:1536
	global_load_dwordx2 v[122:123], v[46:47], off
	global_load_dwordx2 v[120:121], v[46:47], off offset:512
	global_load_dwordx2 v[118:119], v[46:47], off offset:1024
	global_load_dwordx2 v[116:117], v[46:47], off offset:1536
	global_load_dwordx2 v[106:107], v[72:73], off
	global_load_dwordx2 v[104:105], v[72:73], off offset:512
	global_load_dwordx2 v[96:97], v[72:73], off offset:1024
	global_load_dwordx2 v[94:95], v[72:73], off offset:1536
	global_load_dwordx2 v[108:109], v[48:49], off
	global_load_dwordx2 v[102:103], v[48:49], off offset:512
	global_load_dwordx2 v[100:101], v[48:49], off offset:1024
	global_load_dwordx2 v[98:99], v[48:49], off offset:1536
	s_waitcnt vmcnt(35)
	v_lshlrev_b32_e32 v172, 16, v2
	v_and_b32_e32 v173, 0xffff0000, v2
	v_lshlrev_b32_e32 v174, 16, v3
	v_and_b32_e32 v175, 0xffff0000, v3
	s_waitcnt vmcnt(33)
	v_lshlrev_b32_e32 v180, 16, v42
	s_waitcnt vmcnt(30)
	v_pk_mul_f32 v[74:75], v[12:13], v[8:9]
	v_pk_mul_f32 v[76:77], v[10:11], v[6:7]
	s_waitcnt vmcnt(29)
	v_pk_add_f32 v[6:7], v[16:17], 1.0 op_sel_hi:[1,0]
	v_pk_add_f32 v[8:9], v[14:15], 1.0 op_sel_hi:[1,0]
	v_and_b32_e32 v181, 0xffff0000, v42
	v_lshlrev_b32_e32 v182, 16, v43
	v_and_b32_e32 v183, 0xffff0000, v43
	v_lshl_add_u64 v[42:43], v[34:35], 0, s[6:7]
	v_lshl_add_u64 v[2:3], v[36:37], 0, s[6:7]
	s_waitcnt vmcnt(28)
	v_pk_mul_f32 v[66:67], v[62:63], v[6:7]
	v_pk_mul_f32 v[70:71], v[60:61], v[8:9]
	s_waitcnt vmcnt(25)
	v_pk_add_f32 v[6:7], v[90:91], 1.0 op_sel_hi:[1,0]
	v_pk_add_f32 v[8:9], v[88:89], 1.0 op_sel_hi:[1,0]
	v_lshlrev_b32_e32 v176, 16, v4
	v_and_b32_e32 v177, 0xffff0000, v4
	v_lshlrev_b32_e32 v178, 16, v5
	v_and_b32_e32 v179, 0xffff0000, v5
	v_lshlrev_b32_e32 v184, 16, v44
	v_and_b32_e32 v185, 0xffff0000, v44
	v_lshlrev_b32_e32 v186, 16, v45
	v_and_b32_e32 v187, 0xffff0000, v45
	global_load_dwordx2 v[58:59], v[42:43], off
	global_load_dwordx2 v[56:57], v[42:43], off offset:512
	global_load_dwordx2 v[46:47], v[42:43], off offset:1024
	global_load_dwordx2 v[44:45], v[42:43], off offset:1536
	global_load_dwordx2 v[54:55], v[2:3], off
	global_load_dwordx2 v[52:53], v[2:3], off offset:512
	global_load_dwordx2 v[50:51], v[2:3], off offset:1024
	global_load_dwordx2 v[48:49], v[2:3], off offset:1536
	s_nop 0
	global_load_dwordx4 v[2:5], v1, s[0:1]
	global_load_dwordx4 v[10:13], v1, s[0:1] offset:3072
	global_load_dwordx4 v[154:157], v130, s[14:15]
	global_load_dwordx4 v[158:161], v[30:31], off
	global_load_dwordx4 v[162:165], v130, s[16:17]
	s_waitcnt vmcnt(37)
	v_pk_mul_f32 v[62:63], v[136:137], v[6:7]
	v_pk_mul_f32 v[68:69], v[134:135], v[8:9]
	s_waitcnt vmcnt(34)
	v_pk_add_f32 v[6:7], v[148:149], 1.0 op_sel_hi:[1,0]
	v_pk_add_f32 v[8:9], v[146:147], 1.0 op_sel_hi:[1,0]
	s_waitcnt vmcnt(33)
	v_pk_mul_f32 v[60:61], v[152:153], v[6:7]
	v_pk_mul_f32 v[64:65], v[150:151], v[8:9]
	global_load_dwordx4 v[14:17], v1, s[0:1] offset:1024
	global_load_dwordx4 v[6:9], v1, s[0:1] offset:2048
	global_load_dwordx4 v[134:137], v[32:33], off
	v_pk_mul_f32 v[84:85], v[84:85], v[80:81]
	v_pk_mul_f32 v[86:87], v[82:83], v[78:79]
	v_pk_mul_f32 v[78:79], v[144:145], v[140:141]
	v_pk_mul_f32 v[80:81], v[142:143], v[138:139]
	s_waitcnt vmcnt(35)
	v_and_b32_e32 v139, 0xffff0000, v92
	v_and_b32_e32 v141, 0xffff0000, v93
	v_lshlrev_b32_e32 v138, 16, v92
	v_lshlrev_b32_e32 v140, 16, v93
	v_mul_f32_e32 v82, v141, v141
	s_waitcnt vmcnt(34)
	v_and_b32_e32 v145, 0xffff0000, v167
	v_and_b32_e32 v144, 0xffff0000, v166
	v_mul_f32_e32 v90, v139, v139
	v_pk_fma_f32 v[82:83], v[140:141], v[140:141], v[82:83] op_sel_hi:[1,1,0]
	v_lshlrev_b32_e32 v143, 16, v167
	v_lshlrev_b32_e32 v142, 16, v166
	v_pk_mul_f32 v[88:89], v[144:145], v[144:145]
	s_waitcnt vmcnt(32)
	v_lshlrev_b32_e32 v151, 16, v170
	v_pk_fma_f32 v[90:91], v[138:139], v[138:139], v[90:91] op_sel_hi:[1,1,0]
	v_pk_fma_f32 v[88:89], v[142:143], v[142:143], v[88:89]
	v_and_b32_e32 v153, 0xffff0000, v170
	v_mov_b32_e32 v150, v90
	v_mov_b32_e32 v92, v82
	v_mov_b32_e32 v93, v151
	v_mul_f32_e32 v133, v153, v153
	v_pk_add_f32 v[82:83], v[90:91], v[82:83]
	v_pk_mul_f32 v[90:91], v[150:151], v[92:93]
	v_pk_add_f32 v[88:89], v[88:89], v[88:89] op_sel:[0,1] op_sel_hi:[1,0]
	v_and_b32_e32 v147, 0xffff0000, v168
	v_and_b32_e32 v149, 0xffff0000, v169
	v_mov_b32_e32 v83, v91
	v_mov_b32_e32 v89, v133
	v_lshlrev_b32_e32 v146, 16, v168
	v_lshlrev_b32_e32 v148, 16, v169
	v_lshlrev_b32_e32 v166, 16, v171
	v_and_b32_e32 v167, 0xffff0000, v171
	v_pk_add_f32 v[82:83], v[82:83], v[88:89]
	v_mul_f32_e32 v88, v147, v147
	v_mul_f32_e32 v90, v149, v149
	v_mul_f32_e32 v152, v166, v166
	v_mul_f32_e32 v168, v167, v167
	v_pk_fma_f32 v[88:89], v[146:147], v[146:147], v[88:89] op_sel_hi:[1,1,0]
	v_pk_fma_f32 v[90:91], v[148:149], v[148:149], v[90:91] op_sel_hi:[1,1,0]
	v_mov_b32_e32 v89, v152
	v_mov_b32_e32 v91, v168
	v_pk_add_f32 v[88:89], v[88:89], v[90:91]
	s_waitcnt vmcnt(4)
	v_pk_mul_f32 v[92:93], v[154:155], v[158:159]
	v_pk_add_f32 v[82:83], v[82:83], v[88:89]
	v_pk_mul_f32 v[90:91], v[156:157], v[160:161]
	v_add_f32_e32 v82, v82, v83
	s_nop 1
	v_add_f32_dpp v82, v82, v82 quad_perm:[1,0,3,2] row_mask:0xf bank_mask:0xf bound_ctrl:1
	s_nop 1
	v_add_f32_dpp v82, v82, v82 quad_perm:[2,3,0,1] row_mask:0xf bank_mask:0xf bound_ctrl:1
	s_nop 1
	v_add_f32_dpp v82, v82, v82 row_half_mirror row_mask:0xf bank_mask:0xf bound_ctrl:1
	s_nop 1
	v_add_f32_dpp v82, v82, v82 row_mirror row_mask:0xf bank_mask:0xf bound_ctrl:1
	s_nop 0
	v_readlane_b32 s14, v82, 16
	v_readlane_b32 s15, v82, 48
	v_readlane_b32 s0, v82, 0
	v_readlane_b32 s1, v82, 32
	v_mov_b32_e32 v82, s14
	v_mov_b32_e32 v83, s15
	v_pk_add_f32 v[82:83], s[0:1], v[82:83]
	s_nop 0
	v_add_f32_e32 v82, v82, v83
	v_fmamk_f32 v82, v82, 0x3a800000, v131
	v_mul_f32_e32 v83, 0x4f800000, v82
	v_cmp_gt_f32_e32 vcc, s24, v82
	s_nop 1
	v_cndmask_b32_e32 v88, v82, v83, vcc
	v_sqrt_f32_e32 v89, v88
	s_waitcnt vmcnt(3)
	v_pk_add_f32 v[82:83], v[164:165], 1.0 op_sel_hi:[1,0]
	v_add_u32_e32 v133, -1, v89
	v_fma_f32 v150, -v133, v89, v88
	v_cmp_ge_f32_e64 s[0:1], 0, v150
	v_add_u32_e32 v150, 1, v89
	s_waitcnt vmcnt(0)
	v_pk_mul_f32 v[82:83], v[136:137], v[82:83]
	v_cndmask_b32_e64 v133, v89, v133, s[0:1]
	v_fma_f32 v89, -v150, v89, v88
	v_cmp_lt_f32_e64 s[0:1], 0, v89
	s_nop 1
	v_cndmask_b32_e64 v89, v133, v150, s[0:1]
	v_mul_f32_e32 v133, 0x37800000, v89
	v_cndmask_b32_e32 v89, v89, v133, vcc
	v_cmp_class_f32_e32 vcc, v88, v132
	s_nop 1
	v_cndmask_b32_e32 v133, v89, v88, vcc
	v_div_scale_f32 v150, s[0:1], v133, v133, 1.0
	v_rcp_f32_e32 v152, v150
	v_pk_add_f32 v[88:89], v[162:163], 1.0 op_sel_hi:[1,0]
	s_nop 0
	v_pk_mul_f32 v[88:89], v[134:135], v[88:89]
	v_fma_f32 v134, -v150, v152, 1.0
	v_fmac_f32_e32 v152, v134, v152
	v_div_scale_f32 v134, vcc, 1.0, v133, 1.0
	v_mul_f32_e32 v135, v134, v152
	v_fma_f32 v136, -v150, v135, v134
	v_fmac_f32_e32 v135, v136, v152
	v_fma_f32 v134, -v150, v135, v134
	v_div_fmas_f32 v134, v134, v152, v135
	v_div_fixup_f32 v134, v134, v133, 1.0
	v_pk_mul_f32 v[136:137], v[134:135], v[138:139] op_sel_hi:[0,1]
	v_pk_mul_f32 v[138:139], v[134:135], v[140:141] op_sel_hi:[0,1]
	v_pk_fma_f32 v[138:139], v[74:75], v[138:139], v[174:175]
	v_pk_fma_f32 v[136:137], v[76:77], v[136:137], v[172:173]
	v_cvt_pk_bf16_f32 v141, v138, v139
	v_cvt_pk_bf16_f32 v140, v136, v137
	global_store_dwordx2 v[40:41], v[140:141], off offset:-1536 nt
	v_mov_b32_e32 v140, v142
	v_mov_b32_e32 v141, v144
	v_mov_b32_e32 v144, v143
	v_pk_mul_f32 v[140:141], v[134:135], v[140:141] op_sel_hi:[0,1]
	v_pk_mul_f32 v[142:143], v[134:135], v[144:145] op_sel_hi:[0,1]
	v_pk_fma_f32 v[142:143], v[84:85], v[142:143], v[178:179]
	v_pk_fma_f32 v[140:141], v[86:87], v[140:141], v[176:177]
	v_cvt_pk_bf16_f32 v145, v142, v143
	v_cvt_pk_bf16_f32 v144, v140, v141
	v_mov_b32_e32 v152, v151
	global_store_dwordx2 v[40:41], v[144:145], off offset:-1024 nt
	v_pk_mul_f32 v[144:145], v[134:135], v[146:147] op_sel_hi:[0,1]
	v_pk_mul_f32 v[146:147], v[134:135], v[148:149] op_sel_hi:[0,1]
	v_pk_mul_f32 v[148:149], v[152:153], v[134:135] op_sel_hi:[1,0]
	v_pk_mul_f32 v[150:151], v[138:139], v[138:139]
	v_pk_mul_f32 v[152:153], v[136:137], v[136:137]
	v_pk_fma_f32 v[144:145], v[80:81], v[144:145], v[180:181]
	v_pk_mov_b32 v[154:155], v[152:153], v[150:151] op_sel:[1,0]
	v_mov_b32_e32 v153, v151
	v_pk_add_f32 v[150:151], v[154:155], v[152:153]
	v_pk_mul_f32 v[152:153], v[142:143], v[142:143]
	v_pk_add_f32 v[150:151], v[150:151], v[150:151] op_sel_hi:[0,1]
	v_pk_mul_f32 v[154:155], v[140:141], v[140:141]
	v_pk_fma_f32 v[146:147], v[78:79], v[146:147], v[182:183]
	v_pk_mov_b32 v[156:157], v[154:155], v[152:153] op_sel:[1,0]
	v_mov_b32_e32 v155, v153
	v_mul_f32_e32 v150, v144, v144
	v_pk_mul_f32 v[134:135], v[166:167], v[134:135] op_sel_hi:[1,0]
	v_pk_add_f32 v[152:153], v[156:157], v[154:155]
	v_pk_fma_f32 v[154:155], v[144:145], v[144:145], v[150:151] op_sel_hi:[1,1,0]
	v_mul_f32_e32 v150, v146, v146
	v_pk_fma_f32 v[134:135], v[90:91], v[134:135], v[186:187]
	v_pk_fma_f32 v[148:149], v[92:93], v[148:149], v[184:185]
	v_pk_add_f32 v[152:153], v[152:153], v[152:153] op_sel_hi:[0,1]
	v_pk_fma_f32 v[156:157], v[146:147], v[146:147], v[150:151] op_sel_hi:[1,1,0]
	v_mul_f32_e32 v154, v148, v148
	v_mul_f32_e32 v156, v149, v149
	v_mul_f32_e32 v150, v134, v134
	v_mul_f32_e32 v152, v135, v135
	v_pk_add_f32 v[154:155], v[154:155], v[156:157]
	v_pk_add_f32 v[150:151], v[150:151], v[152:153]
	s_nop 0
	v_pk_add_f32 v[150:151], v[154:155], v[150:151]
	s_nop 0
	v_add_f32_e32 v133, v150, v151
	s_nop 1
	v_add_f32_dpp v133, v133, v133 quad_perm:[1,0,3,2] row_mask:0xf bank_mask:0xf bound_ctrl:1
	s_nop 1
	v_add_f32_dpp v133, v133, v133 quad_perm:[2,3,0,1] row_mask:0xf bank_mask:0xf bound_ctrl:1
	s_nop 1
	v_add_f32_dpp v133, v133, v133 row_half_mirror row_mask:0xf bank_mask:0xf bound_ctrl:1
	s_nop 1
	v_add_f32_dpp v133, v133, v133 row_mirror row_mask:0xf bank_mask:0xf bound_ctrl:1
	s_nop 0
	v_readlane_b32 s14, v133, 16
	v_readlane_b32 s15, v133, 48
	v_readlane_b32 s0, v133, 0
	v_readlane_b32 s1, v133, 32
	v_mov_b32_e32 v150, s14
	v_mov_b32_e32 v151, s15
	v_pk_add_f32 v[150:151], s[0:1], v[150:151]
	s_nop 0
	v_add_f32_e32 v133, v150, v151
	v_fmamk_f32 v133, v133, 0x3a800000, v131
	v_mul_f32_e32 v150, 0x4f800000, v133
	v_cmp_gt_f32_e32 vcc, s24, v133
	v_cvt_pk_bf16_f32 v151, v146, v147
	s_nop 0
	v_cndmask_b32_e32 v133, v133, v150, vcc
	v_sqrt_f32_e32 v152, v133
	v_cvt_pk_bf16_f32 v150, v144, v145
	global_store_dwordx2 v[40:41], v[150:151], off offset:-512 nt
	v_add_u32_e32 v150, -1, v152
	v_fma_f32 v151, -v150, v152, v133
	v_cmp_ge_f32_e64 s[0:1], 0, v151
	v_add_u32_e32 v151, 1, v152
	s_nop 0
	v_cndmask_b32_e64 v150, v152, v150, s[0:1]
	v_fma_f32 v152, -v151, v152, v133
	v_cmp_lt_f32_e64 s[0:1], 0, v152
	s_nop 1
	v_cndmask_b32_e64 v150, v150, v151, s[0:1]
	v_mul_f32_e32 v151, 0x37800000, v150
	v_cndmask_b32_e32 v150, v150, v151, vcc
	v_cmp_class_f32_e32 vcc, v133, v132
	v_cvt_pk_bf16_f32 v151, v134, v135
	s_nop 0
	v_cndmask_b32_e32 v133, v150, v133, vcc
	v_div_scale_f32 v152, s[0:1], v133, v133, 1.0
	v_rcp_f32_e32 v153, v152
	v_cvt_pk_bf16_f32 v150, v148, v149
	global_store_dwordx2 v[40:41], v[150:151], off nt
	s_lshr_b32 s0, s11, 18
	v_fma_f32 v150, -v152, v153, 1.0
	v_fmac_f32_e32 v153, v150, v153
	v_div_scale_f32 v150, vcc, 1.0, v133, 1.0
	v_mul_f32_e32 v151, v150, v153
	v_fma_f32 v154, -v152, v151, v150
	v_fmac_f32_e32 v151, v154, v153
	v_fma_f32 v150, -v152, v151, v150
	v_div_fmas_f32 v150, v150, v153, v151
	v_div_fixup_f32 v150, v150, v133, 1.0
	v_pk_mul_f32 v[136:137], v[136:137], v[150:151] op_sel_hi:[1,0]
	v_pk_mul_f32 v[138:139], v[138:139], v[150:151] op_sel_hi:[1,0]
	v_pk_fma_f32 v[136:137], v[70:71], v[136:137], v[2:3]
	v_pk_fma_f32 v[138:139], v[66:67], v[138:139], v[4:5]
	v_cvt_pk_bf16_f32 v136, v136, v137
	v_cvt_pk_bf16_f32 v137, v138, v139
	v_add_co_u32_e32 v138, vcc, s25, v40
	v_pk_mul_f32 v[134:135], v[134:135], v[150:151] op_sel_hi:[1,0]
	s_nop 0
	v_addc_co_u32_e32 v139, vcc, -1, v41, vcc
	global_store_dwordx2 v[138:139], v[136:137], off offset:-1536 nt
	v_pk_mul_f32 v[136:137], v[140:141], v[150:151] op_sel_hi:[1,0]
	v_pk_mul_f32 v[140:141], v[142:143], v[150:151] op_sel_hi:[1,0]
	v_pk_fma_f32 v[136:137], v[68:69], v[136:137], v[14:15]
	v_pk_fma_f32 v[140:141], v[62:63], v[140:141], v[16:17]
	v_cvt_pk_bf16_f32 v136, v136, v137
	v_cvt_pk_bf16_f32 v137, v140, v141
	global_store_dwordx2 v[138:139], v[136:137], off offset:-1024 nt
	v_pk_mul_f32 v[136:137], v[144:145], v[150:151] op_sel_hi:[1,0]
	v_pk_mul_f32 v[140:141], v[146:147], v[150:151] op_sel_hi:[1,0]
	v_pk_fma_f32 v[136:137], v[64:65], v[136:137], v[6:7]
	v_pk_fma_f32 v[140:141], v[60:61], v[140:141], v[8:9]
	v_cvt_pk_bf16_f32 v136, v136, v137
	v_cvt_pk_bf16_f32 v137, v140, v141
	global_store_dwordx2 v[138:139], v[136:137], off offset:-512 nt
	v_pk_mul_f32 v[136:137], v[148:149], v[150:151] op_sel_hi:[1,0]
	s_add_i32 s0, s10, s0
	v_pk_fma_f32 v[134:135], v[82:83], v[134:135], v[12:13]
	v_pk_fma_f32 v[136:137], v[88:89], v[136:137], v[10:11]
	s_ashr_i32 s11, s0, 14
	v_cvt_pk_bf16_f32 v136, v136, v137
	v_cvt_pk_bf16_f32 v137, v134, v135
	s_cmp_eq_u32 s11, s26
	global_store_dwordx2 v[138:139], v[136:137], off nt
	s_cbranch_scc1 .LBB0_791
	s_mul_i32 s0, s11, 0xc00
	s_ashr_i32 s1, s0, 31
	s_lshl_b64 s[0:1], s[0:1], 2
	s_add_u32 s14, s18, s0
	s_addc_u32 s15, s19, s1
	s_add_u32 s16, s14, 0x2000
	s_addc_u32 s17, s15, 0
	s_add_u32 s0, s20, s0
	global_load_dwordx4 v[60:63], v1, s[16:17]
	global_load_dwordx4 v[64:67], v[18:19], off
	global_load_dwordx4 v[68:71], v128, s[16:17]
	global_load_dwordx4 v[78:81], v[22:23], off
	global_load_dwordx4 v[88:91], v129, s[16:17]
	global_load_dwordx4 v[134:137], v[26:27], off
	global_load_dwordx4 v[138:141], v130, s[16:17]
	global_load_dwordx4 v[142:145], v[30:31], off
	s_addc_u32 s1, s21, s1
	s_add_u32 s14, s0, 0x1000
	s_addc_u32 s15, s1, 0
	global_load_dwordx4 v[146:149], v1, s[14:15]
	global_load_dwordx4 v[150:153], v128, s[14:15]
	global_load_dwordx4 v[154:157], v129, s[14:15]
	global_load_dwordx4 v[158:161], v130, s[14:15]
	global_load_dwordx4 v[162:165], v[20:21], off
	global_load_dwordx4 v[166:169], v[24:25], off
	global_load_dwordx4 v[170:173], v[28:29], off
	global_load_dwordx4 v[174:177], v[32:33], off
	global_load_dwordx4 v[2:5], v1, s[0:1]
	global_load_dwordx4 v[14:17], v1, s[0:1] offset:1024
	global_load_dwordx4 v[6:9], v1, s[0:1] offset:2048
	global_load_dwordx4 v[10:13], v1, s[0:1] offset:3072
	s_mov_b32 s26, s11
	s_waitcnt vmcnt(18)
	v_pk_mul_f32 v[74:75], v[62:63], v[66:67]
	v_pk_mul_f32 v[76:77], v[60:61], v[64:65]
	s_waitcnt vmcnt(16)
	v_pk_mul_f32 v[84:85], v[70:71], v[80:81]
	v_pk_mul_f32 v[86:87], v[68:69], v[78:79]
	s_waitcnt vmcnt(14)
	v_pk_mul_f32 v[78:79], v[90:91], v[136:137]
	v_pk_mul_f32 v[80:81], v[88:89], v[134:135]
	s_waitcnt vmcnt(11)
	v_pk_add_f32 v[60:61], v[148:149], 1.0 op_sel_hi:[1,0]
	v_pk_add_f32 v[62:63], v[146:147], 1.0 op_sel_hi:[1,0]
	s_waitcnt vmcnt(10)
	v_pk_add_f32 v[64:65], v[152:153], 1.0 op_sel_hi:[1,0]
	v_pk_add_f32 v[68:69], v[150:151], 1.0 op_sel_hi:[1,0]
	s_waitcnt vmcnt(9)
	v_pk_add_f32 v[82:83], v[156:157], 1.0 op_sel_hi:[1,0]
	v_pk_add_f32 v[88:89], v[154:155], 1.0 op_sel_hi:[1,0]
	s_waitcnt vmcnt(8)
	v_pk_add_f32 v[134:135], v[160:161], 1.0 op_sel_hi:[1,0]
	v_pk_add_f32 v[136:137], v[158:159], 1.0 op_sel_hi:[1,0]
	v_pk_mul_f32 v[90:91], v[140:141], v[144:145]
	v_pk_mul_f32 v[92:93], v[138:139], v[142:143]
	s_waitcnt vmcnt(7)
	v_pk_mul_f32 v[66:67], v[164:165], v[60:61]
	v_pk_mul_f32 v[70:71], v[162:163], v[62:63]
	s_waitcnt vmcnt(6)
	v_pk_mul_f32 v[62:63], v[168:169], v[64:65]
	v_pk_mul_f32 v[68:69], v[166:167], v[68:69]
	s_waitcnt vmcnt(5)
	v_pk_mul_f32 v[60:61], v[172:173], v[82:83]
	v_pk_mul_f32 v[64:65], v[170:171], v[88:89]
	s_waitcnt vmcnt(4)
	v_pk_mul_f32 v[82:83], v[176:177], v[134:135]
	v_pk_mul_f32 v[88:89], v[174:175], v[136:137]
.LBB0_791:
	v_lshlrev_b32_e32 v140, 16, v122
	v_and_b32_e32 v141, 0xffff0000, v122
	v_lshlrev_b32_e32 v122, 16, v123
	v_and_b32_e32 v123, 0xffff0000, v123
	v_lshlrev_b32_e32 v138, 16, v114
	v_and_b32_e32 v139, 0xffff0000, v114
	v_mul_f32_e32 v114, v123, v123
	v_pk_fma_f32 v[142:143], v[122:123], v[122:123], v[114:115] op_sel_hi:[1,1,0]
	v_lshlrev_b32_e32 v145, 16, v121
	v_lshlrev_b32_e32 v144, 16, v120
	v_and_b32_e32 v121, 0xffff0000, v121
	v_and_b32_e32 v120, 0xffff0000, v120
	v_mul_f32_e32 v114, v141, v141
	v_pk_mul_f32 v[146:147], v[120:121], v[120:121]
	v_lshlrev_b32_e32 v151, 16, v116
	v_pk_fma_f32 v[154:155], v[140:141], v[140:141], v[114:115] op_sel_hi:[1,1,0]
	v_pk_fma_f32 v[146:147], v[144:145], v[144:145], v[146:147]
	v_and_b32_e32 v153, 0xffff0000, v116
	v_mov_b32_e32 v150, v154
	v_mov_b32_e32 v156, v142
	v_mov_b32_e32 v157, v151
	v_and_b32_e32 v149, 0xffff0000, v118
	v_mul_f32_e32 v133, v153, v153
	v_pk_add_f32 v[142:143], v[154:155], v[142:143]
	v_pk_mul_f32 v[154:155], v[150:151], v[156:157]
	v_pk_add_f32 v[146:147], v[146:147], v[146:147] op_sel:[0,1] op_sel_hi:[1,0]
	v_lshlrev_b32_e32 v148, 16, v118
	v_lshlrev_b32_e32 v118, 16, v119
	v_and_b32_e32 v119, 0xffff0000, v119
	v_mov_b32_e32 v143, v155
	v_mov_b32_e32 v147, v133
	v_mul_f32_e32 v114, v149, v149
	v_lshlrev_b32_e32 v116, 16, v117
	v_and_b32_e32 v117, 0xffff0000, v117
	v_pk_add_f32 v[142:143], v[142:143], v[146:147]
	v_pk_fma_f32 v[146:147], v[148:149], v[148:149], v[114:115] op_sel_hi:[1,1,0]
	v_mul_f32_e32 v114, v119, v119
	v_mul_f32_e32 v152, v116, v116
	v_mul_f32_e32 v158, v117, v117
	v_pk_fma_f32 v[154:155], v[118:119], v[118:119], v[114:115] op_sel_hi:[1,1,0]
	v_mov_b32_e32 v147, v152
	v_mov_b32_e32 v155, v158
	v_pk_add_f32 v[146:147], v[146:147], v[154:155]
	v_lshlrev_b32_e32 v134, 16, v126
	v_pk_add_f32 v[142:143], v[142:143], v[146:147]
	v_and_b32_e32 v135, 0xffff0000, v126
	v_add_f32_e32 v114, v142, v143
	v_lshlrev_b32_e32 v126, 16, v127
	v_and_b32_e32 v127, 0xffff0000, v127
	v_add_f32_dpp v114, v114, v114 quad_perm:[1,0,3,2] row_mask:0xf bank_mask:0xf bound_ctrl:1
	v_lshlrev_b32_e32 v136, 16, v124
	v_and_b32_e32 v137, 0xffff0000, v124
	v_add_f32_dpp v114, v114, v114 quad_perm:[2,3,0,1] row_mask:0xf bank_mask:0xf bound_ctrl:1
	v_lshlrev_b32_e32 v124, 16, v125
	v_and_b32_e32 v125, 0xffff0000, v125
	v_add_f32_dpp v114, v114, v114 row_half_mirror row_mask:0xf bank_mask:0xf bound_ctrl:1
	s_nop 1
	v_add_f32_dpp v114, v114, v114 row_mirror row_mask:0xf bank_mask:0xf bound_ctrl:1
	s_nop 0
	v_readlane_b32 s11, v114, 16
	v_readlane_b32 s14, v114, 48
	v_readlane_b32 s0, v114, 0
	v_readlane_b32 s1, v114, 32
	v_mov_b32_e32 v142, s11
	v_mov_b32_e32 v143, s14
	v_pk_add_f32 v[142:143], s[0:1], v[142:143]
	s_nop 0
	v_add_f32_e32 v114, v142, v143
	v_fmamk_f32 v114, v114, 0x3a800000, v131
	v_mul_f32_e32 v133, 0x4f800000, v114
	v_cmp_gt_f32_e32 vcc, s24, v114
	v_lshlrev_b32_e32 v142, 16, v112
	s_nop 0
	v_cndmask_b32_e32 v133, v114, v133, vcc
	v_sqrt_f32_e32 v143, v133
	v_lshlrev_b32_e32 v114, 16, v115
	v_and_b32_e32 v115, 0xffff0000, v115
	v_add_u32_e32 v146, -1, v143
	v_fma_f32 v147, -v146, v143, v133
	v_cmp_ge_f32_e64 s[0:1], 0, v147
	v_add_u32_e32 v147, 1, v143
	s_nop 0
	v_cndmask_b32_e64 v146, v143, v146, s[0:1]
	v_fma_f32 v143, -v147, v143, v133
	v_cmp_lt_f32_e64 s[0:1], 0, v143
	s_nop 1
	v_cndmask_b32_e64 v143, v146, v147, s[0:1]
	v_mul_f32_e32 v146, 0x37800000, v143
	v_cndmask_b32_e32 v143, v143, v146, vcc
	v_cmp_class_f32_e32 vcc, v133, v132
	s_nop 1
	v_cndmask_b32_e32 v133, v143, v133, vcc
	v_div_scale_f32 v146, s[0:1], v133, v133, 1.0
	v_rcp_f32_e32 v147, v146
	v_and_b32_e32 v143, 0xffff0000, v112
	v_lshlrev_b32_e32 v112, 16, v113
	v_and_b32_e32 v113, 0xffff0000, v113
	v_fma_f32 v150, -v146, v147, 1.0
	v_fmac_f32_e32 v147, v150, v147
	v_div_scale_f32 v150, vcc, 1.0, v133, 1.0
	v_mul_f32_e32 v152, v150, v147
	v_fma_f32 v154, -v146, v152, v150
	v_fmac_f32_e32 v152, v154, v147
	v_fma_f32 v146, -v146, v152, v150
	v_div_fmas_f32 v146, v146, v147, v152
	v_div_fixup_f32 v146, v146, v133, 1.0
	v_pk_mul_f32 v[140:141], v[146:147], v[140:141] op_sel_hi:[0,1]
	v_pk_mul_f32 v[122:123], v[146:147], v[122:123] op_sel_hi:[0,1]
	v_pk_fma_f32 v[122:123], v[74:75], v[122:123], v[126:127]
	v_pk_fma_f32 v[126:127], v[76:77], v[140:141], v[134:135]
	v_cvt_pk_bf16_f32 v135, v122, v123
	v_cvt_pk_bf16_f32 v134, v126, v127
	global_store_dwordx2 v[110:111], v[134:135], off nt
	v_mov_b32_e32 v134, v144
	v_mov_b32_e32 v135, v120
	v_mov_b32_e32 v120, v145
	v_pk_mul_f32 v[134:135], v[146:147], v[134:135] op_sel_hi:[0,1]
	v_pk_mul_f32 v[120:121], v[146:147], v[120:121] op_sel_hi:[0,1]
	v_pk_fma_f32 v[120:121], v[84:85], v[120:121], v[124:125]
	v_pk_fma_f32 v[124:125], v[86:87], v[134:135], v[136:137]
	v_cvt_pk_bf16_f32 v135, v120, v121
	v_cvt_pk_bf16_f32 v134, v124, v125
	global_store_dwordx2 v[110:111], v[134:135], off offset:512 nt
	v_pk_mul_f32 v[134:135], v[146:147], v[148:149] op_sel_hi:[0,1]
	v_pk_mul_f32 v[118:119], v[146:147], v[118:119] op_sel_hi:[0,1]
	v_mov_b32_e32 v152, v151
	v_pk_fma_f32 v[114:115], v[78:79], v[118:119], v[114:115]
	v_pk_fma_f32 v[118:119], v[80:81], v[134:135], v[138:139]
	v_pk_mul_f32 v[134:135], v[152:153], v[146:147] op_sel_hi:[1,0]
	v_pk_mul_f32 v[116:117], v[116:117], v[146:147] op_sel_hi:[1,0]
	v_pk_mul_f32 v[136:137], v[126:127], v[126:127]
	v_pk_fma_f32 v[112:113], v[90:91], v[116:117], v[112:113]
	v_pk_fma_f32 v[116:117], v[92:93], v[134:135], v[142:143]
	v_pk_mul_f32 v[134:135], v[122:123], v[122:123]
	s_nop 0
	v_pk_mov_b32 v[138:139], v[136:137], v[134:135] op_sel:[1,0]
	v_mov_b32_e32 v137, v135
	v_pk_add_f32 v[134:135], v[138:139], v[136:137]
	v_pk_mul_f32 v[136:137], v[120:121], v[120:121]
	v_pk_add_f32 v[134:135], v[134:135], v[134:135] op_sel_hi:[0,1]
	v_pk_mul_f32 v[138:139], v[124:125], v[124:125]
	v_mul_f32_e32 v134, v118, v118
	v_pk_mov_b32 v[140:141], v[138:139], v[136:137] op_sel:[1,0]
	v_mov_b32_e32 v139, v137
	v_pk_add_f32 v[136:137], v[140:141], v[138:139]
	v_pk_fma_f32 v[138:139], v[118:119], v[118:119], v[134:135] op_sel_hi:[1,1,0]
	v_mul_f32_e32 v134, v114, v114
	v_pk_add_f32 v[136:137], v[136:137], v[136:137] op_sel_hi:[0,1]
	v_pk_fma_f32 v[140:141], v[114:115], v[114:115], v[134:135] op_sel_hi:[1,1,0]
	v_mul_f32_e32 v138, v116, v116
	v_mul_f32_e32 v140, v117, v117
	v_mul_f32_e32 v134, v112, v112
	v_mul_f32_e32 v136, v113, v113
	v_pk_add_f32 v[138:139], v[138:139], v[140:141]
	v_pk_add_f32 v[134:135], v[134:135], v[136:137]
	s_nop 0
	v_pk_add_f32 v[134:135], v[138:139], v[134:135]
	s_nop 0
	v_add_f32_e32 v133, v134, v135
	s_nop 1
	v_add_f32_dpp v133, v133, v133 quad_perm:[1,0,3,2] row_mask:0xf bank_mask:0xf bound_ctrl:1
	s_nop 1
	v_add_f32_dpp v133, v133, v133 quad_perm:[2,3,0,1] row_mask:0xf bank_mask:0xf bound_ctrl:1
	s_nop 1
	v_add_f32_dpp v133, v133, v133 row_half_mirror row_mask:0xf bank_mask:0xf bound_ctrl:1
	s_nop 1
	v_add_f32_dpp v133, v133, v133 row_mirror row_mask:0xf bank_mask:0xf bound_ctrl:1
	s_nop 0
	v_readlane_b32 s11, v133, 16
	v_readlane_b32 s14, v133, 48
	v_readlane_b32 s0, v133, 0
	v_readlane_b32 s1, v133, 32
	v_mov_b32_e32 v134, s11
	v_mov_b32_e32 v135, s14
	v_pk_add_f32 v[134:135], s[0:1], v[134:135]
	s_add_i32 s14, s3, s10
	v_add_f32_e32 v133, v134, v135
	v_fmamk_f32 v133, v133, 0x3a800000, v131
	v_mul_f32_e32 v134, 0x4f800000, v133
	v_cmp_gt_f32_e32 vcc, s24, v133
	v_cvt_pk_bf16_f32 v135, v114, v115
	s_nop 0
	v_cndmask_b32_e32 v133, v133, v134, vcc
	v_sqrt_f32_e32 v136, v133
	v_cvt_pk_bf16_f32 v134, v118, v119
	global_store_dwordx2 v[110:111], v[134:135], off offset:1024 nt
	v_add_u32_e32 v134, -1, v136
	v_fma_f32 v135, -v134, v136, v133
	v_cmp_ge_f32_e64 s[0:1], 0, v135
	v_add_u32_e32 v135, 1, v136
	s_nop 0
	v_cndmask_b32_e64 v134, v136, v134, s[0:1]
	v_fma_f32 v136, -v135, v136, v133
	v_cmp_lt_f32_e64 s[0:1], 0, v136
	s_nop 1
	v_cndmask_b32_e64 v134, v134, v135, s[0:1]
	v_mul_f32_e32 v135, 0x37800000, v134
	v_cndmask_b32_e32 v134, v134, v135, vcc
	v_cmp_class_f32_e32 vcc, v133, v132
	v_cvt_pk_bf16_f32 v135, v112, v113
	s_nop 0
	v_cndmask_b32_e32 v133, v134, v133, vcc
	v_div_scale_f32 v136, s[0:1], v133, v133, 1.0
	v_rcp_f32_e32 v137, v136
	v_cvt_pk_bf16_f32 v134, v116, v117
	global_store_dwordx2 v[110:111], v[134:135], off offset:1536 nt
	s_ashr_i32 s0, s14, 31
	v_fma_f32 v110, -v136, v137, 1.0
	v_fmac_f32_e32 v137, v110, v137
	v_div_scale_f32 v110, vcc, 1.0, v133, 1.0
	v_mul_f32_e32 v111, v110, v137
	v_fma_f32 v134, -v136, v111, v110
	v_fmac_f32_e32 v111, v134, v137
	v_fma_f32 v110, -v136, v111, v110
	v_div_fmas_f32 v110, v110, v137, v111
	v_div_fixup_f32 v110, v110, v133, 1.0
	v_pk_mul_f32 v[118:119], v[118:119], v[110:111] op_sel_hi:[1,0]
	v_pk_mul_f32 v[114:115], v[114:115], v[110:111] op_sel_hi:[1,0]
	s_waitcnt vmcnt(5)
	v_pk_fma_f32 v[118:119], v[64:65], v[118:119], v[6:7]
	v_pk_fma_f32 v[114:115], v[60:61], v[114:115], v[8:9]
	s_lshr_b32 s0, s0, 18
	v_pk_mul_f32 v[126:127], v[126:127], v[110:111] op_sel_hi:[1,0]
	v_pk_mul_f32 v[122:123], v[122:123], v[110:111] op_sel_hi:[1,0]
	v_pk_mul_f32 v[124:125], v[124:125], v[110:111] op_sel_hi:[1,0]
	v_pk_mul_f32 v[120:121], v[120:121], v[110:111] op_sel_hi:[1,0]
	v_cvt_pk_bf16_f32 v118, v118, v119
	v_cvt_pk_bf16_f32 v119, v114, v115
	v_pk_mul_f32 v[114:115], v[116:117], v[110:111] op_sel_hi:[1,0]
	v_pk_mul_f32 v[110:111], v[112:113], v[110:111] op_sel_hi:[1,0]
	s_add_i32 s0, s14, s0
	v_pk_fma_f32 v[122:123], v[66:67], v[122:123], v[4:5]
	v_pk_fma_f32 v[126:127], v[70:71], v[126:127], v[2:3]
	v_pk_fma_f32 v[120:121], v[62:63], v[120:121], v[16:17]
	v_pk_fma_f32 v[124:125], v[68:69], v[124:125], v[14:15]
	s_waitcnt vmcnt(4)
	v_pk_fma_f32 v[110:111], v[82:83], v[110:111], v[12:13]
	v_pk_fma_f32 v[112:113], v[88:89], v[114:115], v[10:11]
	s_ashr_i32 s15, s0, 14
	v_cvt_pk_bf16_f32 v126, v126, v127
	v_cvt_pk_bf16_f32 v127, v122, v123
	v_lshl_add_u64 v[122:123], v[38:39], 0, s[12:13]
	v_cvt_pk_bf16_f32 v124, v124, v125
	v_cvt_pk_bf16_f32 v125, v120, v121
	v_cvt_pk_bf16_f32 v112, v112, v113
	v_cvt_pk_bf16_f32 v113, v110, v111
	s_cmp_eq_u32 s15, s26
	global_store_dwordx2 v[122:123], v[126:127], off nt
	global_store_dwordx2 v[122:123], v[124:125], off offset:512 nt
	global_store_dwordx2 v[122:123], v[118:119], off offset:1024 nt
	global_store_dwordx2 v[122:123], v[112:113], off offset:1536 nt
	s_cbranch_scc1 .LBB0_793
	s_mul_i32 s0, s15, 0xc00
	s_ashr_i32 s1, s0, 31
	s_lshl_b64 s[0:1], s[0:1], 2
	s_add_u32 s10, s18, s0
	s_addc_u32 s11, s19, s1
	s_add_u32 s12, s10, 0x2000
	s_addc_u32 s13, s11, 0
	s_add_u32 s0, s20, s0
	global_load_dwordx4 v[60:63], v1, s[12:13]
	global_load_dwordx4 v[64:67], v[18:19], off
	global_load_dwordx4 v[68:71], v128, s[12:13]
	global_load_dwordx4 v[78:81], v[22:23], off
	global_load_dwordx4 v[88:91], v129, s[12:13]
	global_load_dwordx4 v[110:113], v[26:27], off
	global_load_dwordx4 v[114:117], v130, s[12:13]
	global_load_dwordx4 v[118:121], v[30:31], off
	s_addc_u32 s1, s21, s1
	s_add_u32 s10, s0, 0x1000
	s_addc_u32 s11, s1, 0
	global_load_dwordx4 v[122:125], v1, s[10:11]
	global_load_dwordx4 v[134:137], v128, s[10:11]
	global_load_dwordx4 v[138:141], v129, s[10:11]
	global_load_dwordx4 v[142:145], v130, s[10:11]
	global_load_dwordx4 v[146:149], v[20:21], off
	global_load_dwordx4 v[150:153], v[24:25], off
	global_load_dwordx4 v[154:157], v[28:29], off
	global_load_dwordx4 v[158:161], v[32:33], off
	global_load_dwordx4 v[2:5], v1, s[0:1]
	global_load_dwordx4 v[14:17], v1, s[0:1] offset:1024
	global_load_dwordx4 v[6:9], v1, s[0:1] offset:2048
	global_load_dwordx4 v[10:13], v1, s[0:1] offset:3072
	s_mov_b32 s26, s15
	s_waitcnt vmcnt(18)
	v_pk_mul_f32 v[74:75], v[62:63], v[66:67]
	v_pk_mul_f32 v[76:77], v[60:61], v[64:65]
	s_waitcnt vmcnt(16)
	v_pk_mul_f32 v[84:85], v[70:71], v[80:81]
	v_pk_mul_f32 v[86:87], v[68:69], v[78:79]
	s_waitcnt vmcnt(14)
	v_pk_mul_f32 v[78:79], v[90:91], v[112:113]
	v_pk_mul_f32 v[80:81], v[88:89], v[110:111]
	s_waitcnt vmcnt(11)
	v_pk_add_f32 v[60:61], v[124:125], 1.0 op_sel_hi:[1,0]
	v_pk_add_f32 v[62:63], v[122:123], 1.0 op_sel_hi:[1,0]
	s_waitcnt vmcnt(10)
	v_pk_add_f32 v[64:65], v[136:137], 1.0 op_sel_hi:[1,0]
	v_pk_add_f32 v[68:69], v[134:135], 1.0 op_sel_hi:[1,0]
	s_waitcnt vmcnt(9)
	v_pk_add_f32 v[82:83], v[140:141], 1.0 op_sel_hi:[1,0]
	v_pk_add_f32 v[88:89], v[138:139], 1.0 op_sel_hi:[1,0]
	s_waitcnt vmcnt(8)
	v_pk_add_f32 v[110:111], v[144:145], 1.0 op_sel_hi:[1,0]
	v_pk_add_f32 v[112:113], v[142:143], 1.0 op_sel_hi:[1,0]
	v_pk_mul_f32 v[90:91], v[116:117], v[120:121]
	v_pk_mul_f32 v[92:93], v[114:115], v[118:119]
	s_waitcnt vmcnt(7)
	v_pk_mul_f32 v[66:67], v[148:149], v[60:61]
	v_pk_mul_f32 v[70:71], v[146:147], v[62:63]
	s_waitcnt vmcnt(6)
	v_pk_mul_f32 v[62:63], v[152:153], v[64:65]
	v_pk_mul_f32 v[68:69], v[150:151], v[68:69]
	s_waitcnt vmcnt(5)
	v_pk_mul_f32 v[60:61], v[156:157], v[82:83]
	v_pk_mul_f32 v[64:65], v[154:155], v[88:89]
	s_waitcnt vmcnt(4)
	v_pk_mul_f32 v[82:83], v[160:161], v[110:111]
	v_pk_mul_f32 v[88:89], v[158:159], v[112:113]
.LBB0_793:
	v_lshlrev_b32_e32 v116, 16, v108
	v_and_b32_e32 v117, 0xffff0000, v108
	v_lshlrev_b32_e32 v108, 16, v109
	v_and_b32_e32 v109, 0xffff0000, v109
	v_lshlrev_b32_e32 v114, 16, v96
	v_and_b32_e32 v115, 0xffff0000, v96
	v_mul_f32_e32 v96, v109, v109
	v_pk_fma_f32 v[118:119], v[108:109], v[108:109], v[96:97] op_sel_hi:[1,1,0]
	v_lshlrev_b32_e32 v121, 16, v103
	v_lshlrev_b32_e32 v120, 16, v102
	v_and_b32_e32 v103, 0xffff0000, v103
	v_and_b32_e32 v102, 0xffff0000, v102
	v_mul_f32_e32 v96, v117, v117
	v_pk_mul_f32 v[122:123], v[102:103], v[102:103]
	v_lshlrev_b32_e32 v127, 16, v98
	v_pk_fma_f32 v[136:137], v[116:117], v[116:117], v[96:97] op_sel_hi:[1,1,0]
	v_pk_fma_f32 v[122:123], v[120:121], v[120:121], v[122:123]
	v_and_b32_e32 v135, 0xffff0000, v98
	v_mov_b32_e32 v126, v136
	v_mov_b32_e32 v138, v118
	v_mov_b32_e32 v139, v127
	v_and_b32_e32 v125, 0xffff0000, v100
	v_mul_f32_e32 v133, v135, v135
	v_pk_add_f32 v[118:119], v[136:137], v[118:119]
	v_pk_mul_f32 v[136:137], v[126:127], v[138:139]
	v_pk_add_f32 v[122:123], v[122:123], v[122:123] op_sel:[0,1] op_sel_hi:[1,0]
	v_lshlrev_b32_e32 v124, 16, v100
	v_lshlrev_b32_e32 v100, 16, v101
	v_and_b32_e32 v101, 0xffff0000, v101
	v_mov_b32_e32 v119, v137
	v_mov_b32_e32 v123, v133
	v_mul_f32_e32 v96, v125, v125
	v_lshlrev_b32_e32 v98, 16, v99
	v_and_b32_e32 v99, 0xffff0000, v99
	v_pk_add_f32 v[118:119], v[118:119], v[122:123]
	v_pk_fma_f32 v[122:123], v[124:125], v[124:125], v[96:97] op_sel_hi:[1,1,0]
	v_mul_f32_e32 v96, v101, v101
	v_mul_f32_e32 v134, v98, v98
	v_mul_f32_e32 v140, v99, v99
	v_pk_fma_f32 v[136:137], v[100:101], v[100:101], v[96:97] op_sel_hi:[1,1,0]
	v_mov_b32_e32 v123, v134
	v_mov_b32_e32 v137, v140
	v_pk_add_f32 v[122:123], v[122:123], v[136:137]
	v_lshlrev_b32_e32 v110, 16, v106
	v_pk_add_f32 v[118:119], v[118:119], v[122:123]
	v_and_b32_e32 v111, 0xffff0000, v106
	v_add_f32_e32 v96, v118, v119
	v_lshlrev_b32_e32 v106, 16, v107
	v_and_b32_e32 v107, 0xffff0000, v107
	v_add_f32_dpp v96, v96, v96 quad_perm:[1,0,3,2] row_mask:0xf bank_mask:0xf bound_ctrl:1
	v_lshlrev_b32_e32 v112, 16, v104
	v_and_b32_e32 v113, 0xffff0000, v104
	v_add_f32_dpp v96, v96, v96 quad_perm:[2,3,0,1] row_mask:0xf bank_mask:0xf bound_ctrl:1
	v_lshlrev_b32_e32 v104, 16, v105
	v_and_b32_e32 v105, 0xffff0000, v105
	v_add_f32_dpp v96, v96, v96 row_half_mirror row_mask:0xf bank_mask:0xf bound_ctrl:1
	s_add_i32 s12, s3, s14
	s_nop 0
	v_add_f32_dpp v96, v96, v96 row_mirror row_mask:0xf bank_mask:0xf bound_ctrl:1
	s_nop 0
	v_readlane_b32 s10, v96, 16
	v_readlane_b32 s11, v96, 48
	v_readlane_b32 s0, v96, 0
	v_readlane_b32 s1, v96, 32
	v_mov_b32_e32 v118, s10
	v_mov_b32_e32 v119, s11
	v_pk_add_f32 v[118:119], s[0:1], v[118:119]
	s_nop 0
	v_add_f32_e32 v96, v118, v119
	v_fmamk_f32 v96, v96, 0x3a800000, v131
	v_mul_f32_e32 v118, 0x4f800000, v96
	v_cmp_gt_f32_e32 vcc, s24, v96
	s_nop 1
	v_cndmask_b32_e32 v119, v96, v118, vcc
	v_sqrt_f32_e32 v122, v119
	v_lshlrev_b32_e32 v96, 16, v97
	v_and_b32_e32 v97, 0xffff0000, v97
	v_lshlrev_b32_e32 v118, 16, v94
	v_add_u32_e32 v123, -1, v122
	v_fma_f32 v126, -v123, v122, v119
	v_cmp_ge_f32_e64 s[0:1], 0, v126
	v_add_u32_e32 v126, 1, v122
	s_nop 0
	v_cndmask_b32_e64 v123, v122, v123, s[0:1]
	v_fma_f32 v122, -v126, v122, v119
	v_cmp_lt_f32_e64 s[0:1], 0, v122
	s_nop 1
	v_cndmask_b32_e64 v122, v123, v126, s[0:1]
	v_mul_f32_e32 v123, 0x37800000, v122
	v_cndmask_b32_e32 v122, v122, v123, vcc
	v_cmp_class_f32_e32 vcc, v119, v132
	s_nop 1
	v_cndmask_b32_e32 v122, v122, v119, vcc
	v_div_scale_f32 v123, s[0:1], v122, v122, 1.0
	v_rcp_f32_e32 v126, v123
	v_and_b32_e32 v119, 0xffff0000, v94
	v_lshlrev_b32_e32 v94, 16, v95
	v_and_b32_e32 v95, 0xffff0000, v95
	v_fma_f32 v133, -v123, v126, 1.0
	v_fmac_f32_e32 v126, v133, v126
	v_div_scale_f32 v133, vcc, 1.0, v122, 1.0
	v_mul_f32_e32 v134, v133, v126
	v_fma_f32 v136, -v123, v134, v133
	v_fmac_f32_e32 v134, v136, v126
	v_fma_f32 v123, -v123, v134, v133
	v_div_fmas_f32 v123, v123, v126, v134
	v_div_fixup_f32 v122, v123, v122, 1.0
	v_pk_mul_f32 v[116:117], v[122:123], v[116:117] op_sel_hi:[0,1]
	v_pk_mul_f32 v[108:109], v[122:123], v[108:109] op_sel_hi:[0,1]
	v_pk_fma_f32 v[106:107], v[74:75], v[108:109], v[106:107]
	v_pk_fma_f32 v[108:109], v[76:77], v[116:117], v[110:111]
	v_cvt_pk_bf16_f32 v111, v106, v107
	v_cvt_pk_bf16_f32 v110, v108, v109
	global_store_dwordx2 v[72:73], v[110:111], off nt
	v_mov_b32_e32 v110, v120
	v_mov_b32_e32 v111, v102
	v_mov_b32_e32 v102, v121
	v_pk_mul_f32 v[110:111], v[122:123], v[110:111] op_sel_hi:[0,1]
	v_pk_mul_f32 v[102:103], v[122:123], v[102:103] op_sel_hi:[0,1]
	v_pk_fma_f32 v[102:103], v[84:85], v[102:103], v[104:105]
	v_pk_fma_f32 v[104:105], v[86:87], v[110:111], v[112:113]
	v_cvt_pk_bf16_f32 v111, v102, v103
	v_cvt_pk_bf16_f32 v110, v104, v105
	global_store_dwordx2 v[72:73], v[110:111], off offset:512 nt
	v_pk_mul_f32 v[110:111], v[122:123], v[124:125] op_sel_hi:[0,1]
	v_pk_mul_f32 v[100:101], v[122:123], v[100:101] op_sel_hi:[0,1]
	v_mov_b32_e32 v134, v127
	v_pk_fma_f32 v[96:97], v[78:79], v[100:101], v[96:97]
	v_pk_fma_f32 v[100:101], v[80:81], v[110:111], v[114:115]
	v_pk_mul_f32 v[110:111], v[134:135], v[122:123] op_sel_hi:[1,0]
	v_pk_mul_f32 v[98:99], v[98:99], v[122:123] op_sel_hi:[1,0]
	v_pk_mul_f32 v[112:113], v[108:109], v[108:109]
	v_pk_fma_f32 v[94:95], v[90:91], v[98:99], v[94:95]
	v_pk_fma_f32 v[98:99], v[92:93], v[110:111], v[118:119]
	v_pk_mul_f32 v[110:111], v[106:107], v[106:107]
	s_nop 0
	v_pk_mov_b32 v[114:115], v[112:113], v[110:111] op_sel:[1,0]
	v_mov_b32_e32 v113, v111
	v_pk_add_f32 v[110:111], v[114:115], v[112:113]
	v_pk_mul_f32 v[112:113], v[102:103], v[102:103]
	v_pk_add_f32 v[110:111], v[110:111], v[110:111] op_sel_hi:[0,1]
	v_pk_mul_f32 v[114:115], v[104:105], v[104:105]
	v_mul_f32_e32 v110, v100, v100
	v_pk_mov_b32 v[116:117], v[114:115], v[112:113] op_sel:[1,0]
	v_mov_b32_e32 v115, v113
	v_pk_add_f32 v[112:113], v[116:117], v[114:115]
	v_pk_fma_f32 v[114:115], v[100:101], v[100:101], v[110:111] op_sel_hi:[1,1,0]
	v_mul_f32_e32 v110, v96, v96
	v_pk_add_f32 v[112:113], v[112:113], v[112:113] op_sel_hi:[0,1]
	v_pk_fma_f32 v[116:117], v[96:97], v[96:97], v[110:111] op_sel_hi:[1,1,0]
	v_mul_f32_e32 v114, v98, v98
	v_mul_f32_e32 v116, v99, v99
	v_mul_f32_e32 v110, v94, v94
	v_mul_f32_e32 v112, v95, v95
	v_pk_add_f32 v[114:115], v[114:115], v[116:117]
	v_pk_add_f32 v[110:111], v[110:111], v[112:113]
	s_nop 0
	v_pk_add_f32 v[110:111], v[114:115], v[110:111]
	s_nop 0
	v_add_f32_e32 v110, v110, v111
	s_nop 1
	v_add_f32_dpp v110, v110, v110 quad_perm:[1,0,3,2] row_mask:0xf bank_mask:0xf bound_ctrl:1
	s_nop 1
	v_add_f32_dpp v110, v110, v110 quad_perm:[2,3,0,1] row_mask:0xf bank_mask:0xf bound_ctrl:1
	s_nop 1
	v_add_f32_dpp v110, v110, v110 row_half_mirror row_mask:0xf bank_mask:0xf bound_ctrl:1
	s_nop 1
	v_add_f32_dpp v110, v110, v110 row_mirror row_mask:0xf bank_mask:0xf bound_ctrl:1
	s_nop 0
	v_readlane_b32 s10, v110, 16
	v_readlane_b32 s11, v110, 48
	v_readlane_b32 s0, v110, 0
	v_readlane_b32 s1, v110, 32
	v_mov_b32_e32 v110, s10
	v_mov_b32_e32 v111, s11
	v_pk_add_f32 v[110:111], s[0:1], v[110:111]
	s_nop 0
	v_add_f32_e32 v110, v110, v111
	v_fmamk_f32 v110, v110, 0x3a800000, v131
	v_mul_f32_e32 v111, 0x4f800000, v110
	v_cmp_gt_f32_e32 vcc, s24, v110
	s_nop 1
	v_cndmask_b32_e32 v112, v110, v111, vcc
	v_sqrt_f32_e32 v113, v112
	v_cvt_pk_bf16_f32 v110, v100, v101
	v_cvt_pk_bf16_f32 v111, v96, v97
	global_store_dwordx2 v[72:73], v[110:111], off offset:1024 nt
	v_add_u32_e32 v110, -1, v113
	v_fma_f32 v111, -v110, v113, v112
	v_cmp_ge_f32_e64 s[0:1], 0, v111
	v_add_u32_e32 v111, 1, v113
	s_nop 0
	v_cndmask_b32_e64 v110, v113, v110, s[0:1]
	v_fma_f32 v113, -v111, v113, v112
	v_cmp_lt_f32_e64 s[0:1], 0, v113
	s_nop 1
	v_cndmask_b32_e64 v110, v110, v111, s[0:1]
	v_mul_f32_e32 v111, 0x37800000, v110
	v_cndmask_b32_e32 v110, v110, v111, vcc
	v_cmp_class_f32_e32 vcc, v112, v132
	v_cvt_pk_bf16_f32 v111, v94, v95
	s_nop 0
	v_cndmask_b32_e32 v112, v110, v112, vcc
	v_div_scale_f32 v113, s[0:1], v112, v112, 1.0
	v_rcp_f32_e32 v114, v113
	v_cvt_pk_bf16_f32 v110, v98, v99
	global_store_dwordx2 v[72:73], v[110:111], off offset:1536 nt
	s_ashr_i32 s0, s12, 31
	v_fma_f32 v72, -v113, v114, 1.0
	v_fmac_f32_e32 v114, v72, v114
	v_div_scale_f32 v72, vcc, 1.0, v112, 1.0
	v_mul_f32_e32 v73, v72, v114
	v_fma_f32 v110, -v113, v73, v72
	v_fmac_f32_e32 v73, v110, v114
	v_fma_f32 v72, -v113, v73, v72
	v_div_fmas_f32 v72, v72, v114, v73
	v_div_fixup_f32 v72, v72, v112, 1.0
	v_pk_mul_f32 v[100:101], v[100:101], v[72:73] op_sel_hi:[1,0]
	v_pk_mul_f32 v[96:97], v[96:97], v[72:73] op_sel_hi:[1,0]
	s_waitcnt vmcnt(5)
	v_pk_fma_f32 v[100:101], v[64:65], v[100:101], v[6:7]
	v_pk_fma_f32 v[96:97], v[60:61], v[96:97], v[8:9]
	s_lshr_b32 s0, s0, 18
	v_pk_mul_f32 v[108:109], v[108:109], v[72:73] op_sel_hi:[1,0]
	v_pk_mul_f32 v[106:107], v[106:107], v[72:73] op_sel_hi:[1,0]
	v_pk_mul_f32 v[104:105], v[104:105], v[72:73] op_sel_hi:[1,0]
	v_pk_mul_f32 v[102:103], v[102:103], v[72:73] op_sel_hi:[1,0]
	v_cvt_pk_bf16_f32 v100, v100, v101
	v_cvt_pk_bf16_f32 v101, v96, v97
	v_pk_mul_f32 v[96:97], v[98:99], v[72:73] op_sel_hi:[1,0]
	v_pk_mul_f32 v[72:73], v[94:95], v[72:73] op_sel_hi:[1,0]
	s_add_i32 s0, s12, s0
	v_pk_fma_f32 v[106:107], v[66:67], v[106:107], v[4:5]
	v_pk_fma_f32 v[108:109], v[70:71], v[108:109], v[2:3]
	v_pk_fma_f32 v[102:103], v[62:63], v[102:103], v[16:17]
	v_pk_fma_f32 v[104:105], v[68:69], v[104:105], v[14:15]
	s_waitcnt vmcnt(4)
	v_pk_fma_f32 v[72:73], v[82:83], v[72:73], v[12:13]
	v_pk_fma_f32 v[94:95], v[88:89], v[96:97], v[10:11]
	s_ashr_i32 s0, s0, 14
	v_cvt_pk_bf16_f32 v108, v108, v109
	v_cvt_pk_bf16_f32 v109, v106, v107
	v_lshl_add_u64 v[106:107], v[38:39], 0, s[8:9]
	v_cvt_pk_bf16_f32 v104, v104, v105
	v_cvt_pk_bf16_f32 v105, v102, v103
	v_cvt_pk_bf16_f32 v94, v94, v95
	v_cvt_pk_bf16_f32 v95, v72, v73
	s_cmp_eq_u32 s0, s26
	global_store_dwordx2 v[106:107], v[108:109], off nt
	global_store_dwordx2 v[106:107], v[104:105], off offset:512 nt
	global_store_dwordx2 v[106:107], v[100:101], off offset:1024 nt
	global_store_dwordx2 v[106:107], v[94:95], off offset:1536 nt
	s_cbranch_scc1 .LBB0_788
	s_mulk_i32 s0, 0xc00
	s_ashr_i32 s1, s0, 31
	s_lshl_b64 s[0:1], s[0:1], 2
	s_add_u32 s8, s18, s0
	s_addc_u32 s9, s19, s1
	s_add_u32 s10, s8, 0x2000
	s_addc_u32 s11, s9, 0
	global_load_dwordx4 v[60:63], v1, s[10:11]
	global_load_dwordx4 v[64:67], v[18:19], off
	global_load_dwordx4 v[68:71], v128, s[10:11]
	global_load_dwordx4 v[78:81], v[22:23], off
	global_load_dwordx4 v[88:91], v129, s[10:11]
	global_load_dwordx4 v[92:95], v[26:27], off
	global_load_dwordx4 v[96:99], v130, s[10:11]
	global_load_dwordx4 v[100:103], v[30:31], off
	s_add_u32 s0, s20, s0
	s_addc_u32 s1, s21, s1
	s_add_u32 s8, s0, 0x1000
	s_addc_u32 s9, s1, 0
	global_load_dwordx4 v[104:107], v1, s[8:9]
	global_load_dwordx4 v[108:111], v128, s[8:9]
	global_load_dwordx4 v[112:115], v129, s[8:9]
	global_load_dwordx4 v[116:119], v130, s[8:9]
	global_load_dwordx4 v[120:123], v[20:21], off
	global_load_dwordx4 v[124:127], v[24:25], off
	global_load_dwordx4 v[134:137], v[28:29], off
	global_load_dwordx4 v[138:141], v[32:33], off
	global_load_dwordx4 v[2:5], v1, s[0:1]
	global_load_dwordx4 v[14:17], v1, s[0:1] offset:1024
	global_load_dwordx4 v[6:9], v1, s[0:1] offset:2048
	global_load_dwordx4 v[10:13], v1, s[0:1] offset:3072
	s_waitcnt vmcnt(18)
	v_pk_mul_f32 v[74:75], v[62:63], v[66:67]
	v_pk_mul_f32 v[76:77], v[60:61], v[64:65]
	s_waitcnt vmcnt(16)
	v_pk_mul_f32 v[84:85], v[70:71], v[80:81]
	v_pk_mul_f32 v[86:87], v[68:69], v[78:79]
	s_waitcnt vmcnt(14)
	v_pk_mul_f32 v[78:79], v[90:91], v[94:95]
	v_pk_mul_f32 v[80:81], v[88:89], v[92:93]
	s_waitcnt vmcnt(11)
	v_pk_add_f32 v[60:61], v[106:107], 1.0 op_sel_hi:[1,0]
	v_pk_add_f32 v[62:63], v[104:105], 1.0 op_sel_hi:[1,0]
	s_waitcnt vmcnt(10)
	v_pk_add_f32 v[64:65], v[110:111], 1.0 op_sel_hi:[1,0]
	v_pk_add_f32 v[68:69], v[108:109], 1.0 op_sel_hi:[1,0]
	s_waitcnt vmcnt(9)
	v_pk_add_f32 v[72:73], v[114:115], 1.0 op_sel_hi:[1,0]
	v_pk_add_f32 v[82:83], v[112:113], 1.0 op_sel_hi:[1,0]
	s_waitcnt vmcnt(8)
	v_pk_add_f32 v[88:89], v[118:119], 1.0 op_sel_hi:[1,0]
	v_pk_add_f32 v[94:95], v[116:117], 1.0 op_sel_hi:[1,0]
	v_pk_mul_f32 v[90:91], v[98:99], v[102:103]
	v_pk_mul_f32 v[92:93], v[96:97], v[100:101]
	s_waitcnt vmcnt(7)
	v_pk_mul_f32 v[66:67], v[122:123], v[60:61]
	v_pk_mul_f32 v[70:71], v[120:121], v[62:63]
	s_waitcnt vmcnt(6)
	v_pk_mul_f32 v[62:63], v[126:127], v[64:65]
	v_pk_mul_f32 v[68:69], v[124:125], v[68:69]
	s_waitcnt vmcnt(5)
	v_pk_mul_f32 v[60:61], v[136:137], v[72:73]
	v_pk_mul_f32 v[64:65], v[134:135], v[82:83]
	s_waitcnt vmcnt(4)
	v_pk_mul_f32 v[82:83], v[140:141], v[88:89]
	v_pk_mul_f32 v[88:89], v[138:139], v[94:95]
	s_branch .LBB0_788

.LBB0_1092:
	s_ashr_i32 s1, s0, 31
	s_lshr_b32 s1, s1, 18
	s_add_i32 s10, s3, s0
	s_add_i32 s6, s22, s0
	s_add_i32 s14, s23, s0
	s_add_i32 s0, s0, s1
	s_ashr_i32 s27, s0, 14
	s_mul_i32 s0, s27, 0xc00
	s_ashr_i32 s11, s10, 31
	s_ashr_i32 s7, s6, 31
	s_ashr_i32 s15, s14, 31
	s_ashr_i32 s1, s0, 31
	s_lshl_b64 s[12:13], s[10:11], 11
	s_lshl_b64 s[8:9], s[6:7], 11
	s_lshl_b64 s[6:7], s[14:15], 11
	s_lshl_b64 s[0:1], s[0:1], 2
	s_add_u32 s14, s18, s0
	s_addc_u32 s15, s19, s1
	s_add_u32 s14, s14, 0x2000
	s_addc_u32 s15, s15, 0
	s_add_u32 s0, s20, s0
	s_addc_u32 s1, s21, s1
	global_load_dwordx2 v[2:3], v[40:41], off
	global_load_dwordx2 v[4:5], v[40:41], off offset:512
	global_load_dwordx2 v[42:43], v[40:41], off offset:1024
	global_load_dwordx2 v[44:45], v[40:41], off offset:1536
	global_load_dwordx4 v[6:9], v[18:19], off
	global_load_dwordx4 v[10:13], v1, s[14:15]
	s_add_u32 s16, s0, 0x1000
	s_addc_u32 s17, s1, 0
	global_load_dwordx4 v[14:17], v1, s[16:17]
	global_load_dwordx4 v[60:63], v[20:21], off
	global_load_dwordx4 v[78:81], v[22:23], off
	global_load_dwordx4 v[82:85], v128, s[14:15]
	global_load_dwordx4 v[88:91], v128, s[16:17]
	global_load_dwordx4 v[134:137], v[24:25], off
	global_load_dwordx4 v[138:141], v[26:27], off
	global_load_dwordx4 v[142:145], v129, s[14:15]
	global_load_dwordx4 v[146:149], v129, s[16:17]
	global_load_dwordx4 v[150:153], v[28:29], off
	v_add_co_u32_e32 v46, vcc, 0xec000000, v40
	v_lshl_add_u64 v[110:111], v[34:35], 0, s[12:13]
	s_nop 0
	v_addc_co_u32_e32 v47, vcc, -1, v41, vcc
	global_load_dwordx2 v[92:93], v[46:47], off
	v_add_co_u32_e32 v46, vcc, 0xec001000, v40
	v_lshl_add_u64 v[72:73], v[34:35], 0, s[8:9]
	s_nop 0
	v_addc_co_u32_e32 v47, vcc, -1, v41, vcc
	global_load_dwordx2 v[166:167], v[46:47], off offset:-3584
	global_load_dwordx2 v[168:169], v[46:47], off offset:-3072
	global_load_dwordx2 v[170:171], v[46:47], off offset:-2560
	v_lshl_add_u64 v[46:47], v[36:37], 0, s[12:13]
	global_load_dwordx2 v[126:127], v[110:111], off
	global_load_dwordx2 v[124:125], v[110:111], off offset:512
	global_load_dwordx2 v[114:115], v[110:111], off offset:1024
	global_load_dwordx2 v[112:113], v[110:111], off offset:1536
	global_load_dwordx2 v[122:123], v[46:47], off
	global_load_dwordx2 v[120:121], v[46:47], off offset:512
	global_load_dwordx2 v[118:119], v[46:47], off offset:1024
	global_load_dwordx2 v[116:117], v[46:47], off offset:1536
	s_waitcnt vmcnt(27)
	v_lshlrev_b32_e32 v172, 16, v2
	v_and_b32_e32 v173, 0xffff0000, v2
	v_lshlrev_b32_e32 v174, 16, v3
	v_and_b32_e32 v175, 0xffff0000, v3
	v_lshl_add_u64 v[2:3], v[36:37], 0, s[8:9]
	s_waitcnt vmcnt(22)
	v_pk_mul_f32 v[74:75], v[12:13], v[8:9]
	v_pk_mul_f32 v[76:77], v[10:11], v[6:7]
	s_waitcnt vmcnt(21)
	v_pk_add_f32 v[6:7], v[16:17], 1.0 op_sel_hi:[1,0]
	v_pk_add_f32 v[8:9], v[14:15], 1.0 op_sel_hi:[1,0]
	v_lshlrev_b32_e32 v180, 16, v42
	v_and_b32_e32 v181, 0xffff0000, v42
	v_lshlrev_b32_e32 v182, 16, v43
	v_and_b32_e32 v183, 0xffff0000, v43
	global_load_dwordx2 v[108:109], v[72:73], off
	global_load_dwordx2 v[106:107], v[72:73], off offset:512
	global_load_dwordx2 v[96:97], v[72:73], off offset:1024
	global_load_dwordx2 v[94:95], v[72:73], off offset:1536
	global_load_dwordx2 v[104:105], v[2:3], off
	global_load_dwordx2 v[102:103], v[2:3], off offset:512
	global_load_dwordx2 v[100:101], v[2:3], off offset:1024
	global_load_dwordx2 v[98:99], v[2:3], off offset:1536
	v_lshl_add_u64 v[42:43], v[34:35], 0, s[6:7]
	v_lshl_add_u64 v[2:3], v[36:37], 0, s[6:7]
	s_waitcnt vmcnt(28)
	v_pk_mul_f32 v[66:67], v[62:63], v[6:7]
	v_pk_mul_f32 v[70:71], v[60:61], v[8:9]
	s_waitcnt vmcnt(25)
	v_pk_add_f32 v[6:7], v[90:91], 1.0 op_sel_hi:[1,0]
	v_pk_add_f32 v[8:9], v[88:89], 1.0 op_sel_hi:[1,0]
	v_lshlrev_b32_e32 v176, 16, v4
	v_and_b32_e32 v177, 0xffff0000, v4
	v_lshlrev_b32_e32 v178, 16, v5
	v_and_b32_e32 v179, 0xffff0000, v5
	v_lshlrev_b32_e32 v184, 16, v44
	v_and_b32_e32 v185, 0xffff0000, v44
	v_lshlrev_b32_e32 v186, 16, v45
	v_and_b32_e32 v187, 0xffff0000, v45
	global_load_dwordx2 v[58:59], v[42:43], off
	global_load_dwordx2 v[56:57], v[42:43], off offset:512
	global_load_dwordx2 v[46:47], v[42:43], off offset:1024
	global_load_dwordx2 v[44:45], v[42:43], off offset:1536
	global_load_dwordx2 v[54:55], v[2:3], off
	global_load_dwordx2 v[52:53], v[2:3], off offset:512
	global_load_dwordx2 v[50:51], v[2:3], off offset:1024
	global_load_dwordx2 v[48:49], v[2:3], off offset:1536
	s_nop 0
	global_load_dwordx4 v[2:5], v1, s[0:1]
	global_load_dwordx4 v[10:13], v1, s[0:1] offset:3072
	global_load_dwordx4 v[154:157], v130, s[14:15]
	global_load_dwordx4 v[158:161], v[30:31], off
	global_load_dwordx4 v[162:165], v130, s[16:17]
	s_waitcnt vmcnt(37)
	v_pk_mul_f32 v[62:63], v[136:137], v[6:7]
	v_pk_mul_f32 v[68:69], v[134:135], v[8:9]
	s_waitcnt vmcnt(34)
	v_pk_add_f32 v[6:7], v[148:149], 1.0 op_sel_hi:[1,0]
	v_pk_add_f32 v[8:9], v[146:147], 1.0 op_sel_hi:[1,0]
	s_waitcnt vmcnt(33)
	v_pk_mul_f32 v[60:61], v[152:153], v[6:7]
	v_pk_mul_f32 v[64:65], v[150:151], v[8:9]
	global_load_dwordx4 v[14:17], v1, s[0:1] offset:1024
	global_load_dwordx4 v[6:9], v1, s[0:1] offset:2048
	global_load_dwordx4 v[134:137], v[32:33], off
	v_pk_mul_f32 v[84:85], v[84:85], v[80:81]
	v_pk_mul_f32 v[86:87], v[82:83], v[78:79]
	v_pk_mul_f32 v[78:79], v[144:145], v[140:141]
	v_pk_mul_f32 v[80:81], v[142:143], v[138:139]
	s_waitcnt vmcnt(35)
	v_and_b32_e32 v139, 0xffff0000, v92
	v_and_b32_e32 v141, 0xffff0000, v93
	v_lshlrev_b32_e32 v138, 16, v92
	v_lshlrev_b32_e32 v140, 16, v93
	v_mul_f32_e32 v82, v141, v141
	s_waitcnt vmcnt(34)
	v_and_b32_e32 v145, 0xffff0000, v167
	v_and_b32_e32 v144, 0xffff0000, v166
	v_mul_f32_e32 v90, v139, v139
	v_pk_fma_f32 v[82:83], v[140:141], v[140:141], v[82:83] op_sel_hi:[1,1,0]
	v_lshlrev_b32_e32 v143, 16, v167
	v_lshlrev_b32_e32 v142, 16, v166
	v_pk_mul_f32 v[88:89], v[144:145], v[144:145]
	s_waitcnt vmcnt(32)
	v_lshlrev_b32_e32 v151, 16, v170
	v_pk_fma_f32 v[90:91], v[138:139], v[138:139], v[90:91] op_sel_hi:[1,1,0]
	v_pk_fma_f32 v[88:89], v[142:143], v[142:143], v[88:89]
	v_and_b32_e32 v153, 0xffff0000, v170
	v_mov_b32_e32 v150, v90
	v_mov_b32_e32 v92, v82
	v_mov_b32_e32 v93, v151
	v_mul_f32_e32 v133, v153, v153
	v_pk_add_f32 v[82:83], v[90:91], v[82:83]
	v_pk_mul_f32 v[90:91], v[150:151], v[92:93]
	v_pk_add_f32 v[88:89], v[88:89], v[88:89] op_sel:[0,1] op_sel_hi:[1,0]
	v_and_b32_e32 v147, 0xffff0000, v168
	v_and_b32_e32 v149, 0xffff0000, v169
	v_mov_b32_e32 v83, v91
	v_mov_b32_e32 v89, v133
	v_lshlrev_b32_e32 v146, 16, v168
	v_lshlrev_b32_e32 v148, 16, v169
	v_lshlrev_b32_e32 v166, 16, v171
	v_and_b32_e32 v167, 0xffff0000, v171
	v_pk_add_f32 v[82:83], v[82:83], v[88:89]
	v_mul_f32_e32 v88, v147, v147
	v_mul_f32_e32 v90, v149, v149
	v_mul_f32_e32 v152, v166, v166
	v_mul_f32_e32 v168, v167, v167
	v_pk_fma_f32 v[88:89], v[146:147], v[146:147], v[88:89] op_sel_hi:[1,1,0]
	v_pk_fma_f32 v[90:91], v[148:149], v[148:149], v[90:91] op_sel_hi:[1,1,0]
	v_mov_b32_e32 v89, v152
	v_mov_b32_e32 v91, v168
	v_pk_add_f32 v[88:89], v[88:89], v[90:91]
	s_waitcnt vmcnt(4)
	v_pk_mul_f32 v[92:93], v[154:155], v[158:159]
	v_pk_add_f32 v[82:83], v[82:83], v[88:89]
	v_pk_mul_f32 v[90:91], v[156:157], v[160:161]
	v_add_f32_e32 v82, v82, v83
	s_nop 1
	v_add_f32_dpp v82, v82, v82 quad_perm:[1,0,3,2] row_mask:0xf bank_mask:0xf bound_ctrl:1
	s_nop 1
	v_add_f32_dpp v82, v82, v82 quad_perm:[2,3,0,1] row_mask:0xf bank_mask:0xf bound_ctrl:1
	s_nop 1
	v_add_f32_dpp v82, v82, v82 row_half_mirror row_mask:0xf bank_mask:0xf bound_ctrl:1
	s_nop 1
	v_add_f32_dpp v82, v82, v82 row_mirror row_mask:0xf bank_mask:0xf bound_ctrl:1
	s_nop 0
	v_readlane_b32 s14, v82, 16
	v_readlane_b32 s15, v82, 48
	v_readlane_b32 s0, v82, 0
	v_readlane_b32 s1, v82, 32
	v_mov_b32_e32 v82, s14
	v_mov_b32_e32 v83, s15
	v_pk_add_f32 v[82:83], s[0:1], v[82:83]
	s_nop 0
	v_add_f32_e32 v82, v82, v83
	v_fmamk_f32 v82, v82, 0x3a800000, v131
	v_mul_f32_e32 v83, 0x4f800000, v82
	v_cmp_gt_f32_e32 vcc, s24, v82
	s_nop 1
	v_cndmask_b32_e32 v88, v82, v83, vcc
	v_sqrt_f32_e32 v89, v88
	s_waitcnt vmcnt(3)
	v_pk_add_f32 v[82:83], v[164:165], 1.0 op_sel_hi:[1,0]
	v_add_u32_e32 v133, -1, v89
	v_fma_f32 v150, -v133, v89, v88
	v_cmp_ge_f32_e64 s[0:1], 0, v150
	v_add_u32_e32 v150, 1, v89
	s_waitcnt vmcnt(0)
	v_pk_mul_f32 v[82:83], v[136:137], v[82:83]
	v_cndmask_b32_e64 v133, v89, v133, s[0:1]
	v_fma_f32 v89, -v150, v89, v88
	v_cmp_lt_f32_e64 s[0:1], 0, v89
	s_nop 1
	v_cndmask_b32_e64 v89, v133, v150, s[0:1]
	v_mul_f32_e32 v133, 0x37800000, v89
	v_cndmask_b32_e32 v89, v89, v133, vcc
	v_cmp_class_f32_e32 vcc, v88, v132
	s_nop 1
	v_cndmask_b32_e32 v133, v89, v88, vcc
	v_div_scale_f32 v150, s[0:1], v133, v133, 1.0
	v_rcp_f32_e32 v152, v150
	v_pk_add_f32 v[88:89], v[162:163], 1.0 op_sel_hi:[1,0]
	s_nop 0
	v_pk_mul_f32 v[88:89], v[134:135], v[88:89]
	v_fma_f32 v134, -v150, v152, 1.0
	v_fmac_f32_e32 v152, v134, v152
	v_div_scale_f32 v134, vcc, 1.0, v133, 1.0
	v_mul_f32_e32 v135, v134, v152
	v_fma_f32 v136, -v150, v135, v134
	v_fmac_f32_e32 v135, v136, v152
	v_fma_f32 v134, -v150, v135, v134
	v_div_fmas_f32 v134, v134, v152, v135
	v_div_fixup_f32 v134, v134, v133, 1.0
	v_pk_mul_f32 v[136:137], v[134:135], v[138:139] op_sel_hi:[0,1]
	v_pk_mul_f32 v[138:139], v[134:135], v[140:141] op_sel_hi:[0,1]
	v_pk_fma_f32 v[138:139], v[74:75], v[138:139], v[174:175]
	v_pk_fma_f32 v[136:137], v[76:77], v[136:137], v[172:173]
	v_cvt_pk_bf16_f32 v141, v138, v139
	v_cvt_pk_bf16_f32 v140, v136, v137
	global_store_dwordx2 v[40:41], v[140:141], off nt
	v_mov_b32_e32 v140, v142
	v_mov_b32_e32 v141, v144
	v_mov_b32_e32 v144, v143
	v_pk_mul_f32 v[140:141], v[134:135], v[140:141] op_sel_hi:[0,1]
	v_pk_mul_f32 v[142:143], v[134:135], v[144:145] op_sel_hi:[0,1]
	v_pk_fma_f32 v[142:143], v[84:85], v[142:143], v[178:179]
	v_pk_fma_f32 v[140:141], v[86:87], v[140:141], v[176:177]
	v_cvt_pk_bf16_f32 v145, v142, v143
	v_cvt_pk_bf16_f32 v144, v140, v141
	v_mov_b32_e32 v152, v151
	global_store_dwordx2 v[40:41], v[144:145], off offset:512 nt
	v_pk_mul_f32 v[144:145], v[134:135], v[146:147] op_sel_hi:[0,1]
	v_pk_mul_f32 v[146:147], v[134:135], v[148:149] op_sel_hi:[0,1]
	v_pk_mul_f32 v[148:149], v[152:153], v[134:135] op_sel_hi:[1,0]
	v_pk_mul_f32 v[150:151], v[138:139], v[138:139]
	v_pk_mul_f32 v[152:153], v[136:137], v[136:137]
	v_pk_fma_f32 v[144:145], v[80:81], v[144:145], v[180:181]
	v_pk_mov_b32 v[154:155], v[152:153], v[150:151] op_sel:[1,0]
	v_mov_b32_e32 v153, v151
	v_pk_add_f32 v[150:151], v[154:155], v[152:153]
	v_pk_mul_f32 v[152:153], v[142:143], v[142:143]
	v_pk_add_f32 v[150:151], v[150:151], v[150:151] op_sel_hi:[0,1]
	v_pk_mul_f32 v[154:155], v[140:141], v[140:141]
	v_pk_fma_f32 v[146:147], v[78:79], v[146:147], v[182:183]
	v_pk_mov_b32 v[156:157], v[154:155], v[152:153] op_sel:[1,0]
	v_mov_b32_e32 v155, v153
	v_mul_f32_e32 v150, v144, v144
	v_pk_mul_f32 v[134:135], v[166:167], v[134:135] op_sel_hi:[1,0]
	v_pk_add_f32 v[152:153], v[156:157], v[154:155]
	v_pk_fma_f32 v[154:155], v[144:145], v[144:145], v[150:151] op_sel_hi:[1,1,0]
	v_mul_f32_e32 v150, v146, v146
	v_pk_fma_f32 v[134:135], v[90:91], v[134:135], v[186:187]
	v_pk_fma_f32 v[148:149], v[92:93], v[148:149], v[184:185]
	v_pk_add_f32 v[152:153], v[152:153], v[152:153] op_sel_hi:[0,1]
	v_pk_fma_f32 v[156:157], v[146:147], v[146:147], v[150:151] op_sel_hi:[1,1,0]
	v_mul_f32_e32 v154, v148, v148
	v_mul_f32_e32 v156, v149, v149
	v_mul_f32_e32 v150, v134, v134
	v_mul_f32_e32 v152, v135, v135
	v_pk_add_f32 v[154:155], v[154:155], v[156:157]
	v_pk_add_f32 v[150:151], v[150:151], v[152:153]
	s_nop 0
	v_pk_add_f32 v[150:151], v[154:155], v[150:151]
	s_nop 0
	v_add_f32_e32 v133, v150, v151
	s_nop 1
	v_add_f32_dpp v133, v133, v133 quad_perm:[1,0,3,2] row_mask:0xf bank_mask:0xf bound_ctrl:1
	s_nop 1
	v_add_f32_dpp v133, v133, v133 quad_perm:[2,3,0,1] row_mask:0xf bank_mask:0xf bound_ctrl:1
	s_nop 1
	v_add_f32_dpp v133, v133, v133 row_half_mirror row_mask:0xf bank_mask:0xf bound_ctrl:1
	s_nop 1
	v_add_f32_dpp v133, v133, v133 row_mirror row_mask:0xf bank_mask:0xf bound_ctrl:1
	s_nop 0
	v_readlane_b32 s14, v133, 16
	v_readlane_b32 s15, v133, 48
	v_readlane_b32 s0, v133, 0
	v_readlane_b32 s1, v133, 32
	v_mov_b32_e32 v150, s14
	v_mov_b32_e32 v151, s15
	v_pk_add_f32 v[150:151], s[0:1], v[150:151]
	s_nop 0
	v_add_f32_e32 v133, v150, v151
	v_fmamk_f32 v133, v133, 0x3a800000, v131
	v_mul_f32_e32 v150, 0x4f800000, v133
	v_cmp_gt_f32_e32 vcc, s24, v133
	v_cvt_pk_bf16_f32 v151, v146, v147
	s_nop 0
	v_cndmask_b32_e32 v133, v133, v150, vcc
	v_sqrt_f32_e32 v152, v133
	v_cvt_pk_bf16_f32 v150, v144, v145
	global_store_dwordx2 v[40:41], v[150:151], off offset:1024 nt
	v_add_u32_e32 v150, -1, v152
	v_fma_f32 v151, -v150, v152, v133
	v_cmp_ge_f32_e64 s[0:1], 0, v151
	v_add_u32_e32 v151, 1, v152
	s_nop 0
	v_cndmask_b32_e64 v150, v152, v150, s[0:1]
	v_fma_f32 v152, -v151, v152, v133
	v_cmp_lt_f32_e64 s[0:1], 0, v152
	s_nop 1
	v_cndmask_b32_e64 v150, v150, v151, s[0:1]
	v_mul_f32_e32 v151, 0x37800000, v150
	v_cndmask_b32_e32 v150, v150, v151, vcc
	v_cmp_class_f32_e32 vcc, v133, v132
	v_cvt_pk_bf16_f32 v151, v134, v135
	s_nop 0
	v_cndmask_b32_e32 v133, v150, v133, vcc
	v_div_scale_f32 v152, s[0:1], v133, v133, 1.0
	v_rcp_f32_e32 v153, v152
	v_cvt_pk_bf16_f32 v150, v148, v149
	global_store_dwordx2 v[40:41], v[150:151], off offset:1536 nt
	s_lshr_b32 s0, s11, 18
	v_fma_f32 v150, -v152, v153, 1.0
	v_fmac_f32_e32 v153, v150, v153
	v_div_scale_f32 v150, vcc, 1.0, v133, 1.0
	v_mul_f32_e32 v151, v150, v153
	v_fma_f32 v154, -v152, v151, v150
	v_fmac_f32_e32 v151, v154, v153
	v_fma_f32 v150, -v152, v151, v150
	v_div_fmas_f32 v150, v150, v153, v151
	v_div_fixup_f32 v150, v150, v133, 1.0
	v_pk_mul_f32 v[136:137], v[136:137], v[150:151] op_sel_hi:[1,0]
	v_pk_mul_f32 v[138:139], v[138:139], v[150:151] op_sel_hi:[1,0]
	v_pk_fma_f32 v[136:137], v[70:71], v[136:137], v[2:3]
	v_pk_fma_f32 v[138:139], v[66:67], v[138:139], v[4:5]
	v_cvt_pk_bf16_f32 v136, v136, v137
	v_cvt_pk_bf16_f32 v137, v138, v139
	v_add_co_u32_e32 v138, vcc, s25, v40
	v_pk_mul_f32 v[134:135], v[134:135], v[150:151] op_sel_hi:[1,0]
	s_nop 0
	v_addc_co_u32_e32 v139, vcc, -1, v41, vcc
	global_store_dwordx2 v[138:139], v[136:137], off nt
	v_pk_mul_f32 v[136:137], v[140:141], v[150:151] op_sel_hi:[1,0]
	v_pk_mul_f32 v[138:139], v[142:143], v[150:151] op_sel_hi:[1,0]
	v_pk_fma_f32 v[136:137], v[68:69], v[136:137], v[14:15]
	v_pk_fma_f32 v[138:139], v[62:63], v[138:139], v[16:17]
	v_cvt_pk_bf16_f32 v136, v136, v137
	v_cvt_pk_bf16_f32 v137, v138, v139
	v_add_co_u32_e32 v138, vcc, s26, v40
	v_pk_mul_f32 v[140:141], v[146:147], v[150:151] op_sel_hi:[1,0]
	s_nop 0
	v_addc_co_u32_e32 v139, vcc, -1, v41, vcc
	global_store_dwordx2 v[138:139], v[136:137], off offset:-3584 nt
	v_pk_mul_f32 v[136:137], v[144:145], v[150:151] op_sel_hi:[1,0]
	v_pk_fma_f32 v[140:141], v[60:61], v[140:141], v[8:9]
	v_pk_fma_f32 v[136:137], v[64:65], v[136:137], v[6:7]
	s_add_i32 s0, s10, s0
	v_cvt_pk_bf16_f32 v136, v136, v137
	v_cvt_pk_bf16_f32 v137, v140, v141
	global_store_dwordx2 v[138:139], v[136:137], off offset:-3072 nt
	v_pk_mul_f32 v[136:137], v[148:149], v[150:151] op_sel_hi:[1,0]
	v_pk_fma_f32 v[134:135], v[82:83], v[134:135], v[12:13]
	v_pk_fma_f32 v[136:137], v[88:89], v[136:137], v[10:11]
	s_ashr_i32 s11, s0, 14
	v_cvt_pk_bf16_f32 v136, v136, v137
	v_cvt_pk_bf16_f32 v137, v134, v135
	s_cmp_eq_u32 s11, s27
	global_store_dwordx2 v[138:139], v[136:137], off offset:-2560 nt
	s_cbranch_scc1 .LBB0_1094
	s_mul_i32 s0, s11, 0xc00
	s_ashr_i32 s1, s0, 31
	s_lshl_b64 s[0:1], s[0:1], 2
	s_add_u32 s14, s18, s0
	s_addc_u32 s15, s19, s1
	s_add_u32 s16, s14, 0x2000
	s_addc_u32 s17, s15, 0
	s_add_u32 s0, s20, s0
	global_load_dwordx4 v[60:63], v1, s[16:17]
	global_load_dwordx4 v[64:67], v[18:19], off
	global_load_dwordx4 v[68:71], v128, s[16:17]
	global_load_dwordx4 v[78:81], v[22:23], off
	global_load_dwordx4 v[88:91], v129, s[16:17]
	global_load_dwordx4 v[134:137], v[26:27], off
	global_load_dwordx4 v[138:141], v130, s[16:17]
	global_load_dwordx4 v[142:145], v[30:31], off
	s_addc_u32 s1, s21, s1
	s_add_u32 s14, s0, 0x1000
	s_addc_u32 s15, s1, 0
	global_load_dwordx4 v[146:149], v1, s[14:15]
	global_load_dwordx4 v[150:153], v128, s[14:15]
	global_load_dwordx4 v[154:157], v129, s[14:15]
	global_load_dwordx4 v[158:161], v130, s[14:15]
	global_load_dwordx4 v[162:165], v[20:21], off
	global_load_dwordx4 v[166:169], v[24:25], off
	global_load_dwordx4 v[170:173], v[28:29], off
	global_load_dwordx4 v[174:177], v[32:33], off
	global_load_dwordx4 v[2:5], v1, s[0:1]
	global_load_dwordx4 v[14:17], v1, s[0:1] offset:1024
	global_load_dwordx4 v[6:9], v1, s[0:1] offset:2048
	global_load_dwordx4 v[10:13], v1, s[0:1] offset:3072
	s_mov_b32 s27, s11
	s_waitcnt vmcnt(18)
	v_pk_mul_f32 v[74:75], v[62:63], v[66:67]
	v_pk_mul_f32 v[76:77], v[60:61], v[64:65]
	s_waitcnt vmcnt(16)
	v_pk_mul_f32 v[84:85], v[70:71], v[80:81]
	v_pk_mul_f32 v[86:87], v[68:69], v[78:79]
	s_waitcnt vmcnt(14)
	v_pk_mul_f32 v[78:79], v[90:91], v[136:137]
	v_pk_mul_f32 v[80:81], v[88:89], v[134:135]
	s_waitcnt vmcnt(11)
	v_pk_add_f32 v[60:61], v[148:149], 1.0 op_sel_hi:[1,0]
	v_pk_add_f32 v[62:63], v[146:147], 1.0 op_sel_hi:[1,0]
	s_waitcnt vmcnt(10)
	v_pk_add_f32 v[64:65], v[152:153], 1.0 op_sel_hi:[1,0]
	v_pk_add_f32 v[68:69], v[150:151], 1.0 op_sel_hi:[1,0]
	s_waitcnt vmcnt(9)
	v_pk_add_f32 v[82:83], v[156:157], 1.0 op_sel_hi:[1,0]
	v_pk_add_f32 v[88:89], v[154:155], 1.0 op_sel_hi:[1,0]
	s_waitcnt vmcnt(8)
	v_pk_add_f32 v[134:135], v[160:161], 1.0 op_sel_hi:[1,0]
	v_pk_add_f32 v[136:137], v[158:159], 1.0 op_sel_hi:[1,0]
	v_pk_mul_f32 v[90:91], v[140:141], v[144:145]
	v_pk_mul_f32 v[92:93], v[138:139], v[142:143]
	s_waitcnt vmcnt(7)
	v_pk_mul_f32 v[66:67], v[164:165], v[60:61]
	v_pk_mul_f32 v[70:71], v[162:163], v[62:63]
	s_waitcnt vmcnt(6)
	v_pk_mul_f32 v[62:63], v[168:169], v[64:65]
	v_pk_mul_f32 v[68:69], v[166:167], v[68:69]
	s_waitcnt vmcnt(5)
	v_pk_mul_f32 v[60:61], v[172:173], v[82:83]
	v_pk_mul_f32 v[64:65], v[170:171], v[88:89]
	s_waitcnt vmcnt(4)
	v_pk_mul_f32 v[82:83], v[176:177], v[134:135]
	v_pk_mul_f32 v[88:89], v[174:175], v[136:137]
.LBB0_1094:
	v_lshlrev_b32_e32 v140, 16, v122
	v_and_b32_e32 v141, 0xffff0000, v122
	v_lshlrev_b32_e32 v122, 16, v123
	v_and_b32_e32 v123, 0xffff0000, v123
	v_lshlrev_b32_e32 v138, 16, v114
	v_and_b32_e32 v139, 0xffff0000, v114
	v_mul_f32_e32 v114, v123, v123
	v_pk_fma_f32 v[142:143], v[122:123], v[122:123], v[114:115] op_sel_hi:[1,1,0]
	v_lshlrev_b32_e32 v145, 16, v121
	v_lshlrev_b32_e32 v144, 16, v120
	v_and_b32_e32 v121, 0xffff0000, v121
	v_and_b32_e32 v120, 0xffff0000, v120
	v_mul_f32_e32 v114, v141, v141
	v_pk_mul_f32 v[146:147], v[120:121], v[120:121]
	v_lshlrev_b32_e32 v151, 16, v116
	v_pk_fma_f32 v[154:155], v[140:141], v[140:141], v[114:115] op_sel_hi:[1,1,0]
	v_pk_fma_f32 v[146:147], v[144:145], v[144:145], v[146:147]
	v_and_b32_e32 v153, 0xffff0000, v116
	v_mov_b32_e32 v150, v154
	v_mov_b32_e32 v156, v142
	v_mov_b32_e32 v157, v151
	v_and_b32_e32 v149, 0xffff0000, v118
	v_mul_f32_e32 v133, v153, v153
	v_pk_add_f32 v[142:143], v[154:155], v[142:143]
	v_pk_mul_f32 v[154:155], v[150:151], v[156:157]
	v_pk_add_f32 v[146:147], v[146:147], v[146:147] op_sel:[0,1] op_sel_hi:[1,0]
	v_lshlrev_b32_e32 v148, 16, v118
	v_lshlrev_b32_e32 v118, 16, v119
	v_and_b32_e32 v119, 0xffff0000, v119
	v_mov_b32_e32 v143, v155
	v_mov_b32_e32 v147, v133
	v_mul_f32_e32 v114, v149, v149
	v_lshlrev_b32_e32 v116, 16, v117
	v_and_b32_e32 v117, 0xffff0000, v117
	v_pk_add_f32 v[142:143], v[142:143], v[146:147]
	v_pk_fma_f32 v[146:147], v[148:149], v[148:149], v[114:115] op_sel_hi:[1,1,0]
	v_mul_f32_e32 v114, v119, v119
	v_mul_f32_e32 v152, v116, v116
	v_mul_f32_e32 v158, v117, v117
	v_pk_fma_f32 v[154:155], v[118:119], v[118:119], v[114:115] op_sel_hi:[1,1,0]
	v_mov_b32_e32 v147, v152
	v_mov_b32_e32 v155, v158
	v_pk_add_f32 v[146:147], v[146:147], v[154:155]
	v_lshlrev_b32_e32 v134, 16, v126
	v_pk_add_f32 v[142:143], v[142:143], v[146:147]
	v_and_b32_e32 v135, 0xffff0000, v126
	v_add_f32_e32 v114, v142, v143
	v_lshlrev_b32_e32 v126, 16, v127
	v_and_b32_e32 v127, 0xffff0000, v127
	v_add_f32_dpp v114, v114, v114 quad_perm:[1,0,3,2] row_mask:0xf bank_mask:0xf bound_ctrl:1
	v_lshlrev_b32_e32 v136, 16, v124
	v_and_b32_e32 v137, 0xffff0000, v124
	v_add_f32_dpp v114, v114, v114 quad_perm:[2,3,0,1] row_mask:0xf bank_mask:0xf bound_ctrl:1
	v_lshlrev_b32_e32 v124, 16, v125
	v_and_b32_e32 v125, 0xffff0000, v125
	v_add_f32_dpp v114, v114, v114 row_half_mirror row_mask:0xf bank_mask:0xf bound_ctrl:1
	s_nop 1
	v_add_f32_dpp v114, v114, v114 row_mirror row_mask:0xf bank_mask:0xf bound_ctrl:1
	s_nop 0
	v_readlane_b32 s11, v114, 16
	v_readlane_b32 s14, v114, 48
	v_readlane_b32 s0, v114, 0
	v_readlane_b32 s1, v114, 32
	v_mov_b32_e32 v142, s11
	v_mov_b32_e32 v143, s14
	v_pk_add_f32 v[142:143], s[0:1], v[142:143]
	s_nop 0
	v_add_f32_e32 v114, v142, v143
	v_fmamk_f32 v114, v114, 0x3a800000, v131
	v_mul_f32_e32 v133, 0x4f800000, v114
	v_cmp_gt_f32_e32 vcc, s24, v114
	v_lshlrev_b32_e32 v142, 16, v112
	s_nop 0
	v_cndmask_b32_e32 v133, v114, v133, vcc
	v_sqrt_f32_e32 v143, v133
	v_lshlrev_b32_e32 v114, 16, v115
	v_and_b32_e32 v115, 0xffff0000, v115
	v_add_u32_e32 v146, -1, v143
	v_fma_f32 v147, -v146, v143, v133
	v_cmp_ge_f32_e64 s[0:1], 0, v147
	v_add_u32_e32 v147, 1, v143
	s_nop 0
	v_cndmask_b32_e64 v146, v143, v146, s[0:1]
	v_fma_f32 v143, -v147, v143, v133
	v_cmp_lt_f32_e64 s[0:1], 0, v143
	s_nop 1
	v_cndmask_b32_e64 v143, v146, v147, s[0:1]
	v_mul_f32_e32 v146, 0x37800000, v143
	v_cndmask_b32_e32 v143, v143, v146, vcc
	v_cmp_class_f32_e32 vcc, v133, v132
	s_nop 1
	v_cndmask_b32_e32 v133, v143, v133, vcc
	v_div_scale_f32 v146, s[0:1], v133, v133, 1.0
	v_rcp_f32_e32 v147, v146
	v_and_b32_e32 v143, 0xffff0000, v112
	v_lshlrev_b32_e32 v112, 16, v113
	v_and_b32_e32 v113, 0xffff0000, v113
	v_fma_f32 v150, -v146, v147, 1.0
	v_fmac_f32_e32 v147, v150, v147
	v_div_scale_f32 v150, vcc, 1.0, v133, 1.0
	v_mul_f32_e32 v152, v150, v147
	v_fma_f32 v154, -v146, v152, v150
	v_fmac_f32_e32 v152, v154, v147
	v_fma_f32 v146, -v146, v152, v150
	v_div_fmas_f32 v146, v146, v147, v152
	v_div_fixup_f32 v146, v146, v133, 1.0
	v_pk_mul_f32 v[140:141], v[146:147], v[140:141] op_sel_hi:[0,1]
	v_pk_mul_f32 v[122:123], v[146:147], v[122:123] op_sel_hi:[0,1]
	v_pk_fma_f32 v[122:123], v[74:75], v[122:123], v[126:127]
	v_pk_fma_f32 v[126:127], v[76:77], v[140:141], v[134:135]
	v_cvt_pk_bf16_f32 v135, v122, v123
	v_cvt_pk_bf16_f32 v134, v126, v127
	global_store_dwordx2 v[110:111], v[134:135], off nt
	v_mov_b32_e32 v134, v144
	v_mov_b32_e32 v135, v120
	v_mov_b32_e32 v120, v145
	v_pk_mul_f32 v[134:135], v[146:147], v[134:135] op_sel_hi:[0,1]
	v_pk_mul_f32 v[120:121], v[146:147], v[120:121] op_sel_hi:[0,1]
	v_pk_fma_f32 v[120:121], v[84:85], v[120:121], v[124:125]
	v_pk_fma_f32 v[124:125], v[86:87], v[134:135], v[136:137]
	v_cvt_pk_bf16_f32 v135, v120, v121
	v_cvt_pk_bf16_f32 v134, v124, v125
	global_store_dwordx2 v[110:111], v[134:135], off offset:512 nt
	v_pk_mul_f32 v[134:135], v[146:147], v[148:149] op_sel_hi:[0,1]
	v_pk_mul_f32 v[118:119], v[146:147], v[118:119] op_sel_hi:[0,1]
	v_mov_b32_e32 v152, v151
	v_pk_fma_f32 v[114:115], v[78:79], v[118:119], v[114:115]
	v_pk_fma_f32 v[118:119], v[80:81], v[134:135], v[138:139]
	v_pk_mul_f32 v[134:135], v[152:153], v[146:147] op_sel_hi:[1,0]
	v_pk_mul_f32 v[116:117], v[116:117], v[146:147] op_sel_hi:[1,0]
	v_pk_mul_f32 v[136:137], v[126:127], v[126:127]
	v_pk_fma_f32 v[112:113], v[90:91], v[116:117], v[112:113]
	v_pk_fma_f32 v[116:117], v[92:93], v[134:135], v[142:143]
	v_pk_mul_f32 v[134:135], v[122:123], v[122:123]
	s_nop 0
	v_pk_mov_b32 v[138:139], v[136:137], v[134:135] op_sel:[1,0]
	v_mov_b32_e32 v137, v135
	v_pk_add_f32 v[134:135], v[138:139], v[136:137]
	v_pk_mul_f32 v[136:137], v[120:121], v[120:121]
	v_pk_add_f32 v[134:135], v[134:135], v[134:135] op_sel_hi:[0,1]
	v_pk_mul_f32 v[138:139], v[124:125], v[124:125]
	v_mul_f32_e32 v134, v118, v118
	v_pk_mov_b32 v[140:141], v[138:139], v[136:137] op_sel:[1,0]
	v_mov_b32_e32 v139, v137
	v_pk_add_f32 v[136:137], v[140:141], v[138:139]
	v_pk_fma_f32 v[138:139], v[118:119], v[118:119], v[134:135] op_sel_hi:[1,1,0]
	v_mul_f32_e32 v134, v114, v114
	v_pk_add_f32 v[136:137], v[136:137], v[136:137] op_sel_hi:[0,1]
	v_pk_fma_f32 v[140:141], v[114:115], v[114:115], v[134:135] op_sel_hi:[1,1,0]
	v_mul_f32_e32 v138, v116, v116
	v_mul_f32_e32 v140, v117, v117
	v_mul_f32_e32 v134, v112, v112
	v_mul_f32_e32 v136, v113, v113
	v_pk_add_f32 v[138:139], v[138:139], v[140:141]
	v_pk_add_f32 v[134:135], v[134:135], v[136:137]
	s_nop 0
	v_pk_add_f32 v[134:135], v[138:139], v[134:135]
	s_nop 0
	v_add_f32_e32 v133, v134, v135
	s_nop 1
	v_add_f32_dpp v133, v133, v133 quad_perm:[1,0,3,2] row_mask:0xf bank_mask:0xf bound_ctrl:1
	s_nop 1
	v_add_f32_dpp v133, v133, v133 quad_perm:[2,3,0,1] row_mask:0xf bank_mask:0xf bound_ctrl:1
	s_nop 1
	v_add_f32_dpp v133, v133, v133 row_half_mirror row_mask:0xf bank_mask:0xf bound_ctrl:1
	s_nop 1
	v_add_f32_dpp v133, v133, v133 row_mirror row_mask:0xf bank_mask:0xf bound_ctrl:1
	s_nop 0
	v_readlane_b32 s11, v133, 16
	v_readlane_b32 s14, v133, 48
	v_readlane_b32 s0, v133, 0
	v_readlane_b32 s1, v133, 32
	v_mov_b32_e32 v134, s11
	v_mov_b32_e32 v135, s14
	v_pk_add_f32 v[134:135], s[0:1], v[134:135]
	s_add_i32 s14, s3, s10
	v_add_f32_e32 v133, v134, v135
	v_fmamk_f32 v133, v133, 0x3a800000, v131
	v_mul_f32_e32 v134, 0x4f800000, v133
	v_cmp_gt_f32_e32 vcc, s24, v133
	v_cvt_pk_bf16_f32 v135, v114, v115
	s_nop 0
	v_cndmask_b32_e32 v133, v133, v134, vcc
	v_sqrt_f32_e32 v136, v133
	v_cvt_pk_bf16_f32 v134, v118, v119
	global_store_dwordx2 v[110:111], v[134:135], off offset:1024 nt
	v_add_u32_e32 v134, -1, v136
	v_fma_f32 v135, -v134, v136, v133
	v_cmp_ge_f32_e64 s[0:1], 0, v135
	v_add_u32_e32 v135, 1, v136
	s_nop 0
	v_cndmask_b32_e64 v134, v136, v134, s[0:1]
	v_fma_f32 v136, -v135, v136, v133
	v_cmp_lt_f32_e64 s[0:1], 0, v136
	s_nop 1
	v_cndmask_b32_e64 v134, v134, v135, s[0:1]
	v_mul_f32_e32 v135, 0x37800000, v134
	v_cndmask_b32_e32 v134, v134, v135, vcc
	v_cmp_class_f32_e32 vcc, v133, v132
	v_cvt_pk_bf16_f32 v135, v112, v113
	s_nop 0
	v_cndmask_b32_e32 v133, v134, v133, vcc
	v_div_scale_f32 v136, s[0:1], v133, v133, 1.0
	v_rcp_f32_e32 v137, v136
	v_cvt_pk_bf16_f32 v134, v116, v117
	global_store_dwordx2 v[110:111], v[134:135], off offset:1536 nt
	s_ashr_i32 s0, s14, 31
	v_fma_f32 v110, -v136, v137, 1.0
	v_fmac_f32_e32 v137, v110, v137
	v_div_scale_f32 v110, vcc, 1.0, v133, 1.0
	v_mul_f32_e32 v111, v110, v137
	v_fma_f32 v134, -v136, v111, v110
	v_fmac_f32_e32 v111, v134, v137
	v_fma_f32 v110, -v136, v111, v110
	v_div_fmas_f32 v110, v110, v137, v111
	v_div_fixup_f32 v110, v110, v133, 1.0
	v_pk_mul_f32 v[118:119], v[118:119], v[110:111] op_sel_hi:[1,0]
	v_pk_mul_f32 v[114:115], v[114:115], v[110:111] op_sel_hi:[1,0]
	s_waitcnt vmcnt(5)
	v_pk_fma_f32 v[118:119], v[64:65], v[118:119], v[6:7]
	v_pk_fma_f32 v[114:115], v[60:61], v[114:115], v[8:9]
	s_lshr_b32 s0, s0, 18
	v_pk_mul_f32 v[126:127], v[126:127], v[110:111] op_sel_hi:[1,0]
	v_pk_mul_f32 v[122:123], v[122:123], v[110:111] op_sel_hi:[1,0]
	v_pk_mul_f32 v[124:125], v[124:125], v[110:111] op_sel_hi:[1,0]
	v_pk_mul_f32 v[120:121], v[120:121], v[110:111] op_sel_hi:[1,0]
	v_cvt_pk_bf16_f32 v118, v118, v119
	v_cvt_pk_bf16_f32 v119, v114, v115
	v_pk_mul_f32 v[114:115], v[116:117], v[110:111] op_sel_hi:[1,0]
	v_pk_mul_f32 v[110:111], v[112:113], v[110:111] op_sel_hi:[1,0]
	s_add_i32 s0, s14, s0
	v_pk_fma_f32 v[122:123], v[66:67], v[122:123], v[4:5]
	v_pk_fma_f32 v[126:127], v[70:71], v[126:127], v[2:3]
	v_pk_fma_f32 v[120:121], v[62:63], v[120:121], v[16:17]
	v_pk_fma_f32 v[124:125], v[68:69], v[124:125], v[14:15]
	s_waitcnt vmcnt(4)
	v_pk_fma_f32 v[110:111], v[82:83], v[110:111], v[12:13]
	v_pk_fma_f32 v[112:113], v[88:89], v[114:115], v[10:11]
	s_ashr_i32 s15, s0, 14
	v_cvt_pk_bf16_f32 v126, v126, v127
	v_cvt_pk_bf16_f32 v127, v122, v123
	v_lshl_add_u64 v[122:123], v[38:39], 0, s[12:13]
	v_cvt_pk_bf16_f32 v124, v124, v125
	v_cvt_pk_bf16_f32 v125, v120, v121
	v_cvt_pk_bf16_f32 v112, v112, v113
	v_cvt_pk_bf16_f32 v113, v110, v111
	s_cmp_eq_u32 s15, s27
	global_store_dwordx2 v[122:123], v[126:127], off nt
	global_store_dwordx2 v[122:123], v[124:125], off offset:512 nt
	global_store_dwordx2 v[122:123], v[118:119], off offset:1024 nt
	global_store_dwordx2 v[122:123], v[112:113], off offset:1536 nt
	s_cbranch_scc1 .LBB0_1096
	s_mul_i32 s0, s15, 0xc00
	s_ashr_i32 s1, s0, 31
	s_lshl_b64 s[0:1], s[0:1], 2
	s_add_u32 s10, s18, s0
	s_addc_u32 s11, s19, s1
	s_add_u32 s12, s10, 0x2000
	s_addc_u32 s13, s11, 0
	s_add_u32 s0, s20, s0
	global_load_dwordx4 v[60:63], v1, s[12:13]
	global_load_dwordx4 v[64:67], v[18:19], off
	global_load_dwordx4 v[68:71], v128, s[12:13]
	global_load_dwordx4 v[78:81], v[22:23], off
	global_load_dwordx4 v[88:91], v129, s[12:13]
	global_load_dwordx4 v[110:113], v[26:27], off
	global_load_dwordx4 v[114:117], v130, s[12:13]
	global_load_dwordx4 v[118:121], v[30:31], off
	s_addc_u32 s1, s21, s1
	s_add_u32 s10, s0, 0x1000
	s_addc_u32 s11, s1, 0
	global_load_dwordx4 v[122:125], v1, s[10:11]
	global_load_dwordx4 v[134:137], v128, s[10:11]
	global_load_dwordx4 v[138:141], v129, s[10:11]
	global_load_dwordx4 v[142:145], v130, s[10:11]
	global_load_dwordx4 v[146:149], v[20:21], off
	global_load_dwordx4 v[150:153], v[24:25], off
	global_load_dwordx4 v[154:157], v[28:29], off
	global_load_dwordx4 v[158:161], v[32:33], off
	global_load_dwordx4 v[2:5], v1, s[0:1]
	global_load_dwordx4 v[14:17], v1, s[0:1] offset:1024
	global_load_dwordx4 v[6:9], v1, s[0:1] offset:2048
	global_load_dwordx4 v[10:13], v1, s[0:1] offset:3072
	s_mov_b32 s27, s15
	s_waitcnt vmcnt(18)
	v_pk_mul_f32 v[74:75], v[62:63], v[66:67]
	v_pk_mul_f32 v[76:77], v[60:61], v[64:65]
	s_waitcnt vmcnt(16)
	v_pk_mul_f32 v[84:85], v[70:71], v[80:81]
	v_pk_mul_f32 v[86:87], v[68:69], v[78:79]
	s_waitcnt vmcnt(14)
	v_pk_mul_f32 v[78:79], v[90:91], v[112:113]
	v_pk_mul_f32 v[80:81], v[88:89], v[110:111]
	s_waitcnt vmcnt(11)
	v_pk_add_f32 v[60:61], v[124:125], 1.0 op_sel_hi:[1,0]
	v_pk_add_f32 v[62:63], v[122:123], 1.0 op_sel_hi:[1,0]
	s_waitcnt vmcnt(10)
	v_pk_add_f32 v[64:65], v[136:137], 1.0 op_sel_hi:[1,0]
	v_pk_add_f32 v[68:69], v[134:135], 1.0 op_sel_hi:[1,0]
	s_waitcnt vmcnt(9)
	v_pk_add_f32 v[82:83], v[140:141], 1.0 op_sel_hi:[1,0]
	v_pk_add_f32 v[88:89], v[138:139], 1.0 op_sel_hi:[1,0]
	s_waitcnt vmcnt(8)
	v_pk_add_f32 v[110:111], v[144:145], 1.0 op_sel_hi:[1,0]
	v_pk_add_f32 v[112:113], v[142:143], 1.0 op_sel_hi:[1,0]
	v_pk_mul_f32 v[90:91], v[116:117], v[120:121]
	v_pk_mul_f32 v[92:93], v[114:115], v[118:119]
	s_waitcnt vmcnt(7)
	v_pk_mul_f32 v[66:67], v[148:149], v[60:61]
	v_pk_mul_f32 v[70:71], v[146:147], v[62:63]
	s_waitcnt vmcnt(6)
	v_pk_mul_f32 v[62:63], v[152:153], v[64:65]
	v_pk_mul_f32 v[68:69], v[150:151], v[68:69]
	s_waitcnt vmcnt(5)
	v_pk_mul_f32 v[60:61], v[156:157], v[82:83]
	v_pk_mul_f32 v[64:65], v[154:155], v[88:89]
	s_waitcnt vmcnt(4)
	v_pk_mul_f32 v[82:83], v[160:161], v[110:111]
	v_pk_mul_f32 v[88:89], v[158:159], v[112:113]
.LBB0_1096:
	v_lshlrev_b32_e32 v116, 16, v104
	v_and_b32_e32 v117, 0xffff0000, v104
	v_lshlrev_b32_e32 v104, 16, v105
	v_and_b32_e32 v105, 0xffff0000, v105
	v_lshlrev_b32_e32 v114, 16, v96
	v_and_b32_e32 v115, 0xffff0000, v96
	v_mul_f32_e32 v96, v105, v105
	v_pk_fma_f32 v[118:119], v[104:105], v[104:105], v[96:97] op_sel_hi:[1,1,0]
	v_lshlrev_b32_e32 v121, 16, v103
	v_lshlrev_b32_e32 v120, 16, v102
	v_and_b32_e32 v103, 0xffff0000, v103
	v_and_b32_e32 v102, 0xffff0000, v102
	v_mul_f32_e32 v96, v117, v117
	v_pk_mul_f32 v[122:123], v[102:103], v[102:103]
	v_lshlrev_b32_e32 v127, 16, v98
	v_pk_fma_f32 v[136:137], v[116:117], v[116:117], v[96:97] op_sel_hi:[1,1,0]
	v_pk_fma_f32 v[122:123], v[120:121], v[120:121], v[122:123]
	v_and_b32_e32 v135, 0xffff0000, v98
	v_mov_b32_e32 v126, v136
	v_mov_b32_e32 v138, v118
	v_mov_b32_e32 v139, v127
	v_and_b32_e32 v125, 0xffff0000, v100
	v_mul_f32_e32 v133, v135, v135
	v_pk_add_f32 v[118:119], v[136:137], v[118:119]
	v_pk_mul_f32 v[136:137], v[126:127], v[138:139]
	v_pk_add_f32 v[122:123], v[122:123], v[122:123] op_sel:[0,1] op_sel_hi:[1,0]
	v_lshlrev_b32_e32 v124, 16, v100
	v_lshlrev_b32_e32 v100, 16, v101
	v_and_b32_e32 v101, 0xffff0000, v101
	v_mov_b32_e32 v119, v137
	v_mov_b32_e32 v123, v133
	v_mul_f32_e32 v96, v125, v125
	v_lshlrev_b32_e32 v98, 16, v99
	v_and_b32_e32 v99, 0xffff0000, v99
	v_pk_add_f32 v[118:119], v[118:119], v[122:123]
	v_pk_fma_f32 v[122:123], v[124:125], v[124:125], v[96:97] op_sel_hi:[1,1,0]
	v_mul_f32_e32 v96, v101, v101
	v_mul_f32_e32 v134, v98, v98
	v_mul_f32_e32 v140, v99, v99
	v_pk_fma_f32 v[136:137], v[100:101], v[100:101], v[96:97] op_sel_hi:[1,1,0]
	v_mov_b32_e32 v123, v134
	v_mov_b32_e32 v137, v140
	v_pk_add_f32 v[122:123], v[122:123], v[136:137]
	v_lshlrev_b32_e32 v110, 16, v108
	v_pk_add_f32 v[118:119], v[118:119], v[122:123]
	v_and_b32_e32 v111, 0xffff0000, v108
	v_add_f32_e32 v96, v118, v119
	v_lshlrev_b32_e32 v108, 16, v109
	v_and_b32_e32 v109, 0xffff0000, v109
	v_add_f32_dpp v96, v96, v96 quad_perm:[1,0,3,2] row_mask:0xf bank_mask:0xf bound_ctrl:1
	v_lshlrev_b32_e32 v112, 16, v106
	v_and_b32_e32 v113, 0xffff0000, v106
	v_add_f32_dpp v96, v96, v96 quad_perm:[2,3,0,1] row_mask:0xf bank_mask:0xf bound_ctrl:1
	v_lshlrev_b32_e32 v106, 16, v107
	v_and_b32_e32 v107, 0xffff0000, v107
	v_add_f32_dpp v96, v96, v96 row_half_mirror row_mask:0xf bank_mask:0xf bound_ctrl:1
	s_add_i32 s12, s3, s14
	s_nop 0
	v_add_f32_dpp v96, v96, v96 row_mirror row_mask:0xf bank_mask:0xf bound_ctrl:1
	s_nop 0
	v_readlane_b32 s10, v96, 16
	v_readlane_b32 s11, v96, 48
	v_readlane_b32 s0, v96, 0
	v_readlane_b32 s1, v96, 32
	v_mov_b32_e32 v118, s10
	v_mov_b32_e32 v119, s11
	v_pk_add_f32 v[118:119], s[0:1], v[118:119]
	s_nop 0
	v_add_f32_e32 v96, v118, v119
	v_fmamk_f32 v96, v96, 0x3a800000, v131
	v_mul_f32_e32 v118, 0x4f800000, v96
	v_cmp_gt_f32_e32 vcc, s24, v96
	s_nop 1
	v_cndmask_b32_e32 v119, v96, v118, vcc
	v_sqrt_f32_e32 v122, v119
	v_lshlrev_b32_e32 v96, 16, v97
	v_and_b32_e32 v97, 0xffff0000, v97
	v_lshlrev_b32_e32 v118, 16, v94
	v_add_u32_e32 v123, -1, v122
	v_fma_f32 v126, -v123, v122, v119
	v_cmp_ge_f32_e64 s[0:1], 0, v126
	v_add_u32_e32 v126, 1, v122
	s_nop 0
	v_cndmask_b32_e64 v123, v122, v123, s[0:1]
	v_fma_f32 v122, -v126, v122, v119
	v_cmp_lt_f32_e64 s[0:1], 0, v122
	s_nop 1
	v_cndmask_b32_e64 v122, v123, v126, s[0:1]
	v_mul_f32_e32 v123, 0x37800000, v122
	v_cndmask_b32_e32 v122, v122, v123, vcc
	v_cmp_class_f32_e32 vcc, v119, v132
	s_nop 1
	v_cndmask_b32_e32 v122, v122, v119, vcc
	v_div_scale_f32 v123, s[0:1], v122, v122, 1.0
	v_rcp_f32_e32 v126, v123
	v_and_b32_e32 v119, 0xffff0000, v94
	v_lshlrev_b32_e32 v94, 16, v95
	v_and_b32_e32 v95, 0xffff0000, v95
	v_fma_f32 v133, -v123, v126, 1.0
	v_fmac_f32_e32 v126, v133, v126
	v_div_scale_f32 v133, vcc, 1.0, v122, 1.0
	v_mul_f32_e32 v134, v133, v126
	v_fma_f32 v136, -v123, v134, v133
	v_fmac_f32_e32 v134, v136, v126
	v_fma_f32 v123, -v123, v134, v133
	v_div_fmas_f32 v123, v123, v126, v134
	v_div_fixup_f32 v122, v123, v122, 1.0
	v_pk_mul_f32 v[116:117], v[122:123], v[116:117] op_sel_hi:[0,1]
	v_pk_mul_f32 v[104:105], v[122:123], v[104:105] op_sel_hi:[0,1]
	v_pk_fma_f32 v[104:105], v[74:75], v[104:105], v[108:109]
	v_pk_fma_f32 v[108:109], v[76:77], v[116:117], v[110:111]
	v_cvt_pk_bf16_f32 v111, v104, v105
	v_cvt_pk_bf16_f32 v110, v108, v109
	global_store_dwordx2 v[72:73], v[110:111], off nt
	v_mov_b32_e32 v110, v120
	v_mov_b32_e32 v111, v102
	v_mov_b32_e32 v102, v121
	v_pk_mul_f32 v[110:111], v[122:123], v[110:111] op_sel_hi:[0,1]
	v_pk_mul_f32 v[102:103], v[122:123], v[102:103] op_sel_hi:[0,1]
	v_pk_fma_f32 v[102:103], v[84:85], v[102:103], v[106:107]
	v_pk_fma_f32 v[106:107], v[86:87], v[110:111], v[112:113]
	v_cvt_pk_bf16_f32 v111, v102, v103
	v_cvt_pk_bf16_f32 v110, v106, v107
	global_store_dwordx2 v[72:73], v[110:111], off offset:512 nt
	v_pk_mul_f32 v[110:111], v[122:123], v[124:125] op_sel_hi:[0,1]
	v_pk_mul_f32 v[100:101], v[122:123], v[100:101] op_sel_hi:[0,1]
	v_mov_b32_e32 v134, v127
	v_pk_fma_f32 v[96:97], v[78:79], v[100:101], v[96:97]
	v_pk_fma_f32 v[100:101], v[80:81], v[110:111], v[114:115]
	v_pk_mul_f32 v[110:111], v[134:135], v[122:123] op_sel_hi:[1,0]
	v_pk_mul_f32 v[98:99], v[98:99], v[122:123] op_sel_hi:[1,0]
	v_pk_mul_f32 v[112:113], v[108:109], v[108:109]
	v_pk_fma_f32 v[94:95], v[90:91], v[98:99], v[94:95]
	v_pk_fma_f32 v[98:99], v[92:93], v[110:111], v[118:119]
	v_pk_mul_f32 v[110:111], v[104:105], v[104:105]
	s_nop 0
	v_pk_mov_b32 v[114:115], v[112:113], v[110:111] op_sel:[1,0]
	v_mov_b32_e32 v113, v111
	v_pk_add_f32 v[110:111], v[114:115], v[112:113]
	v_pk_mul_f32 v[112:113], v[102:103], v[102:103]
	v_pk_add_f32 v[110:111], v[110:111], v[110:111] op_sel_hi:[0,1]
	v_pk_mul_f32 v[114:115], v[106:107], v[106:107]
	v_mul_f32_e32 v110, v100, v100
	v_pk_mov_b32 v[116:117], v[114:115], v[112:113] op_sel:[1,0]
	v_mov_b32_e32 v115, v113
	v_pk_add_f32 v[112:113], v[116:117], v[114:115]
	v_pk_fma_f32 v[114:115], v[100:101], v[100:101], v[110:111] op_sel_hi:[1,1,0]
	v_mul_f32_e32 v110, v96, v96
	v_pk_add_f32 v[112:113], v[112:113], v[112:113] op_sel_hi:[0,1]
	v_pk_fma_f32 v[116:117], v[96:97], v[96:97], v[110:111] op_sel_hi:[1,1,0]
	v_mul_f32_e32 v114, v98, v98
	v_mul_f32_e32 v116, v99, v99
	v_mul_f32_e32 v110, v94, v94
	v_mul_f32_e32 v112, v95, v95
	v_pk_add_f32 v[114:115], v[114:115], v[116:117]
	v_pk_add_f32 v[110:111], v[110:111], v[112:113]
	s_nop 0
	v_pk_add_f32 v[110:111], v[114:115], v[110:111]
	s_nop 0
	v_add_f32_e32 v110, v110, v111
	s_nop 1
	v_add_f32_dpp v110, v110, v110 quad_perm:[1,0,3,2] row_mask:0xf bank_mask:0xf bound_ctrl:1
	s_nop 1
	v_add_f32_dpp v110, v110, v110 quad_perm:[2,3,0,1] row_mask:0xf bank_mask:0xf bound_ctrl:1
	s_nop 1
	v_add_f32_dpp v110, v110, v110 row_half_mirror row_mask:0xf bank_mask:0xf bound_ctrl:1
	s_nop 1
	v_add_f32_dpp v110, v110, v110 row_mirror row_mask:0xf bank_mask:0xf bound_ctrl:1
	s_nop 0
	v_readlane_b32 s10, v110, 16
	v_readlane_b32 s11, v110, 48
	v_readlane_b32 s0, v110, 0
	v_readlane_b32 s1, v110, 32
	v_mov_b32_e32 v110, s10
	v_mov_b32_e32 v111, s11
	v_pk_add_f32 v[110:111], s[0:1], v[110:111]
	s_nop 0
	v_add_f32_e32 v110, v110, v111
	v_fmamk_f32 v110, v110, 0x3a800000, v131
	v_mul_f32_e32 v111, 0x4f800000, v110
	v_cmp_gt_f32_e32 vcc, s24, v110
	s_nop 1
	v_cndmask_b32_e32 v112, v110, v111, vcc
	v_sqrt_f32_e32 v113, v112
	v_cvt_pk_bf16_f32 v110, v100, v101
	v_cvt_pk_bf16_f32 v111, v96, v97
	global_store_dwordx2 v[72:73], v[110:111], off offset:1024 nt
	v_add_u32_e32 v110, -1, v113
	v_fma_f32 v111, -v110, v113, v112
	v_cmp_ge_f32_e64 s[0:1], 0, v111
	v_add_u32_e32 v111, 1, v113
	s_nop 0
	v_cndmask_b32_e64 v110, v113, v110, s[0:1]
	v_fma_f32 v113, -v111, v113, v112
	v_cmp_lt_f32_e64 s[0:1], 0, v113
	s_nop 1
	v_cndmask_b32_e64 v110, v110, v111, s[0:1]
	v_mul_f32_e32 v111, 0x37800000, v110
	v_cndmask_b32_e32 v110, v110, v111, vcc
	v_cmp_class_f32_e32 vcc, v112, v132
	v_cvt_pk_bf16_f32 v111, v94, v95
	s_nop 0
	v_cndmask_b32_e32 v112, v110, v112, vcc
	v_div_scale_f32 v113, s[0:1], v112, v112, 1.0
	v_rcp_f32_e32 v114, v113
	v_cvt_pk_bf16_f32 v110, v98, v99
	global_store_dwordx2 v[72:73], v[110:111], off offset:1536 nt
	s_ashr_i32 s0, s12, 31
	v_fma_f32 v72, -v113, v114, 1.0
	v_fmac_f32_e32 v114, v72, v114
	v_div_scale_f32 v72, vcc, 1.0, v112, 1.0
	v_mul_f32_e32 v73, v72, v114
	v_fma_f32 v110, -v113, v73, v72
	v_fmac_f32_e32 v73, v110, v114
	v_fma_f32 v72, -v113, v73, v72
	v_div_fmas_f32 v72, v72, v114, v73
	v_div_fixup_f32 v72, v72, v112, 1.0
	v_pk_mul_f32 v[100:101], v[100:101], v[72:73] op_sel_hi:[1,0]
	v_pk_mul_f32 v[96:97], v[96:97], v[72:73] op_sel_hi:[1,0]
	s_waitcnt vmcnt(5)
	v_pk_fma_f32 v[100:101], v[64:65], v[100:101], v[6:7]
	v_pk_fma_f32 v[96:97], v[60:61], v[96:97], v[8:9]
	s_lshr_b32 s0, s0, 18
	v_pk_mul_f32 v[108:109], v[108:109], v[72:73] op_sel_hi:[1,0]
	v_pk_mul_f32 v[104:105], v[104:105], v[72:73] op_sel_hi:[1,0]
	v_pk_mul_f32 v[106:107], v[106:107], v[72:73] op_sel_hi:[1,0]
	v_pk_mul_f32 v[102:103], v[102:103], v[72:73] op_sel_hi:[1,0]
	v_cvt_pk_bf16_f32 v100, v100, v101
	v_cvt_pk_bf16_f32 v101, v96, v97
	v_pk_mul_f32 v[96:97], v[98:99], v[72:73] op_sel_hi:[1,0]
	v_pk_mul_f32 v[72:73], v[94:95], v[72:73] op_sel_hi:[1,0]
	s_add_i32 s0, s12, s0
	v_pk_fma_f32 v[104:105], v[66:67], v[104:105], v[4:5]
	v_pk_fma_f32 v[108:109], v[70:71], v[108:109], v[2:3]
	v_pk_fma_f32 v[102:103], v[62:63], v[102:103], v[16:17]
	v_pk_fma_f32 v[106:107], v[68:69], v[106:107], v[14:15]
	s_waitcnt vmcnt(4)
	v_pk_fma_f32 v[72:73], v[82:83], v[72:73], v[12:13]
	v_pk_fma_f32 v[94:95], v[88:89], v[96:97], v[10:11]
	s_ashr_i32 s0, s0, 14
	v_cvt_pk_bf16_f32 v108, v108, v109
	v_cvt_pk_bf16_f32 v109, v104, v105
	v_lshl_add_u64 v[104:105], v[38:39], 0, s[8:9]
	v_cvt_pk_bf16_f32 v106, v106, v107
	v_cvt_pk_bf16_f32 v107, v102, v103
	v_cvt_pk_bf16_f32 v94, v94, v95
	v_cvt_pk_bf16_f32 v95, v72, v73
	s_cmp_eq_u32 s0, s27
	global_store_dwordx2 v[104:105], v[108:109], off nt
	global_store_dwordx2 v[104:105], v[106:107], off offset:512 nt
	global_store_dwordx2 v[104:105], v[100:101], off offset:1024 nt
	global_store_dwordx2 v[104:105], v[94:95], off offset:1536 nt
	s_cbranch_scc1 .LBB0_1091
	s_mulk_i32 s0, 0xc00
	s_ashr_i32 s1, s0, 31
	s_lshl_b64 s[0:1], s[0:1], 2
	s_add_u32 s8, s18, s0
	s_addc_u32 s9, s19, s1
	s_add_u32 s10, s8, 0x2000
	s_addc_u32 s11, s9, 0
	global_load_dwordx4 v[60:63], v1, s[10:11]
	global_load_dwordx4 v[64:67], v[18:19], off
	global_load_dwordx4 v[68:71], v128, s[10:11]
	global_load_dwordx4 v[78:81], v[22:23], off
	global_load_dwordx4 v[88:91], v129, s[10:11]
	global_load_dwordx4 v[92:95], v[26:27], off
	global_load_dwordx4 v[96:99], v130, s[10:11]
	global_load_dwordx4 v[100:103], v[30:31], off
	s_add_u32 s0, s20, s0
	s_addc_u32 s1, s21, s1
	s_add_u32 s8, s0, 0x1000
	s_addc_u32 s9, s1, 0
	global_load_dwordx4 v[104:107], v1, s[8:9]
	global_load_dwordx4 v[108:111], v128, s[8:9]
	global_load_dwordx4 v[112:115], v129, s[8:9]
	global_load_dwordx4 v[116:119], v130, s[8:9]
	global_load_dwordx4 v[120:123], v[20:21], off
	global_load_dwordx4 v[124:127], v[24:25], off
	global_load_dwordx4 v[134:137], v[28:29], off
	global_load_dwordx4 v[138:141], v[32:33], off
	global_load_dwordx4 v[2:5], v1, s[0:1]
	global_load_dwordx4 v[14:17], v1, s[0:1] offset:1024
	global_load_dwordx4 v[6:9], v1, s[0:1] offset:2048
	global_load_dwordx4 v[10:13], v1, s[0:1] offset:3072
	s_waitcnt vmcnt(18)
	v_pk_mul_f32 v[74:75], v[62:63], v[66:67]
	v_pk_mul_f32 v[76:77], v[60:61], v[64:65]
	s_waitcnt vmcnt(16)
	v_pk_mul_f32 v[84:85], v[70:71], v[80:81]
	v_pk_mul_f32 v[86:87], v[68:69], v[78:79]
	s_waitcnt vmcnt(14)
	v_pk_mul_f32 v[78:79], v[90:91], v[94:95]
	v_pk_mul_f32 v[80:81], v[88:89], v[92:93]
	s_waitcnt vmcnt(11)
	v_pk_add_f32 v[60:61], v[106:107], 1.0 op_sel_hi:[1,0]
	v_pk_add_f32 v[62:63], v[104:105], 1.0 op_sel_hi:[1,0]
	s_waitcnt vmcnt(10)
	v_pk_add_f32 v[64:65], v[110:111], 1.0 op_sel_hi:[1,0]
	v_pk_add_f32 v[68:69], v[108:109], 1.0 op_sel_hi:[1,0]
	s_waitcnt vmcnt(9)
	v_pk_add_f32 v[72:73], v[114:115], 1.0 op_sel_hi:[1,0]
	v_pk_add_f32 v[82:83], v[112:113], 1.0 op_sel_hi:[1,0]
	s_waitcnt vmcnt(8)
	v_pk_add_f32 v[88:89], v[118:119], 1.0 op_sel_hi:[1,0]
	v_pk_add_f32 v[94:95], v[116:117], 1.0 op_sel_hi:[1,0]
	v_pk_mul_f32 v[90:91], v[98:99], v[102:103]
	v_pk_mul_f32 v[92:93], v[96:97], v[100:101]
	s_waitcnt vmcnt(7)
	v_pk_mul_f32 v[66:67], v[122:123], v[60:61]
	v_pk_mul_f32 v[70:71], v[120:121], v[62:63]
	s_waitcnt vmcnt(6)
	v_pk_mul_f32 v[62:63], v[126:127], v[64:65]
	v_pk_mul_f32 v[68:69], v[124:125], v[68:69]
	s_waitcnt vmcnt(5)
	v_pk_mul_f32 v[60:61], v[136:137], v[72:73]
	v_pk_mul_f32 v[64:65], v[134:135], v[82:83]
	s_waitcnt vmcnt(4)
	v_pk_mul_f32 v[82:83], v[140:141], v[88:89]
	v_pk_mul_f32 v[88:89], v[138:139], v[94:95]
	s_branch .LBB0_1091

.LBB0_1301:
	v_lshlrev_b32_e32 v58, 16, v30
	v_and_b32_e32 v59, 0xffff0000, v30
	v_lshlrev_b32_e32 v30, 16, v31
	v_and_b32_e32 v31, 0xffff0000, v31
	v_lshlrev_b32_e32 v56, 16, v22
	v_and_b32_e32 v57, 0xffff0000, v22
	v_mul_f32_e32 v22, v31, v31
	v_pk_fma_f32 v[60:61], v[30:31], v[30:31], v[22:23] op_sel_hi:[1,1,0]
	v_lshlrev_b32_e32 v63, 16, v29
	v_lshlrev_b32_e32 v62, 16, v28
	v_and_b32_e32 v29, 0xffff0000, v29
	v_and_b32_e32 v28, 0xffff0000, v28
	v_mul_f32_e32 v22, v59, v59
	v_pk_mul_f32 v[64:65], v[28:29], v[28:29]
	v_lshlrev_b32_e32 v69, 16, v24
	v_pk_fma_f32 v[72:73], v[58:59], v[58:59], v[22:23] op_sel_hi:[1,1,0]
	v_pk_fma_f32 v[64:65], v[62:63], v[62:63], v[64:65]
	v_and_b32_e32 v71, 0xffff0000, v24
	v_mov_b32_e32 v68, v72
	v_mov_b32_e32 v74, v60
	v_mov_b32_e32 v75, v69
	v_and_b32_e32 v67, 0xffff0000, v26
	v_mul_f32_e32 v70, v71, v71
	v_pk_add_f32 v[60:61], v[72:73], v[60:61]
	v_pk_mul_f32 v[72:73], v[68:69], v[74:75]
	v_pk_add_f32 v[64:65], v[64:65], v[64:65] op_sel:[0,1] op_sel_hi:[1,0]
	v_lshlrev_b32_e32 v66, 16, v26
	v_lshlrev_b32_e32 v26, 16, v27
	v_and_b32_e32 v27, 0xffff0000, v27
	v_mov_b32_e32 v61, v73
	v_mov_b32_e32 v65, v70
	v_mul_f32_e32 v22, v67, v67
	v_lshlrev_b32_e32 v24, 16, v25
	v_and_b32_e32 v25, 0xffff0000, v25
	v_pk_add_f32 v[60:61], v[60:61], v[64:65]
	v_pk_fma_f32 v[64:65], v[66:67], v[66:67], v[22:23] op_sel_hi:[1,1,0]
	v_mul_f32_e32 v22, v27, v27
	v_mul_f32_e32 v76, v24, v24
	v_mul_f32_e32 v77, v25, v25
	v_pk_fma_f32 v[72:73], v[26:27], v[26:27], v[22:23] op_sel_hi:[1,1,0]
	v_mov_b32_e32 v65, v76
	v_mov_b32_e32 v73, v77
	v_pk_add_f32 v[64:65], v[64:65], v[72:73]
	v_lshlrev_b32_e32 v72, 16, v21
	v_pk_add_f32 v[60:61], v[60:61], v[64:65]
	v_lshlrev_b32_e32 v64, 16, v20
	v_add_f32_e32 v22, v60, v61
	v_and_b32_e32 v73, 0xffff0000, v21
	v_lshlrev_b32_e32 v52, 16, v34
	v_add_f32_dpp v22, v22, v22 quad_perm:[1,0,3,2] row_mask:0xf bank_mask:0xf bound_ctrl:1
	v_and_b32_e32 v53, 0xffff0000, v34
	v_lshlrev_b32_e32 v34, 16, v35
	v_add_f32_dpp v22, v22, v22 quad_perm:[2,3,0,1] row_mask:0xf bank_mask:0xf bound_ctrl:1
	v_and_b32_e32 v35, 0xffff0000, v35
	v_lshlrev_b32_e32 v54, 16, v32
	v_add_f32_dpp v22, v22, v22 row_half_mirror row_mask:0xf bank_mask:0xf bound_ctrl:1
	v_and_b32_e32 v55, 0xffff0000, v32
	v_lshlrev_b32_e32 v32, 16, v33
	v_add_f32_dpp v22, v22, v22 row_mirror row_mask:0xf bank_mask:0xf bound_ctrl:1
	v_and_b32_e32 v33, 0xffff0000, v33
	v_readlane_b32 s9, v22, 16
	v_readlane_b32 s10, v22, 48
	v_readlane_b32 s0, v22, 0
	v_readlane_b32 s1, v22, 32
	v_mov_b32_e32 v60, s9
	v_mov_b32_e32 v61, s10
	v_pk_add_f32 v[60:61], s[0:1], v[60:61]
	v_lshl_add_u64 v[16:17], v[16:17], 0, s[2:3]
	v_add_f32_e32 v22, v60, v61
	v_fmamk_f32 v22, v22, 0x3a800000, v87
	v_mul_f32_e32 v60, 0x4f800000, v22
	v_cmp_gt_f32_e32 vcc, s17, v22
	v_and_b32_e32 v61, 0xffff0000, v23
	v_lshl_add_u64 v[18:19], v[18:19], 0, s[4:5]
	v_cndmask_b32_e32 v22, v22, v60, vcc
	v_sqrt_f32_e32 v65, v22
	v_lshlrev_b32_e32 v60, 16, v23
	v_add_u32_e32 v23, -1, v65
	v_fma_f32 v68, -v23, v65, v22
	v_cmp_ge_f32_e64 s[0:1], 0, v68
	v_add_u32_e32 v68, 1, v65
	s_nop 0
	v_cndmask_b32_e64 v23, v65, v23, s[0:1]
	v_fma_f32 v65, -v68, v65, v22
	v_cmp_lt_f32_e64 s[0:1], 0, v65
	s_nop 1
	v_cndmask_b32_e64 v23, v23, v68, s[0:1]
	v_mul_f32_e32 v65, 0x37800000, v23
	v_cndmask_b32_e32 v23, v23, v65, vcc
	v_cmp_class_f32_e32 vcc, v22, v88
	v_and_b32_e32 v65, 0xffff0000, v20
	s_nop 0
	v_cndmask_b32_e32 v22, v23, v22, vcc
	v_div_scale_f32 v23, s[0:1], v22, v22, 1.0
	v_rcp_f32_e32 v68, v23
	s_lshl_b64 s[0:1], s[6:7], 12
	v_fma_f32 v20, -v23, v68, 1.0
	v_fmac_f32_e32 v68, v20, v68
	v_div_scale_f32 v20, vcc, 1.0, v22, 1.0
	v_mul_f32_e32 v21, v20, v68
	v_fma_f32 v70, -v23, v21, v20
	v_fmac_f32_e32 v21, v70, v68
	v_fma_f32 v20, -v23, v21, v20
	v_div_fmas_f32 v20, v20, v68, v21
	v_div_fixup_f32 v68, v20, v22, 1.0
	v_pk_mul_f32 v[20:21], v[68:69], v[58:59] op_sel_hi:[0,1]
	v_pk_mul_f32 v[22:23], v[68:69], v[30:31] op_sel_hi:[0,1]
	v_pk_fma_f32 v[22:23], v[36:37], v[22:23], v[34:35]
	v_pk_fma_f32 v[20:21], v[38:39], v[20:21], v[52:53]
	v_lshl_add_u64 v[30:31], v[14:15], 0, s[0:1]
	global_store_dwordx4 v[30:31], v[20:23], off nt
	v_mov_b32_e32 v70, v69
	s_add_i32 s0, s12, s8
	v_mov_b32_e32 v20, v62
	v_mov_b32_e32 v21, v28
	v_mov_b32_e32 v28, v63
	v_pk_mul_f32 v[20:21], v[68:69], v[20:21] op_sel_hi:[0,1]
	v_pk_mul_f32 v[22:23], v[68:69], v[28:29] op_sel_hi:[0,1]
	v_pk_fma_f32 v[22:23], v[42:43], v[22:23], v[32:33]
	v_pk_fma_f32 v[20:21], v[44:45], v[20:21], v[54:55]
	global_store_dwordx4 v[30:31], v[20:23], off offset:1024 nt
	s_cmp_lt_i32 s0, 0x8000
	s_nop 0
	v_pk_mul_f32 v[20:21], v[68:69], v[66:67] op_sel_hi:[0,1]
	v_pk_mul_f32 v[22:23], v[68:69], v[26:27] op_sel_hi:[0,1]
	v_pk_fma_f32 v[22:23], v[40:41], v[22:23], v[60:61]
	v_pk_fma_f32 v[20:21], v[46:47], v[20:21], v[56:57]
	global_store_dwordx4 v[30:31], v[20:23], off offset:2048 nt
	s_nop 1
	v_pk_mul_f32 v[20:21], v[70:71], v[68:69] op_sel_hi:[1,0]
	v_pk_mul_f32 v[22:23], v[24:25], v[68:69] op_sel_hi:[1,0]
	v_pk_fma_f32 v[20:21], v[50:51], v[20:21], v[64:65]
	v_pk_fma_f32 v[22:23], v[48:49], v[22:23], v[72:73]
	global_store_dwordx4 v[30:31], v[20:23], off offset:3072 nt
	s_cbranch_scc0 .LBB0_1308
.LBB0_1302:
	s_ashr_i32 s1, s0, 31
	s_lshr_b32 s1, s1, 18
	s_add_i32 s10, s12, s0
	s_add_i32 s8, s15, s0
	s_add_i32 s6, s16, s0
	s_add_i32 s0, s0, s1
	s_ashr_i32 s18, s0, 14
	s_mul_i32 s0, s18, 0xc00
	s_ashr_i32 s11, s10, 31
	s_ashr_i32 s9, s8, 31
	s_ashr_i32 s7, s6, 31
	s_ashr_i32 s1, s0, 31
	s_lshl_b64 s[20:21], s[10:11], 11
	s_lshl_b64 s[22:23], s[8:9], 11
	s_lshl_b64 s[24:25], s[6:7], 11
	s_lshl_b64 s[0:1], s[0:1], 2
	s_add_u32 s0, s13, s0
	s_addc_u32 s1, s14, s1
	v_add_co_u32_e32 v20, vcc, 0x4000000, v16
	s_add_u32 s0, s0, 0x2000
	s_nop 0
	v_addc_co_u32_e32 v21, vcc, 0, v17, vcc
	global_load_dwordx2 v[50:51], v[16:17], off
	global_load_dwordx2 v[36:37], v[20:21], off
	global_load_dwordx2 v[110:111], v[20:21], off offset:512
	global_load_dwordx2 v[112:113], v[20:21], off offset:1024
	global_load_dwordx2 v[114:115], v[20:21], off offset:1536
	s_addc_u32 s1, s1, 0
	global_load_dwordx4 v[38:41], v1, s[0:1]
	global_load_dwordx4 v[42:45], v[2:3], off
	global_load_dwordx2 v[116:117], v[16:17], off offset:512
	global_load_dwordx2 v[118:119], v[16:17], off offset:1024
	global_load_dwordx2 v[120:121], v[16:17], off offset:1536
	global_load_dwordx4 v[46:49], v[4:5], off
	global_load_dwordx4 v[90:93], v[6:7], off
	global_load_dwordx4 v[94:97], v[8:9], off
	v_lshl_add_u64 v[20:21], v[10:11], 0, s[20:21]
	v_lshl_add_u64 v[22:23], v[12:13], 0, s[20:21]
	v_lshl_add_u64 v[24:25], v[10:11], 0, s[22:23]
	s_waitcnt vmcnt(0)
	v_lshl_add_u64 v[122:123], v[12:13], 0, s[22:23]
	v_lshl_add_u64 v[124:125], v[10:11], 0, s[24:25]
	v_lshl_add_u64 v[126:127], v[12:13], 0, s[24:25]
	global_load_dwordx2 v[82:83], v[20:21], off
	global_load_dwordx2 v[80:81], v[20:21], off offset:512
	global_load_dwordx2 v[70:71], v[20:21], off offset:1024
	global_load_dwordx2 v[68:69], v[20:21], off offset:1536
	global_load_dwordx2 v[78:79], v[22:23], off
	global_load_dwordx2 v[76:77], v[22:23], off offset:512
	global_load_dwordx2 v[74:75], v[22:23], off offset:1024
	global_load_dwordx2 v[72:73], v[22:23], off offset:1536
	global_load_dwordx2 v[66:67], v[24:25], off
	global_load_dwordx2 v[64:65], v[24:25], off offset:512
	global_load_dwordx2 v[54:55], v[24:25], off offset:1024
	global_load_dwordx2 v[52:53], v[24:25], off offset:1536
	global_load_dwordx2 v[62:63], v[122:123], off
	global_load_dwordx2 v[60:61], v[122:123], off offset:512
	global_load_dwordx2 v[58:59], v[122:123], off offset:1024
	global_load_dwordx2 v[56:57], v[122:123], off offset:1536
	global_load_dwordx2 v[34:35], v[124:125], off
	global_load_dwordx2 v[32:33], v[124:125], off offset:512
	global_load_dwordx2 v[22:23], v[124:125], off offset:1024
	global_load_dwordx2 v[20:21], v[124:125], off offset:1536
	global_load_dwordx2 v[30:31], v[126:127], off
	global_load_dwordx2 v[28:29], v[126:127], off offset:512
	global_load_dwordx2 v[26:27], v[126:127], off offset:1024
	global_load_dwordx2 v[24:25], v[126:127], off offset:1536
	global_load_dwordx4 v[98:101], v84, s[0:1]
	global_load_dwordx4 v[102:105], v85, s[0:1]
	global_load_dwordx4 v[106:109], v86, s[0:1]
	v_and_b32_e32 v123, 0xffff0000, v50
	v_and_b32_e32 v125, 0xffff0000, v51
	v_lshlrev_b32_e32 v122, 16, v50
	v_lshlrev_b32_e32 v124, 16, v51
	v_lshlrev_b32_e32 v126, 16, v36
	v_and_b32_e32 v127, 0xffff0000, v36
	v_lshlrev_b32_e32 v128, 16, v37
	v_and_b32_e32 v129, 0xffff0000, v37
	v_pk_mul_f32 v[36:37], v[40:41], v[44:45]
	v_mul_f32_e32 v40, v125, v125
	v_lshlrev_b32_e32 v137, 16, v117
	v_lshlrev_b32_e32 v136, 16, v116
	v_and_b32_e32 v117, 0xffff0000, v117
	v_and_b32_e32 v116, 0xffff0000, v116
	v_mul_f32_e32 v44, v123, v123
	v_pk_mul_f32 v[38:39], v[38:39], v[42:43]
	v_pk_fma_f32 v[40:41], v[124:125], v[124:125], v[40:41] op_sel_hi:[1,1,0]
	v_pk_mul_f32 v[42:43], v[116:117], v[116:117]
	v_lshlrev_b32_e32 v141, 16, v120
	v_pk_fma_f32 v[44:45], v[122:123], v[122:123], v[44:45] op_sel_hi:[1,1,0]
	v_pk_fma_f32 v[42:43], v[136:137], v[136:137], v[42:43]
	v_and_b32_e32 v143, 0xffff0000, v120
	v_mov_b32_e32 v140, v44
	v_mov_b32_e32 v50, v40
	v_mov_b32_e32 v51, v141
	v_mul_f32_e32 v89, v143, v143
	v_pk_add_f32 v[40:41], v[44:45], v[40:41]
	v_pk_mul_f32 v[44:45], v[140:141], v[50:51]
	v_pk_add_f32 v[42:43], v[42:43], v[42:43] op_sel:[0,1] op_sel_hi:[1,0]
	v_lshlrev_b32_e32 v138, 16, v118
	v_and_b32_e32 v139, 0xffff0000, v118
	v_lshlrev_b32_e32 v118, 16, v119
	v_and_b32_e32 v119, 0xffff0000, v119
	v_mov_b32_e32 v41, v45
	v_mov_b32_e32 v43, v89
	v_lshlrev_b32_e32 v120, 16, v121
	v_and_b32_e32 v121, 0xffff0000, v121
	v_pk_add_f32 v[40:41], v[40:41], v[42:43]
	v_mul_f32_e32 v42, v139, v139
	v_mul_f32_e32 v44, v119, v119
	v_mul_f32_e32 v142, v120, v120
	v_mul_f32_e32 v144, v121, v121
	v_pk_fma_f32 v[42:43], v[138:139], v[138:139], v[42:43] op_sel_hi:[1,1,0]
	v_pk_fma_f32 v[44:45], v[118:119], v[118:119], v[44:45] op_sel_hi:[1,1,0]
	v_mov_b32_e32 v43, v142
	v_mov_b32_e32 v45, v144
	v_pk_add_f32 v[42:43], v[42:43], v[44:45]
	s_waitcnt vmcnt(2)
	v_pk_mul_f32 v[44:45], v[98:99], v[46:47]
	v_pk_add_f32 v[40:41], v[40:41], v[42:43]
	v_pk_mul_f32 v[42:43], v[100:101], v[48:49]
	v_add_f32_e32 v40, v40, v41
	v_lshlrev_b32_e32 v130, 16, v110
	v_and_b32_e32 v131, 0xffff0000, v110
	v_add_f32_dpp v40, v40, v40 quad_perm:[1,0,3,2] row_mask:0xf bank_mask:0xf bound_ctrl:1
	v_lshlrev_b32_e32 v110, 16, v111
	v_and_b32_e32 v111, 0xffff0000, v111
	v_add_f32_dpp v40, v40, v40 quad_perm:[2,3,0,1] row_mask:0xf bank_mask:0xf bound_ctrl:1
	v_lshlrev_b32_e32 v132, 16, v112
	v_and_b32_e32 v133, 0xffff0000, v112
	v_add_f32_dpp v40, v40, v40 row_half_mirror row_mask:0xf bank_mask:0xf bound_ctrl:1
	v_lshlrev_b32_e32 v112, 16, v113
	v_and_b32_e32 v113, 0xffff0000, v113
	v_add_f32_dpp v40, v40, v40 row_mirror row_mask:0xf bank_mask:0xf bound_ctrl:1
	v_mov_b32_e32 v142, v141
	v_readlane_b32 s19, v40, 16
	v_readlane_b32 s20, v40, 48
	v_readlane_b32 s0, v40, 0
	v_readlane_b32 s1, v40, 32
	v_mov_b32_e32 v40, s19
	v_mov_b32_e32 v41, s20
	v_pk_add_f32 v[40:41], s[0:1], v[40:41]
	v_lshlrev_b32_e32 v134, 16, v114
	v_add_f32_e32 v40, v40, v41
	v_fmamk_f32 v40, v40, 0x3a800000, v87
	v_mul_f32_e32 v41, 0x4f800000, v40
	v_cmp_gt_f32_e32 vcc, s17, v40
	v_and_b32_e32 v135, 0xffff0000, v114
	v_lshlrev_b32_e32 v114, 16, v115
	v_cndmask_b32_e32 v50, v40, v41, vcc
	v_sqrt_f32_e32 v51, v50
	s_waitcnt vmcnt(1)
	v_pk_mul_f32 v[40:41], v[104:105], v[92:93]
	v_and_b32_e32 v115, 0xffff0000, v115
	v_add_u32_e32 v46, -1, v51
	v_fma_f32 v47, -v46, v51, v50
	v_cmp_ge_f32_e64 s[0:1], 0, v47
	v_add_u32_e32 v47, 1, v51
	v_fma_f32 v48, -v47, v51, v50
	v_cndmask_b32_e64 v46, v51, v46, s[0:1]
	v_cmp_lt_f32_e64 s[0:1], 0, v48
	s_waitcnt vmcnt(0)
	v_pk_mul_f32 v[48:49], v[108:109], v[96:97]
	v_cndmask_b32_e64 v46, v46, v47, s[0:1]
	v_mul_f32_e32 v47, 0x37800000, v46
	v_cndmask_b32_e32 v46, v46, v47, vcc
	v_cmp_class_f32_e32 vcc, v50, v88
	s_nop 1
	v_cndmask_b32_e32 v89, v46, v50, vcc
	v_div_scale_f32 v92, s[0:1], v89, v89, 1.0
	v_rcp_f32_e32 v93, v92
	v_pk_mul_f32 v[46:47], v[102:103], v[90:91]
	v_pk_mul_f32 v[50:51], v[106:107], v[94:95]
	s_lshr_b32 s0, s11, 18
	v_fma_f32 v90, -v92, v93, 1.0
	v_fmac_f32_e32 v93, v90, v93
	v_div_scale_f32 v90, vcc, 1.0, v89, 1.0
	v_mul_f32_e32 v91, v90, v93
	v_fma_f32 v94, -v92, v91, v90
	v_fmac_f32_e32 v91, v94, v93
	v_fma_f32 v90, -v92, v91, v90
	v_div_fmas_f32 v90, v90, v93, v91
	v_div_fixup_f32 v94, v90, v89, 1.0
	v_pk_mul_f32 v[90:91], v[94:95], v[122:123] op_sel_hi:[0,1]
	v_pk_mul_f32 v[92:93], v[94:95], v[124:125] op_sel_hi:[0,1]
	v_pk_fma_f32 v[92:93], v[36:37], v[92:93], v[128:129]
	v_pk_fma_f32 v[90:91], v[38:39], v[90:91], v[126:127]
	global_store_dwordx4 v[18:19], v[90:93], off offset:-3072 nt
	s_add_i32 s0, s10, s0
	s_ashr_i32 s0, s0, 14
	v_mov_b32_e32 v90, v136
	v_mov_b32_e32 v91, v116
	v_mov_b32_e32 v116, v137
	v_pk_mul_f32 v[90:91], v[94:95], v[90:91] op_sel_hi:[0,1]
	v_pk_mul_f32 v[92:93], v[94:95], v[116:117] op_sel_hi:[0,1]
	v_pk_fma_f32 v[92:93], v[42:43], v[92:93], v[110:111]
	v_pk_fma_f32 v[90:91], v[44:45], v[90:91], v[130:131]
	global_store_dwordx4 v[18:19], v[90:93], off offset:-2048 nt
	s_cmp_eq_u32 s0, s18
	s_nop 0
	v_pk_mul_f32 v[90:91], v[94:95], v[138:139] op_sel_hi:[0,1]
	v_pk_mul_f32 v[92:93], v[94:95], v[118:119] op_sel_hi:[0,1]
	v_pk_fma_f32 v[92:93], v[40:41], v[92:93], v[112:113]
	v_pk_fma_f32 v[90:91], v[46:47], v[90:91], v[132:133]
	global_store_dwordx4 v[18:19], v[90:93], off offset:-1024 nt
	s_nop 1
	v_pk_mul_f32 v[90:91], v[142:143], v[94:95] op_sel_hi:[1,0]
	v_pk_mul_f32 v[92:93], v[120:121], v[94:95] op_sel_hi:[1,0]
	v_pk_fma_f32 v[90:91], v[50:51], v[90:91], v[134:135]
	v_pk_fma_f32 v[92:93], v[48:49], v[92:93], v[114:115]
	global_store_dwordx4 v[18:19], v[90:93], off nt
	s_cbranch_scc1 .LBB0_1304
	s_mul_i32 s18, s0, 0xc00
	s_ashr_i32 s19, s18, 31
	s_lshl_b64 s[18:19], s[18:19], 2
	s_add_u32 s1, s13, s18
	s_addc_u32 s19, s14, s19
	s_add_u32 s18, s1, 0x2000
	s_addc_u32 s19, s19, 0
	global_load_dwordx4 v[38:41], v[2:3], off
	global_load_dwordx4 v[42:45], v1, s[18:19]
	global_load_dwordx4 v[46:49], v84, s[18:19]
	global_load_dwordx4 v[90:93], v[4:5], off
	global_load_dwordx4 v[94:97], v85, s[18:19]
	global_load_dwordx4 v[98:101], v[6:7], off
	global_load_dwordx4 v[102:105], v[8:9], off
	global_load_dwordx4 v[106:109], v86, s[18:19]
	s_mov_b32 s18, s0
	s_waitcnt vmcnt(6)
	v_pk_mul_f32 v[36:37], v[44:45], v[40:41]
	v_pk_mul_f32 v[38:39], v[42:43], v[38:39]
	s_waitcnt vmcnt(4)
	v_pk_mul_f32 v[42:43], v[48:49], v[92:93]
	v_pk_mul_f32 v[44:45], v[46:47], v[90:91]
	s_waitcnt vmcnt(2)
	v_pk_mul_f32 v[40:41], v[96:97], v[100:101]
	v_pk_mul_f32 v[46:47], v[94:95], v[98:99]
	s_waitcnt vmcnt(0)
	v_pk_mul_f32 v[48:49], v[108:109], v[104:105]
	v_pk_mul_f32 v[50:51], v[106:107], v[102:103]
.LBB0_1304:
	v_lshlrev_b32_e32 v96, 16, v78
	v_and_b32_e32 v97, 0xffff0000, v78
	v_lshlrev_b32_e32 v78, 16, v79
	v_and_b32_e32 v79, 0xffff0000, v79
	v_lshlrev_b32_e32 v94, 16, v70
	v_and_b32_e32 v95, 0xffff0000, v70
	v_mul_f32_e32 v70, v79, v79
	v_pk_fma_f32 v[98:99], v[78:79], v[78:79], v[70:71] op_sel_hi:[1,1,0]
	v_lshlrev_b32_e32 v101, 16, v77
	v_lshlrev_b32_e32 v100, 16, v76
	v_and_b32_e32 v77, 0xffff0000, v77
	v_and_b32_e32 v76, 0xffff0000, v76
	v_mul_f32_e32 v70, v97, v97
	v_pk_mul_f32 v[102:103], v[76:77], v[76:77]
	v_lshlrev_b32_e32 v107, 16, v72
	v_pk_fma_f32 v[110:111], v[96:97], v[96:97], v[70:71] op_sel_hi:[1,1,0]
	v_pk_fma_f32 v[102:103], v[100:101], v[100:101], v[102:103]
	v_and_b32_e32 v109, 0xffff0000, v72
	v_mov_b32_e32 v106, v110
	v_mov_b32_e32 v112, v98
	v_mov_b32_e32 v113, v107
	v_and_b32_e32 v105, 0xffff0000, v74
	v_mul_f32_e32 v89, v109, v109
	v_pk_add_f32 v[98:99], v[110:111], v[98:99]
	v_pk_mul_f32 v[110:111], v[106:107], v[112:113]
	v_pk_add_f32 v[102:103], v[102:103], v[102:103] op_sel:[0,1] op_sel_hi:[1,0]
	v_lshlrev_b32_e32 v104, 16, v74
	v_lshlrev_b32_e32 v74, 16, v75
	v_and_b32_e32 v75, 0xffff0000, v75
	v_mov_b32_e32 v99, v111
	v_mov_b32_e32 v103, v89
	v_mul_f32_e32 v70, v105, v105
	v_lshlrev_b32_e32 v72, 16, v73
	v_and_b32_e32 v73, 0xffff0000, v73
	v_pk_add_f32 v[98:99], v[98:99], v[102:103]
	v_pk_fma_f32 v[102:103], v[104:105], v[104:105], v[70:71] op_sel_hi:[1,1,0]
	v_mul_f32_e32 v70, v75, v75
	v_mul_f32_e32 v108, v72, v72
	v_mul_f32_e32 v114, v73, v73
	v_pk_fma_f32 v[110:111], v[74:75], v[74:75], v[70:71] op_sel_hi:[1,1,0]
	v_mov_b32_e32 v103, v108
	v_mov_b32_e32 v111, v114
	v_pk_add_f32 v[102:103], v[102:103], v[110:111]
	v_lshlrev_b32_e32 v110, 16, v69
	v_pk_add_f32 v[98:99], v[98:99], v[102:103]
	v_lshlrev_b32_e32 v102, 16, v68
	v_add_f32_e32 v70, v98, v99
	v_and_b32_e32 v111, 0xffff0000, v69
	v_lshlrev_b32_e32 v90, 16, v82
	v_add_f32_dpp v70, v70, v70 quad_perm:[1,0,3,2] row_mask:0xf bank_mask:0xf bound_ctrl:1
	v_and_b32_e32 v91, 0xffff0000, v82
	v_lshlrev_b32_e32 v82, 16, v83
	v_add_f32_dpp v70, v70, v70 quad_perm:[2,3,0,1] row_mask:0xf bank_mask:0xf bound_ctrl:1
	v_and_b32_e32 v83, 0xffff0000, v83
	v_lshlrev_b32_e32 v92, 16, v80
	v_add_f32_dpp v70, v70, v70 row_half_mirror row_mask:0xf bank_mask:0xf bound_ctrl:1
	v_and_b32_e32 v93, 0xffff0000, v80
	v_lshlrev_b32_e32 v80, 16, v81
	v_add_f32_dpp v70, v70, v70 row_mirror row_mask:0xf bank_mask:0xf bound_ctrl:1
	v_and_b32_e32 v81, 0xffff0000, v81
	v_readlane_b32 s19, v70, 16
	v_readlane_b32 s20, v70, 48
	v_readlane_b32 s0, v70, 0
	v_readlane_b32 s1, v70, 32
	v_mov_b32_e32 v98, s19
	v_mov_b32_e32 v99, s20
	v_pk_add_f32 v[98:99], s[0:1], v[98:99]
	v_mov_b32_e32 v108, v107
	v_add_f32_e32 v70, v98, v99
	v_fmamk_f32 v70, v70, 0x3a800000, v87
	v_mul_f32_e32 v89, 0x4f800000, v70
	v_cmp_gt_f32_e32 vcc, s17, v70
	v_lshlrev_b32_e32 v98, 16, v71
	v_and_b32_e32 v99, 0xffff0000, v71
	v_cndmask_b32_e32 v70, v70, v89, vcc
	v_sqrt_f32_e32 v89, v70
	s_nop 0
	v_add_u32_e32 v71, -1, v89
	v_fma_f32 v103, -v71, v89, v70
	v_cmp_ge_f32_e64 s[0:1], 0, v103
	v_add_u32_e32 v103, 1, v89
	s_nop 0
	v_cndmask_b32_e64 v71, v89, v71, s[0:1]
	v_fma_f32 v89, -v103, v89, v70
	v_cmp_lt_f32_e64 s[0:1], 0, v89
	s_nop 1
	v_cndmask_b32_e64 v71, v71, v103, s[0:1]
	v_mul_f32_e32 v89, 0x37800000, v71
	v_cndmask_b32_e32 v71, v71, v89, vcc
	v_cmp_class_f32_e32 vcc, v70, v88
	v_and_b32_e32 v103, 0xffff0000, v68
	s_nop 0
	v_cndmask_b32_e32 v70, v71, v70, vcc
	v_div_scale_f32 v71, s[0:1], v70, v70, 1.0
	v_rcp_f32_e32 v89, v71
	s_lshl_b64 s[0:1], s[10:11], 12
	s_add_i32 s10, s12, s10
	v_fma_f32 v68, -v71, v89, 1.0
	v_fmac_f32_e32 v89, v68, v89
	v_div_scale_f32 v68, vcc, 1.0, v70, 1.0
	v_mul_f32_e32 v69, v68, v89
	v_fma_f32 v106, -v71, v69, v68
	v_fmac_f32_e32 v69, v106, v89
	v_fma_f32 v68, -v71, v69, v68
	v_div_fmas_f32 v68, v68, v89, v69
	v_div_fixup_f32 v106, v68, v70, 1.0
	v_pk_mul_f32 v[68:69], v[106:107], v[96:97] op_sel_hi:[0,1]
	v_pk_mul_f32 v[70:71], v[106:107], v[78:79] op_sel_hi:[0,1]
	v_pk_fma_f32 v[70:71], v[36:37], v[70:71], v[82:83]
	v_pk_fma_f32 v[68:69], v[38:39], v[68:69], v[90:91]
	v_lshl_add_u64 v[78:79], v[14:15], 0, s[0:1]
	global_store_dwordx4 v[78:79], v[68:71], off nt
	s_ashr_i32 s0, s10, 31
	s_lshr_b32 s0, s0, 18
	v_mov_b32_e32 v68, v100
	v_mov_b32_e32 v69, v76
	v_mov_b32_e32 v76, v101
	v_pk_mul_f32 v[68:69], v[106:107], v[68:69] op_sel_hi:[0,1]
	v_pk_mul_f32 v[70:71], v[106:107], v[76:77] op_sel_hi:[0,1]
	v_pk_fma_f32 v[70:71], v[42:43], v[70:71], v[80:81]
	v_pk_fma_f32 v[68:69], v[44:45], v[68:69], v[92:93]
	global_store_dwordx4 v[78:79], v[68:71], off offset:1024 nt
	s_add_i32 s0, s10, s0
	s_ashr_i32 s0, s0, 14
	v_pk_mul_f32 v[68:69], v[106:107], v[104:105] op_sel_hi:[0,1]
	v_pk_mul_f32 v[70:71], v[106:107], v[74:75] op_sel_hi:[0,1]
	v_pk_fma_f32 v[70:71], v[40:41], v[70:71], v[98:99]
	v_pk_fma_f32 v[68:69], v[46:47], v[68:69], v[94:95]
	global_store_dwordx4 v[78:79], v[68:71], off offset:2048 nt
	s_cmp_eq_u32 s0, s18
	s_nop 0
	v_pk_mul_f32 v[68:69], v[108:109], v[106:107] op_sel_hi:[1,0]
	v_pk_mul_f32 v[70:71], v[72:73], v[106:107] op_sel_hi:[1,0]
	v_pk_fma_f32 v[68:69], v[50:51], v[68:69], v[102:103]
	v_pk_fma_f32 v[70:71], v[48:49], v[70:71], v[110:111]
	global_store_dwordx4 v[78:79], v[68:71], off offset:3072 nt
	s_cbranch_scc1 .LBB0_1306
	s_mul_i32 s18, s0, 0xc00
	s_ashr_i32 s19, s18, 31
	s_lshl_b64 s[18:19], s[18:19], 2
	s_add_u32 s1, s13, s18
	s_addc_u32 s11, s14, s19
	s_add_u32 s18, s1, 0x2000
	s_addc_u32 s19, s11, 0
	global_load_dwordx4 v[38:41], v[2:3], off
	global_load_dwordx4 v[42:45], v1, s[18:19]
	global_load_dwordx4 v[46:49], v84, s[18:19]
	global_load_dwordx4 v[68:71], v[4:5], off
	global_load_dwordx4 v[72:75], v85, s[18:19]
	global_load_dwordx4 v[76:79], v[6:7], off
	global_load_dwordx4 v[80:83], v[8:9], off
	global_load_dwordx4 v[90:93], v86, s[18:19]
	s_mov_b32 s18, s0
	s_waitcnt vmcnt(6)
	v_pk_mul_f32 v[36:37], v[44:45], v[40:41]
	v_pk_mul_f32 v[38:39], v[42:43], v[38:39]
	s_waitcnt vmcnt(4)
	v_pk_mul_f32 v[42:43], v[48:49], v[70:71]
	v_pk_mul_f32 v[44:45], v[46:47], v[68:69]
	s_waitcnt vmcnt(2)
	v_pk_mul_f32 v[40:41], v[74:75], v[78:79]
	v_pk_mul_f32 v[46:47], v[72:73], v[76:77]
	s_waitcnt vmcnt(0)
	v_pk_mul_f32 v[48:49], v[92:93], v[82:83]
	v_pk_mul_f32 v[50:51], v[90:91], v[80:81]
.LBB0_1306:
	v_lshlrev_b32_e32 v74, 16, v62
	v_and_b32_e32 v75, 0xffff0000, v62
	v_lshlrev_b32_e32 v62, 16, v63
	v_and_b32_e32 v63, 0xffff0000, v63
	v_lshlrev_b32_e32 v72, 16, v54
	v_and_b32_e32 v73, 0xffff0000, v54
	v_mul_f32_e32 v54, v63, v63
	v_pk_fma_f32 v[76:77], v[62:63], v[62:63], v[54:55] op_sel_hi:[1,1,0]
	v_lshlrev_b32_e32 v79, 16, v61
	v_lshlrev_b32_e32 v78, 16, v60
	v_and_b32_e32 v61, 0xffff0000, v61
	v_and_b32_e32 v60, 0xffff0000, v60
	v_mul_f32_e32 v54, v75, v75
	v_pk_mul_f32 v[80:81], v[60:61], v[60:61]
	v_lshlrev_b32_e32 v91, 16, v56
	v_pk_fma_f32 v[94:95], v[74:75], v[74:75], v[54:55] op_sel_hi:[1,1,0]
	v_pk_fma_f32 v[80:81], v[78:79], v[78:79], v[80:81]
	v_and_b32_e32 v93, 0xffff0000, v56
	v_mov_b32_e32 v90, v94
	v_mov_b32_e32 v96, v76
	v_mov_b32_e32 v97, v91
	v_and_b32_e32 v83, 0xffff0000, v58
	v_mul_f32_e32 v89, v93, v93
	v_pk_add_f32 v[76:77], v[94:95], v[76:77]
	v_pk_mul_f32 v[94:95], v[90:91], v[96:97]
	v_pk_add_f32 v[80:81], v[80:81], v[80:81] op_sel:[0,1] op_sel_hi:[1,0]
	v_lshlrev_b32_e32 v82, 16, v58
	v_lshlrev_b32_e32 v58, 16, v59
	v_and_b32_e32 v59, 0xffff0000, v59
	v_mov_b32_e32 v77, v95
	v_mov_b32_e32 v81, v89
	v_mul_f32_e32 v54, v83, v83
	v_lshlrev_b32_e32 v56, 16, v57
	v_and_b32_e32 v57, 0xffff0000, v57
	v_pk_add_f32 v[76:77], v[76:77], v[80:81]
	v_pk_fma_f32 v[80:81], v[82:83], v[82:83], v[54:55] op_sel_hi:[1,1,0]
	v_mul_f32_e32 v54, v59, v59
	v_mul_f32_e32 v92, v56, v56
	v_mul_f32_e32 v98, v57, v57
	v_pk_fma_f32 v[94:95], v[58:59], v[58:59], v[54:55] op_sel_hi:[1,1,0]
	v_mov_b32_e32 v81, v92
	v_mov_b32_e32 v95, v98
	v_pk_add_f32 v[80:81], v[80:81], v[94:95]
	v_lshlrev_b32_e32 v94, 16, v53
	v_pk_add_f32 v[76:77], v[76:77], v[80:81]
	v_lshlrev_b32_e32 v80, 16, v52
	v_add_f32_e32 v54, v76, v77
	v_and_b32_e32 v95, 0xffff0000, v53
	v_lshlrev_b32_e32 v68, 16, v66
	v_add_f32_dpp v54, v54, v54 quad_perm:[1,0,3,2] row_mask:0xf bank_mask:0xf bound_ctrl:1
	v_and_b32_e32 v69, 0xffff0000, v66
	v_lshlrev_b32_e32 v66, 16, v67
	v_add_f32_dpp v54, v54, v54 quad_perm:[2,3,0,1] row_mask:0xf bank_mask:0xf bound_ctrl:1
	v_and_b32_e32 v67, 0xffff0000, v67
	v_lshlrev_b32_e32 v70, 16, v64
	v_add_f32_dpp v54, v54, v54 row_half_mirror row_mask:0xf bank_mask:0xf bound_ctrl:1
	v_and_b32_e32 v71, 0xffff0000, v64
	v_lshlrev_b32_e32 v64, 16, v65
	v_add_f32_dpp v54, v54, v54 row_mirror row_mask:0xf bank_mask:0xf bound_ctrl:1
	v_and_b32_e32 v65, 0xffff0000, v65
	v_readlane_b32 s11, v54, 16
	v_readlane_b32 s19, v54, 48
	v_readlane_b32 s0, v54, 0
	v_readlane_b32 s1, v54, 32
	v_mov_b32_e32 v76, s11
	v_mov_b32_e32 v77, s19
	v_pk_add_f32 v[76:77], s[0:1], v[76:77]
	v_mov_b32_e32 v92, v91
	v_add_f32_e32 v54, v76, v77
	v_fmamk_f32 v54, v54, 0x3a800000, v87
	v_mul_f32_e32 v76, 0x4f800000, v54
	v_cmp_gt_f32_e32 vcc, s17, v54
	v_and_b32_e32 v77, 0xffff0000, v55
	s_nop 0
	v_cndmask_b32_e32 v54, v54, v76, vcc
	v_sqrt_f32_e32 v81, v54
	v_lshlrev_b32_e32 v76, 16, v55
	v_add_u32_e32 v55, -1, v81
	v_fma_f32 v89, -v55, v81, v54
	v_cmp_ge_f32_e64 s[0:1], 0, v89
	v_add_u32_e32 v89, 1, v81
	s_nop 0
	v_cndmask_b32_e64 v55, v81, v55, s[0:1]
	v_fma_f32 v81, -v89, v81, v54
	v_cmp_lt_f32_e64 s[0:1], 0, v81
	s_nop 1
	v_cndmask_b32_e64 v55, v55, v89, s[0:1]
	v_mul_f32_e32 v81, 0x37800000, v55
	v_cndmask_b32_e32 v55, v55, v81, vcc
	v_cmp_class_f32_e32 vcc, v54, v88
	v_and_b32_e32 v81, 0xffff0000, v52
	s_nop 0
	v_cndmask_b32_e32 v54, v55, v54, vcc
	v_div_scale_f32 v55, s[0:1], v54, v54, 1.0
	v_rcp_f32_e32 v89, v55
	s_lshl_b64 s[0:1], s[8:9], 12
	s_add_i32 s8, s12, s10
	v_fma_f32 v52, -v55, v89, 1.0
	v_fmac_f32_e32 v89, v52, v89
	v_div_scale_f32 v52, vcc, 1.0, v54, 1.0
	v_mul_f32_e32 v53, v52, v89
	v_fma_f32 v90, -v55, v53, v52
	v_fmac_f32_e32 v53, v90, v89
	v_fma_f32 v52, -v55, v53, v52
	v_div_fmas_f32 v52, v52, v89, v53
	v_div_fixup_f32 v90, v52, v54, 1.0
	v_pk_mul_f32 v[52:53], v[90:91], v[74:75] op_sel_hi:[0,1]
	v_pk_mul_f32 v[54:55], v[90:91], v[62:63] op_sel_hi:[0,1]
	v_pk_fma_f32 v[54:55], v[36:37], v[54:55], v[66:67]
	v_pk_fma_f32 v[52:53], v[38:39], v[52:53], v[68:69]
	v_lshl_add_u64 v[62:63], v[14:15], 0, s[0:1]
	global_store_dwordx4 v[62:63], v[52:55], off nt
	s_ashr_i32 s0, s8, 31
	s_lshr_b32 s0, s0, 18
	v_mov_b32_e32 v52, v78
	v_mov_b32_e32 v53, v60
	v_mov_b32_e32 v60, v79
	v_pk_mul_f32 v[52:53], v[90:91], v[52:53] op_sel_hi:[0,1]
	v_pk_mul_f32 v[54:55], v[90:91], v[60:61] op_sel_hi:[0,1]
	v_pk_fma_f32 v[54:55], v[42:43], v[54:55], v[64:65]
	v_pk_fma_f32 v[52:53], v[44:45], v[52:53], v[70:71]
	global_store_dwordx4 v[62:63], v[52:55], off offset:1024 nt
	s_add_i32 s0, s8, s0
	s_ashr_i32 s0, s0, 14
	v_pk_mul_f32 v[52:53], v[90:91], v[82:83] op_sel_hi:[0,1]
	v_pk_mul_f32 v[54:55], v[90:91], v[58:59] op_sel_hi:[0,1]
	v_pk_fma_f32 v[54:55], v[40:41], v[54:55], v[76:77]
	v_pk_fma_f32 v[52:53], v[46:47], v[52:53], v[72:73]
	global_store_dwordx4 v[62:63], v[52:55], off offset:2048 nt
	s_cmp_eq_u32 s0, s18
	s_nop 0
	v_pk_mul_f32 v[52:53], v[92:93], v[90:91] op_sel_hi:[1,0]
	v_pk_mul_f32 v[54:55], v[56:57], v[90:91] op_sel_hi:[1,0]
	v_pk_fma_f32 v[52:53], v[50:51], v[52:53], v[80:81]
	v_pk_fma_f32 v[54:55], v[48:49], v[54:55], v[94:95]
	global_store_dwordx4 v[62:63], v[52:55], off offset:3072 nt
	s_cbranch_scc1 .LBB0_1301
	s_mulk_i32 s0, 0xc00
	s_ashr_i32 s1, s0, 31
	s_lshl_b64 s[0:1], s[0:1], 2
	s_add_u32 s0, s13, s0
	s_addc_u32 s1, s14, s1
	s_add_u32 s0, s0, 0x2000
	s_addc_u32 s1, s1, 0
	global_load_dwordx4 v[38:41], v[2:3], off
	global_load_dwordx4 v[42:45], v1, s[0:1]
	global_load_dwordx4 v[46:49], v84, s[0:1]
	global_load_dwordx4 v[50:53], v[4:5], off
	global_load_dwordx4 v[54:57], v85, s[0:1]
	global_load_dwordx4 v[58:61], v[6:7], off
	global_load_dwordx4 v[62:65], v[8:9], off
	global_load_dwordx4 v[66:69], v86, s[0:1]
	s_waitcnt vmcnt(6)
	v_pk_mul_f32 v[36:37], v[44:45], v[40:41]
	v_pk_mul_f32 v[38:39], v[42:43], v[38:39]
	s_waitcnt vmcnt(4)
	v_pk_mul_f32 v[42:43], v[48:49], v[52:53]
	v_pk_mul_f32 v[44:45], v[46:47], v[50:51]
	s_waitcnt vmcnt(2)
	v_pk_mul_f32 v[40:41], v[56:57], v[60:61]
	v_pk_mul_f32 v[46:47], v[54:55], v[58:59]
	s_waitcnt vmcnt(0)
	v_pk_mul_f32 v[48:49], v[68:69], v[64:65]
	v_pk_mul_f32 v[50:51], v[66:67], v[62:63]
	s_branch .LBB0_1301
